# GEMM K-loops (8 of 11): per-segment setprio toggles replaced by one static priority raise for the wr==1 wave half
# baseline (speedup 1.0000x reference)
; #define PG8_STAGE(bufoff, gbase, voff) do { _Pragma("unroll") for (int _i = 0; _i < 2; ++_i) \
;         __builtin_amdgcn_global_load_lds((const unsigned*)((const char*)(gbase) + (voff)[_i]), (LAS unsigned*)(lds + (bufoff) + ldsw + _i * 8192), 16, 0, 0); } while (0)
; #define PG8_LDA(dst, b, h) do { _Pragma("unroll") for (int m = 0; m < 4; ++m) _Pragma("unroll") for (int k = 0; k < 2; ++k) dst[m][k] = *(const LAS bf16x8*)(lds + PG8_SA(b, h) + aoff + m * 2048 + k * 1024); } while (0)
; #define PG8_LDB(dst, b, h) do { _Pragma("unroll") for (int n = 0; n < 2; ++n) _Pragma("unroll") for (int k = 0; k < 2; ++k) dst[n][k] = *(const LAS bf16x8*)(lds + PG8_SB(b, h) + boff + n * 2048 + k * 1024); } while (0)
; #define PG8_MMA(ai, bj, At, Bt) do { __builtin_amdgcn_s_setprio(1); _Pragma("unroll") for (int m = 0; m < 4; ++m) _Pragma("unroll") for (int n = 0; n < 2; ++n) _Pragma("unroll") for (int k = 0; k < 2; ++k) \
;         acc[ai][bj][m][n] = __builtin_amdgcn_mfma_f32_16x16x32_bf16(Bt[n][k], At[m][k], acc[ai][bj][m][n], 0, 0, 0); __builtin_amdgcn_s_setprio(0); } while (0)
; #define PG8_BAR __builtin_amdgcn_s_barrier()
; template <class Epi>
; DI void gemm_phase(LAS unsigned char* lds, const Gemm g, const StaticOrder& S, const Epi& E) {
;     ...
;         const bool has_next = S.next(ui + 1, nxt);
;         const char* nA = has_next ? (const char*)g.A + (size_t)nxt.pm * tstepA + (size_t)nxt.pn * g.a_pn_off * 2 : cA; const char* nB = has_next ? (const char*)g.Bt + (size_t)nxt.pn * tstepB : cB;
;         for (int t = 0; t < nt; t += 2) {
;             const bool last = (t == nt - 2);
;             const char* a1 = cA + (size_t)(t + 1) * kstepA;
;             const char* a2 = last ? nA : cA + (size_t)(t + 2) * kstepA; const char* b2 = last ? nB : cB + (size_t)(t + 2) * kstepB;
;             const char* a3 = a2 + kstepA; const char* b3 = b2 + kstepB;
;             PG8_LDB(B0, 0, 0); PG8_LDB(B1, 0, 1); PG8_SCHED; PG8_LDA(At, 0, 0); PG8_STAGE(PG8_SA(1, 1), a1 + hstepA, voffA);
;             PG8_WAIT_V(8); PG8_WAIT_L(0); PG8_BAR; PG8_MMA(0, 0, At, B0); PG8_MMA(0, 1, At, B1); PG8_BAR; PG8_SCHED;
;     ...
; #pragma unroll
;         for (int a = 0; a < 2; ++a)
; #pragma unroll
;             for (int b = 0; b < 2; ++b)
; #pragma unroll
;                 for (int m = 0; m < 4; ++m)
; #pragma unroll
;                     for (int n = 0; n < 2; ++n) acc[a][b][m][n] = (f32x4){0.f, 0.f, 0.f, 0.f};
.LBB0_134:
	s_ashr_i32 s31, s30, 31
	s_lshl_b64 s[22:23], s[30:31], 19
	s_add_u32 s34, s48, s22
	s_addc_u32 s35, s49, s23
	s_and_b64 s[22:23], s[38:39], exec
	s_cselect_b32 s31, s35, s45
	s_cselect_b32 s85, s34, s44
	s_ashr_i32 s29, s28, 31
	s_lshl_b64 s[22:23], s[28:29], 19
	s_add_u32 s36, s50, s22
	s_addc_u32 s37, s51, s23
	s_and_b64 s[22:23], s[38:39], exec
	s_cselect_b32 s29, s37, s19
	s_cselect_b32 s88, s36, s18
	s_add_u32 s89, s18, 0x100
	s_addc_u32 s90, s19, 0
	s_add_u32 s44, s44, 0x40080
	v_mov_b32_e32 v2, 0
	s_addc_u32 s45, s45, 0
	s_mov_b32 s91, -2
	v_mov_b32_e32 v3, v2
	v_mov_b32_e32 v4, v2
	v_mov_b32_e32 v5, v2
	v_mov_b32_e32 v6, v2
	v_mov_b32_e32 v7, v2
	v_mov_b32_e32 v8, v2
	v_mov_b32_e32 v9, v2
	v_mov_b32_e32 v18, v2
	v_mov_b32_e32 v19, v2
	v_mov_b32_e32 v20, v2
	v_mov_b32_e32 v21, v2
	v_mov_b32_e32 v22, v2
	v_mov_b32_e32 v23, v2
	v_mov_b32_e32 v24, v2
	v_mov_b32_e32 v25, v2
	v_mov_b32_e32 v34, v2
	v_mov_b32_e32 v35, v2
	v_mov_b32_e32 v36, v2
	v_mov_b32_e32 v37, v2
	v_mov_b32_e32 v38, v2
	v_mov_b32_e32 v39, v2
	v_mov_b32_e32 v40, v2
	v_mov_b32_e32 v41, v2
	v_mov_b32_e32 v50, v2
	v_mov_b32_e32 v51, v2
	v_mov_b32_e32 v52, v2
	v_mov_b32_e32 v53, v2
	v_mov_b32_e32 v54, v2
	v_mov_b32_e32 v55, v2
	v_mov_b32_e32 v56, v2
	v_mov_b32_e32 v57, v2
	v_mov_b32_e32 v10, v2
	v_mov_b32_e32 v11, v2
	v_mov_b32_e32 v12, v2
	v_mov_b32_e32 v13, v2
	v_mov_b32_e32 v14, v2
	v_mov_b32_e32 v15, v2
	v_mov_b32_e32 v16, v2
	v_mov_b32_e32 v17, v2
	v_mov_b32_e32 v26, v2
	v_mov_b32_e32 v27, v2
	v_mov_b32_e32 v28, v2
	v_mov_b32_e32 v29, v2
	v_mov_b32_e32 v30, v2
	v_mov_b32_e32 v31, v2
	v_mov_b32_e32 v32, v2
	v_mov_b32_e32 v33, v2
	v_mov_b32_e32 v42, v2
	v_mov_b32_e32 v43, v2
	v_mov_b32_e32 v44, v2
	v_mov_b32_e32 v45, v2
	v_mov_b32_e32 v46, v2
	v_mov_b32_e32 v47, v2
	v_mov_b32_e32 v48, v2
	v_mov_b32_e32 v49, v2
	v_mov_b32_e32 v58, v2
	v_mov_b32_e32 v59, v2
	v_mov_b32_e32 v60, v2
	v_mov_b32_e32 v61, v2
	v_mov_b32_e32 v62, v2
	v_mov_b32_e32 v63, v2
	v_mov_b32_e32 v64, v2
	v_mov_b32_e32 v65, v2
	v_mov_b32_e32 v66, v2
	v_mov_b32_e32 v67, v2
	v_mov_b32_e32 v68, v2
	v_mov_b32_e32 v69, v2
	v_mov_b32_e32 v70, v2
	v_mov_b32_e32 v71, v2
	v_mov_b32_e32 v72, v2
	v_mov_b32_e32 v73, v2
	v_mov_b32_e32 v82, v2
	v_mov_b32_e32 v83, v2
	v_mov_b32_e32 v84, v2
	v_mov_b32_e32 v85, v2
	v_mov_b32_e32 v86, v2
	v_mov_b32_e32 v87, v2
	v_mov_b32_e32 v88, v2
	v_mov_b32_e32 v89, v2
	v_mov_b32_e32 v98, v2
	v_mov_b32_e32 v99, v2
	v_mov_b32_e32 v100, v2
	v_mov_b32_e32 v101, v2
	v_mov_b32_e32 v102, v2
	v_mov_b32_e32 v103, v2
	v_mov_b32_e32 v104, v2
	v_mov_b32_e32 v105, v2
	v_mov_b32_e32 v114, v2
	v_mov_b32_e32 v115, v2
	v_mov_b32_e32 v116, v2
	v_mov_b32_e32 v117, v2
	v_mov_b32_e32 v118, v2
	v_mov_b32_e32 v119, v2
	v_mov_b32_e32 v120, v2
	v_mov_b32_e32 v121, v2
	v_mov_b32_e32 v74, v2
	v_mov_b32_e32 v75, v2
	v_mov_b32_e32 v76, v2
	v_mov_b32_e32 v77, v2
	v_mov_b32_e32 v78, v2
	v_mov_b32_e32 v79, v2
	v_mov_b32_e32 v80, v2
	v_mov_b32_e32 v81, v2
	v_mov_b32_e32 v90, v2
	v_mov_b32_e32 v91, v2
	v_mov_b32_e32 v92, v2
	v_mov_b32_e32 v93, v2
	v_mov_b32_e32 v94, v2
	v_mov_b32_e32 v95, v2
	v_mov_b32_e32 v96, v2
	v_mov_b32_e32 v97, v2
	v_mov_b32_e32 v106, v2
	v_mov_b32_e32 v107, v2
	v_mov_b32_e32 v108, v2
	v_mov_b32_e32 v109, v2
	v_mov_b32_e32 v110, v2
	v_mov_b32_e32 v111, v2
	v_mov_b32_e32 v112, v2
	v_mov_b32_e32 v113, v2
	v_mov_b32_e32 v122, v2
	v_mov_b32_e32 v123, v2
	v_mov_b32_e32 v124, v2
	v_mov_b32_e32 v125, v2
	v_mov_b32_e32 v126, v2
	v_mov_b32_e32 v127, v2
	v_mov_b32_e32 v128, v2
	v_mov_b32_e32 v129, v2
	v_readfirstlane_b32 s2, v220
	s_lshr_b32 s2, s2, 8
	s_cmp_eq_u32 s2, 0
	s_cbranch_scc1 .Lsprio_0
	s_setprio 1
.Lsprio_0:
.LBB0_135:
	s_add_u32 s2, s44, 0xfffc0080
	s_addc_u32 s15, s45, -1
	s_add_i32 s25, 0, 0x10000
	s_cmp_eq_u32 s91, 12
	s_cselect_b32 s23, s31, s15
	s_cselect_b32 s22, s85, s2
	s_cselect_b32 s19, s29, s90
	s_cselect_b32 s18, s88, s89
	s_add_i32 s2, 0, 0x14000
	v_add_u32_e32 v158, s25, v148
	v_add_u32_e32 v170, s2, v148
	ds_read_b128 v[144:147], v158
	ds_read_b128 v[150:153], v158 offset:1024
	ds_read_b128 v[154:157], v158 offset:2048
	ds_read_b128 v[158:161], v158 offset:3072
	ds_read_b128 v[162:165], v170
	ds_read_b128 v[166:169], v170 offset:1024
	ds_read_b128 v[180:183], v170 offset:2048
	ds_read_b128 v[184:187], v170 offset:3072
	v_lshl_add_u64 v[170:171], s[44:45], 0, v[142:143]
	s_add_i32 m0, s69, 0xc000
	ds_read_b128 v[188:191], v149
	ds_read_b128 v[192:195], v149 offset:1024
	ds_read_b128 v[196:199], v149 offset:2048
	ds_read_b128 v[200:203], v149 offset:3072
	ds_read_b128 v[204:207], v149 offset:4096
	ds_read_b128 v[208:211], v149 offset:5120
	ds_read_b128 v[212:215], v149 offset:6144
	ds_read_b128 v[216:219], v149 offset:7168
	global_load_lds_dwordx4 v[170:171], off
	v_lshl_add_u64 v[170:171], s[44:45], 0, v[140:141]
	s_add_i32 m0, s69, 0xe000
	s_nop 0
	global_load_lds_dwordx4 v[170:171], off
	s_waitcnt vmcnt(8)
	s_waitcnt lgkmcnt(0)
	s_barrier
; #define PG8_STAGE(bufoff, gbase, voff) do { _Pragma("unroll") for (int _i = 0; _i < 2; ++_i) \
;         __builtin_amdgcn_global_load_lds((const unsigned*)((const char*)(gbase) + (voff)[_i]), (LAS unsigned*)(lds + (bufoff) + ldsw + _i * 8192), 16, 0, 0); } while (0)
; #define PG8_LDA(dst, b, h) do { _Pragma("unroll") for (int m = 0; m < 4; ++m) _Pragma("unroll") for (int k = 0; k < 2; ++k) dst[m][k] = *(const LAS bf16x8*)(lds + PG8_SA(b, h) + aoff + m * 2048 + k * 1024); } while (0)
; #define PG8_LDB(dst, b, h) do { _Pragma("unroll") for (int n = 0; n < 2; ++n) _Pragma("unroll") for (int k = 0; k < 2; ++k) dst[n][k] = *(const LAS bf16x8*)(lds + PG8_SB(b, h) + boff + n * 2048 + k * 1024); } while (0)
; #define PG8_MMA(ai, bj, At, Bt) do { __builtin_amdgcn_s_setprio(1); _Pragma("unroll") for (int m = 0; m < 4; ++m) _Pragma("unroll") for (int n = 0; n < 2; ++n) _Pragma("unroll") for (int k = 0; k < 2; ++k) \
;         acc[ai][bj][m][n] = __builtin_amdgcn_mfma_f32_16x16x32_bf16(Bt[n][k], At[m][k], acc[ai][bj][m][n], 0, 0, 0); __builtin_amdgcn_s_setprio(0); } while (0)
; #define PG8_WAIT_V(n) asm volatile("s_waitcnt vmcnt(" #n ")" ::: "memory")
; #define PG8_WAIT_L(n) asm volatile("s_waitcnt lgkmcnt(" #n ")" ::: "memory")
; #define PG8_BAR __builtin_amdgcn_s_barrier()
; #define PG8_SCHED __builtin_amdgcn_sched_barrier(0)
; template <class Epi>
; DI void gemm_phase(LAS unsigned char* lds, const Gemm g, const StaticOrder& S, const Epi& E) {
;     ...
;             PG8_LDB(B0, 0, 0); PG8_LDB(B1, 0, 1); PG8_SCHED; PG8_LDA(At, 0, 0); PG8_STAGE(PG8_SA(1, 1), a1 + hstepA, voffA);
;             PG8_WAIT_V(8); PG8_WAIT_L(0); PG8_BAR; PG8_MMA(0, 0, At, B0); PG8_MMA(0, 1, At, B1); PG8_BAR; PG8_SCHED;
;             PG8_LDA(At, 0, 1); PG8_STAGE(PG8_SB(0, 0), b2, voffB); PG8_STAGE(PG8_SB(0, 1), b2 + hstepB, voffB); PG8_STAGE(PG8_SA(0, 0), a2, voffA);
;             PG8_WAIT_V(8); PG8_WAIT_L(0); PG8_BAR; PG8_MMA(1, 0, At, B0); PG8_MMA(1, 1, At, B1); PG8_BAR; PG8_SCHED;
	s_waitcnt lgkmcnt(0)
	v_mfma_f32_16x16x32_bf16 v[126:129], v[144:147], v[188:191], v[126:129]
	v_mfma_f32_16x16x32_bf16 v[122:125], v[154:157], v[188:191], v[122:125]
	v_mfma_f32_16x16x32_bf16 v[110:113], v[144:147], v[196:199], v[110:113]
	v_mfma_f32_16x16x32_bf16 v[106:109], v[154:157], v[196:199], v[106:109]
	v_mfma_f32_16x16x32_bf16 v[94:97], v[144:147], v[204:207], v[94:97]
	v_mfma_f32_16x16x32_bf16 v[90:93], v[154:157], v[204:207], v[90:93]
	v_mfma_f32_16x16x32_bf16 v[78:81], v[144:147], v[212:215], v[78:81]
	v_mfma_f32_16x16x32_bf16 v[74:77], v[154:157], v[212:215], v[74:77]
	v_mfma_f32_16x16x32_bf16 v[126:129], v[150:153], v[192:195], v[126:129]
	v_mfma_f32_16x16x32_bf16 v[122:125], v[158:161], v[192:195], v[122:125]
	v_mfma_f32_16x16x32_bf16 v[110:113], v[150:153], v[200:203], v[110:113]
	v_mfma_f32_16x16x32_bf16 v[106:109], v[158:161], v[200:203], v[106:109]
	v_mfma_f32_16x16x32_bf16 v[94:97], v[150:153], v[208:211], v[94:97]
	v_mfma_f32_16x16x32_bf16 v[90:93], v[158:161], v[208:211], v[90:93]
	v_mfma_f32_16x16x32_bf16 v[78:81], v[150:153], v[216:219], v[78:81]
	v_mfma_f32_16x16x32_bf16 v[74:77], v[158:161], v[216:219], v[74:77]
	v_mfma_f32_16x16x32_bf16 v[118:121], v[162:165], v[188:191], v[118:121]
	v_mfma_f32_16x16x32_bf16 v[114:117], v[180:183], v[188:191], v[114:117]
	v_mfma_f32_16x16x32_bf16 v[102:105], v[162:165], v[196:199], v[102:105]
	v_mfma_f32_16x16x32_bf16 v[98:101], v[180:183], v[196:199], v[98:101]
	v_mfma_f32_16x16x32_bf16 v[86:89], v[162:165], v[204:207], v[86:89]
	v_mfma_f32_16x16x32_bf16 v[82:85], v[180:183], v[204:207], v[82:85]
	v_mfma_f32_16x16x32_bf16 v[70:73], v[162:165], v[212:215], v[70:73]
	v_mfma_f32_16x16x32_bf16 v[66:69], v[180:183], v[212:215], v[66:69]
	v_mfma_f32_16x16x32_bf16 v[118:121], v[166:169], v[192:195], v[118:121]
	v_mfma_f32_16x16x32_bf16 v[114:117], v[184:187], v[192:195], v[114:117]
	v_mfma_f32_16x16x32_bf16 v[102:105], v[166:169], v[200:203], v[102:105]
	v_mfma_f32_16x16x32_bf16 v[98:101], v[184:187], v[200:203], v[98:101]
	v_mfma_f32_16x16x32_bf16 v[86:89], v[166:169], v[208:211], v[86:89]
	v_mfma_f32_16x16x32_bf16 v[82:85], v[184:187], v[208:211], v[82:85]
	v_mfma_f32_16x16x32_bf16 v[70:73], v[166:169], v[216:219], v[70:73]
	v_mfma_f32_16x16x32_bf16 v[66:69], v[184:187], v[216:219], v[66:69]
	s_barrier
	s_add_i32 s15, s25, s62
	v_lshl_add_u64 v[170:171], s[18:19], 0, v[136:137]
	s_mov_b32 m0, s15
	ds_read_b128 v[188:191], v149 offset:16384
	ds_read_b128 v[192:195], v149 offset:17408
	ds_read_b128 v[196:199], v149 offset:18432
	ds_read_b128 v[200:203], v149 offset:19456
	ds_read_b128 v[204:207], v149 offset:20480
	ds_read_b128 v[208:211], v149 offset:21504
	ds_read_b128 v[212:215], v149 offset:22528
	ds_read_b128 v[216:219], v149 offset:23552
	global_load_lds_dwordx4 v[170:171], off
	s_add_i32 m0, s15, 0x2000
	s_add_u32 s92, s18, 0x40000
	v_lshl_add_u64 v[238:239], s[18:19], 0, v[132:133]
	s_addc_u32 s93, s19, 0
	s_add_i32 s2, s2, s62
	global_load_lds_dwordx4 v[238:239], off
	v_lshl_add_u64 v[240:241], s[92:93], 0, v[136:137]
	s_mov_b32 m0, s2
	v_lshl_add_u64 v[242:243], s[22:23], 0, v[134:135]
	global_load_lds_dwordx4 v[240:241], off
	v_lshl_add_u64 v[240:241], s[92:93], 0, v[132:133]
	s_add_i32 m0, s2, 0x2000
	s_nop 0
	global_load_lds_dwordx4 v[240:241], off
	v_lshl_add_u64 v[240:241], s[22:23], 0, v[138:139]
	s_mov_b32 m0, s69
	s_nop 0
	global_load_lds_dwordx4 v[240:241], off
	s_mov_b32 m0, s70
	s_nop 0
	global_load_lds_dwordx4 v[242:243], off
	s_waitcnt vmcnt(8)
	s_waitcnt lgkmcnt(0)
	s_barrier
	s_waitcnt lgkmcnt(0)
	v_mfma_f32_16x16x32_bf16 v[62:65], v[144:147], v[188:191], v[62:65]
	v_mfma_f32_16x16x32_bf16 v[58:61], v[154:157], v[188:191], v[58:61]
	v_mfma_f32_16x16x32_bf16 v[46:49], v[144:147], v[196:199], v[46:49]
	v_mfma_f32_16x16x32_bf16 v[42:45], v[154:157], v[196:199], v[42:45]
	v_mfma_f32_16x16x32_bf16 v[30:33], v[144:147], v[204:207], v[30:33]
	v_mfma_f32_16x16x32_bf16 v[26:29], v[154:157], v[204:207], v[26:29]
	v_mfma_f32_16x16x32_bf16 v[14:17], v[144:147], v[212:215], v[14:17]
	v_mfma_f32_16x16x32_bf16 v[10:13], v[154:157], v[212:215], v[10:13]
	v_mfma_f32_16x16x32_bf16 v[62:65], v[150:153], v[192:195], v[62:65]
	v_mfma_f32_16x16x32_bf16 v[58:61], v[158:161], v[192:195], v[58:61]
	v_mfma_f32_16x16x32_bf16 v[46:49], v[150:153], v[200:203], v[46:49]
	v_mfma_f32_16x16x32_bf16 v[42:45], v[158:161], v[200:203], v[42:45]
	v_mfma_f32_16x16x32_bf16 v[30:33], v[150:153], v[208:211], v[30:33]
	v_mfma_f32_16x16x32_bf16 v[26:29], v[158:161], v[208:211], v[26:29]
	v_mfma_f32_16x16x32_bf16 v[14:17], v[150:153], v[216:219], v[14:17]
	v_mfma_f32_16x16x32_bf16 v[10:13], v[158:161], v[216:219], v[10:13]
	v_mfma_f32_16x16x32_bf16 v[54:57], v[162:165], v[188:191], v[54:57]
	v_mfma_f32_16x16x32_bf16 v[50:53], v[180:183], v[188:191], v[50:53]
	v_mfma_f32_16x16x32_bf16 v[38:41], v[162:165], v[196:199], v[38:41]
	v_mfma_f32_16x16x32_bf16 v[34:37], v[180:183], v[196:199], v[34:37]
	v_mfma_f32_16x16x32_bf16 v[22:25], v[162:165], v[204:207], v[22:25]
	v_mfma_f32_16x16x32_bf16 v[18:21], v[180:183], v[204:207], v[18:21]
	v_mfma_f32_16x16x32_bf16 v[6:9], v[162:165], v[212:215], v[6:9]
	v_mfma_f32_16x16x32_bf16 v[2:5], v[180:183], v[212:215], v[2:5]
	v_mfma_f32_16x16x32_bf16 v[54:57], v[166:169], v[192:195], v[54:57]
	v_mfma_f32_16x16x32_bf16 v[50:53], v[184:187], v[192:195], v[50:53]
	v_mfma_f32_16x16x32_bf16 v[38:41], v[166:169], v[200:203], v[38:41]
	v_mfma_f32_16x16x32_bf16 v[34:37], v[184:187], v[200:203], v[34:37]
	v_mfma_f32_16x16x32_bf16 v[22:25], v[166:169], v[208:211], v[22:25]
	v_mfma_f32_16x16x32_bf16 v[18:21], v[184:187], v[208:211], v[18:21]
	v_mfma_f32_16x16x32_bf16 v[6:9], v[166:169], v[216:219], v[6:9]
	v_mfma_f32_16x16x32_bf16 v[2:5], v[184:187], v[216:219], v[2:5]
	s_barrier
; #define PG8_STAGE(bufoff, gbase, voff) do { _Pragma("unroll") for (int _i = 0; _i < 2; ++_i) \
;         __builtin_amdgcn_global_load_lds((const unsigned*)((const char*)(gbase) + (voff)[_i]), (LAS unsigned*)(lds + (bufoff) + ldsw + _i * 8192), 16, 0, 0); } while (0)
; #define PG8_LDA(dst, b, h) do { _Pragma("unroll") for (int m = 0; m < 4; ++m) _Pragma("unroll") for (int k = 0; k < 2; ++k) dst[m][k] = *(const LAS bf16x8*)(lds + PG8_SA(b, h) + aoff + m * 2048 + k * 1024); } while (0)
; #define PG8_LDB(dst, b, h) do { _Pragma("unroll") for (int n = 0; n < 2; ++n) _Pragma("unroll") for (int k = 0; k < 2; ++k) dst[n][k] = *(const LAS bf16x8*)(lds + PG8_SB(b, h) + boff + n * 2048 + k * 1024); } while (0)
; #define PG8_MMA(ai, bj, At, Bt) do { __builtin_amdgcn_s_setprio(1); _Pragma("unroll") for (int m = 0; m < 4; ++m) _Pragma("unroll") for (int n = 0; n < 2; ++n) _Pragma("unroll") for (int k = 0; k < 2; ++k) \
;         acc[ai][bj][m][n] = __builtin_amdgcn_mfma_f32_16x16x32_bf16(Bt[n][k], At[m][k], acc[ai][bj][m][n], 0, 0, 0); __builtin_amdgcn_s_setprio(0); } while (0)
; #define PG8_WAIT_V(n) asm volatile("s_waitcnt vmcnt(" #n ")" ::: "memory")
; #define PG8_WAIT_L(n) asm volatile("s_waitcnt lgkmcnt(" #n ")" ::: "memory")
; #define PG8_BAR __builtin_amdgcn_s_barrier()
; #define PG8_SCHED __builtin_amdgcn_sched_barrier(0)
; template <class Epi>
; DI void gemm_phase(LAS unsigned char* lds, const Gemm g, const StaticOrder& S, const Epi& E) {
;     ...
;             PG8_LDB(B0, 1, 0); PG8_LDB(B1, 1, 1); PG8_SCHED; PG8_LDA(At, 1, 0); PG8_STAGE(PG8_SA(0, 1), a2 + hstepA, voffA);
;             PG8_WAIT_V(8); PG8_WAIT_L(0); PG8_BAR; PG8_MMA(0, 0, At, B0); PG8_MMA(0, 1, At, B1); PG8_BAR; PG8_SCHED;
	s_add_i32 s2, 0, 0x18000
	s_add_i32 s15, 0, 0x1c000
	v_add_u32_e32 v158, s2, v148
	v_add_u32_e32 v184, s15, v148
	ds_read_b128 v[144:147], v158
	ds_read_b128 v[150:153], v158 offset:1024
	ds_read_b128 v[154:157], v158 offset:2048
	ds_read_b128 v[158:161], v158 offset:3072
	ds_read_b128 v[162:165], v184
	ds_read_b128 v[166:169], v184 offset:1024
	ds_read_b128 v[180:183], v184 offset:2048
	ds_read_b128 v[184:187], v184 offset:3072
	s_add_u32 s22, s22, 0x40000
	s_addc_u32 s23, s23, 0
	s_mov_b32 m0, s71
	v_lshl_add_u64 v[244:245], s[22:23], 0, v[138:139]
	ds_read_b128 v[188:191], v149 offset:32768
	ds_read_b128 v[192:195], v149 offset:33792
	ds_read_b128 v[196:199], v149 offset:34816
	ds_read_b128 v[200:203], v149 offset:35840
	ds_read_b128 v[204:207], v149 offset:36864
	ds_read_b128 v[208:211], v149 offset:37888
	ds_read_b128 v[212:215], v149 offset:38912
	ds_read_b128 v[216:219], v149 offset:39936
	global_load_lds_dwordx4 v[244:245], off
	v_lshl_add_u64 v[244:245], s[22:23], 0, v[134:135]
	s_mov_b32 m0, s72
	s_nop 0
	global_load_lds_dwordx4 v[244:245], off
	s_waitcnt vmcnt(8)
	s_waitcnt lgkmcnt(0)
	s_barrier
	s_waitcnt lgkmcnt(0)
	v_mfma_f32_16x16x32_bf16 v[126:129], v[144:147], v[188:191], v[126:129]
	v_mfma_f32_16x16x32_bf16 v[122:125], v[154:157], v[188:191], v[122:125]
	v_mfma_f32_16x16x32_bf16 v[110:113], v[144:147], v[196:199], v[110:113]
	v_mfma_f32_16x16x32_bf16 v[106:109], v[154:157], v[196:199], v[106:109]
	v_mfma_f32_16x16x32_bf16 v[94:97], v[144:147], v[204:207], v[94:97]
	v_mfma_f32_16x16x32_bf16 v[90:93], v[154:157], v[204:207], v[90:93]
	v_mfma_f32_16x16x32_bf16 v[78:81], v[144:147], v[212:215], v[78:81]
	v_mfma_f32_16x16x32_bf16 v[74:77], v[154:157], v[212:215], v[74:77]
	v_mfma_f32_16x16x32_bf16 v[126:129], v[150:153], v[192:195], v[126:129]
	v_mfma_f32_16x16x32_bf16 v[122:125], v[158:161], v[192:195], v[122:125]
	v_mfma_f32_16x16x32_bf16 v[110:113], v[150:153], v[200:203], v[110:113]
	v_mfma_f32_16x16x32_bf16 v[106:109], v[158:161], v[200:203], v[106:109]
	v_mfma_f32_16x16x32_bf16 v[94:97], v[150:153], v[208:211], v[94:97]
	v_mfma_f32_16x16x32_bf16 v[90:93], v[158:161], v[208:211], v[90:93]
	v_mfma_f32_16x16x32_bf16 v[78:81], v[150:153], v[216:219], v[78:81]
	v_mfma_f32_16x16x32_bf16 v[74:77], v[158:161], v[216:219], v[74:77]
	v_mfma_f32_16x16x32_bf16 v[118:121], v[162:165], v[188:191], v[118:121]
	v_mfma_f32_16x16x32_bf16 v[114:117], v[180:183], v[188:191], v[114:117]
	v_mfma_f32_16x16x32_bf16 v[102:105], v[162:165], v[196:199], v[102:105]
	v_mfma_f32_16x16x32_bf16 v[98:101], v[180:183], v[196:199], v[98:101]
	v_mfma_f32_16x16x32_bf16 v[86:89], v[162:165], v[204:207], v[86:89]
	v_mfma_f32_16x16x32_bf16 v[82:85], v[180:183], v[204:207], v[82:85]
	v_mfma_f32_16x16x32_bf16 v[70:73], v[162:165], v[212:215], v[70:73]
	v_mfma_f32_16x16x32_bf16 v[66:69], v[180:183], v[212:215], v[66:69]
	v_mfma_f32_16x16x32_bf16 v[118:121], v[166:169], v[192:195], v[118:121]
	v_mfma_f32_16x16x32_bf16 v[114:117], v[184:187], v[192:195], v[114:117]
	v_mfma_f32_16x16x32_bf16 v[102:105], v[166:169], v[200:203], v[102:105]
	v_mfma_f32_16x16x32_bf16 v[98:101], v[184:187], v[200:203], v[98:101]
	v_mfma_f32_16x16x32_bf16 v[86:89], v[166:169], v[208:211], v[86:89]
	v_mfma_f32_16x16x32_bf16 v[82:85], v[184:187], v[208:211], v[82:85]
	v_mfma_f32_16x16x32_bf16 v[70:73], v[166:169], v[216:219], v[70:73]
	v_mfma_f32_16x16x32_bf16 v[66:69], v[184:187], v[216:219], v[66:69]
	s_barrier
; #define PG8_STAGE(bufoff, gbase, voff) do { _Pragma("unroll") for (int _i = 0; _i < 2; ++_i) \
;         __builtin_amdgcn_global_load_lds((const unsigned*)((const char*)(gbase) + (voff)[_i]), (LAS unsigned*)(lds + (bufoff) + ldsw + _i * 8192), 16, 0, 0); } while (0)
; #define PG8_LDA(dst, b, h) do { _Pragma("unroll") for (int m = 0; m < 4; ++m) _Pragma("unroll") for (int k = 0; k < 2; ++k) dst[m][k] = *(const LAS bf16x8*)(lds + PG8_SA(b, h) + aoff + m * 2048 + k * 1024); } while (0)
; #define PG8_MMA(ai, bj, At, Bt) do { __builtin_amdgcn_s_setprio(1); _Pragma("unroll") for (int m = 0; m < 4; ++m) _Pragma("unroll") for (int n = 0; n < 2; ++n) _Pragma("unroll") for (int k = 0; k < 2; ++k) \
;         acc[ai][bj][m][n] = __builtin_amdgcn_mfma_f32_16x16x32_bf16(Bt[n][k], At[m][k], acc[ai][bj][m][n], 0, 0, 0); __builtin_amdgcn_s_setprio(0); } while (0)
; #define PG8_WAIT_V(n) asm volatile("s_waitcnt vmcnt(" #n ")" ::: "memory")
; #define PG8_WAIT_L(n) asm volatile("s_waitcnt lgkmcnt(" #n ")" ::: "memory")
; #define PG8_BAR __builtin_amdgcn_s_barrier()
; #define PG8_SCHED __builtin_amdgcn_sched_barrier(0)
; template <class Epi>
; DI void gemm_phase(LAS unsigned char* lds, const Gemm g, const StaticOrder& S, const Epi& E) {
;     ...
;             PG8_LDA(At, 1, 1); PG8_STAGE(PG8_SB(1, 0), b3, voffB); PG8_STAGE(PG8_SB(1, 1), b3 + hstepB, voffB); PG8_STAGE(PG8_SA(1, 0), a3, voffA);
;             PG8_WAIT_V(8); PG8_WAIT_L(0); PG8_BAR; PG8_MMA(1, 0, At, B0); PG8_MMA(1, 1, At, B1); PG8_BAR; PG8_SCHED;
;         }
;         if (wr == 0) PG8_BAR;
	s_add_i32 s2, s2, s62
	v_lshl_add_u64 v[170:171], v[170:171], 0, s[6:7]
	s_mov_b32 m0, s2
	ds_read_b128 v[188:191], v149 offset:49152
	ds_read_b128 v[192:195], v149 offset:50176
	ds_read_b128 v[196:199], v149 offset:51200
	ds_read_b128 v[200:203], v149 offset:52224
	ds_read_b128 v[204:207], v149 offset:53248
	ds_read_b128 v[208:211], v149 offset:54272
	ds_read_b128 v[212:215], v149 offset:55296
	ds_read_b128 v[216:219], v149 offset:56320
	global_load_lds_dwordx4 v[170:171], off
	s_add_i32 m0, s2, 0x2000
	s_add_u32 s18, s18, 0x40080
	v_lshl_add_u64 v[170:171], v[238:239], 0, s[6:7]
	s_addc_u32 s19, s19, 0
	s_add_i32 s2, s15, s62
	global_load_lds_dwordx4 v[170:171], off
	v_lshl_add_u64 v[170:171], s[18:19], 0, v[136:137]
	s_mov_b32 m0, s2
	s_nop 0
	global_load_lds_dwordx4 v[170:171], off
	v_lshl_add_u64 v[170:171], s[18:19], 0, v[132:133]
	s_add_i32 m0, s2, 0x2000
	s_nop 0
	global_load_lds_dwordx4 v[170:171], off
	v_lshl_add_u64 v[170:171], v[240:241], 0, s[6:7]
	s_mov_b32 m0, s74
	s_nop 0
	global_load_lds_dwordx4 v[170:171], off
	v_lshl_add_u64 v[170:171], v[242:243], 0, s[6:7]
	s_mov_b32 m0, s75
	s_nop 0
	global_load_lds_dwordx4 v[170:171], off
	s_waitcnt vmcnt(8)
	s_waitcnt lgkmcnt(0)
	s_barrier
	s_waitcnt lgkmcnt(0)
	v_mfma_f32_16x16x32_bf16 v[62:65], v[144:147], v[188:191], v[62:65]
	v_mfma_f32_16x16x32_bf16 v[58:61], v[154:157], v[188:191], v[58:61]
	v_mfma_f32_16x16x32_bf16 v[46:49], v[144:147], v[196:199], v[46:49]
	v_mfma_f32_16x16x32_bf16 v[42:45], v[154:157], v[196:199], v[42:45]
	v_mfma_f32_16x16x32_bf16 v[30:33], v[144:147], v[204:207], v[30:33]
	v_mfma_f32_16x16x32_bf16 v[26:29], v[154:157], v[204:207], v[26:29]
	v_mfma_f32_16x16x32_bf16 v[14:17], v[144:147], v[212:215], v[14:17]
	v_mfma_f32_16x16x32_bf16 v[10:13], v[154:157], v[212:215], v[10:13]
	v_mfma_f32_16x16x32_bf16 v[62:65], v[150:153], v[192:195], v[62:65]
	v_mfma_f32_16x16x32_bf16 v[58:61], v[158:161], v[192:195], v[58:61]
	v_mfma_f32_16x16x32_bf16 v[46:49], v[150:153], v[200:203], v[46:49]
	v_mfma_f32_16x16x32_bf16 v[42:45], v[158:161], v[200:203], v[42:45]
	v_mfma_f32_16x16x32_bf16 v[30:33], v[150:153], v[208:211], v[30:33]
	v_mfma_f32_16x16x32_bf16 v[26:29], v[158:161], v[208:211], v[26:29]
	v_mfma_f32_16x16x32_bf16 v[14:17], v[150:153], v[216:219], v[14:17]
	v_mfma_f32_16x16x32_bf16 v[10:13], v[158:161], v[216:219], v[10:13]
	v_mfma_f32_16x16x32_bf16 v[54:57], v[162:165], v[188:191], v[54:57]
	v_mfma_f32_16x16x32_bf16 v[50:53], v[180:183], v[188:191], v[50:53]
	v_mfma_f32_16x16x32_bf16 v[38:41], v[162:165], v[196:199], v[38:41]
	v_mfma_f32_16x16x32_bf16 v[34:37], v[180:183], v[196:199], v[34:37]
	v_mfma_f32_16x16x32_bf16 v[22:25], v[162:165], v[204:207], v[22:25]
	v_mfma_f32_16x16x32_bf16 v[18:21], v[180:183], v[204:207], v[18:21]
	v_mfma_f32_16x16x32_bf16 v[6:9], v[162:165], v[212:215], v[6:9]
	v_mfma_f32_16x16x32_bf16 v[2:5], v[180:183], v[212:215], v[2:5]
	v_mfma_f32_16x16x32_bf16 v[54:57], v[166:169], v[192:195], v[54:57]
	v_mfma_f32_16x16x32_bf16 v[50:53], v[184:187], v[192:195], v[50:53]
	v_mfma_f32_16x16x32_bf16 v[38:41], v[166:169], v[200:203], v[38:41]
	v_mfma_f32_16x16x32_bf16 v[34:37], v[184:187], v[200:203], v[34:37]
	v_mfma_f32_16x16x32_bf16 v[22:25], v[166:169], v[208:211], v[22:25]
	v_mfma_f32_16x16x32_bf16 v[18:21], v[184:187], v[208:211], v[18:21]
	v_mfma_f32_16x16x32_bf16 v[6:9], v[166:169], v[216:219], v[6:9]
	v_mfma_f32_16x16x32_bf16 v[2:5], v[184:187], v[216:219], v[2:5]
	s_barrier
	s_add_i32 s91, s91, 2
	s_add_u32 s89, s89, 0x100
	s_addc_u32 s90, s90, 0
	s_add_u32 s44, s44, 0x100
	s_addc_u32 s45, s45, 0
	s_cmp_gt_u32 s91, 13
	s_cbranch_scc0 .LBB0_135
	s_setprio 0
	s_and_b64 vcc, exec, s[26:27]
	s_movk_i32 s88, 0x7f
	v_readlane_b32 s89, v255, 19
	v_readlane_b32 s41, v255, 24
	s_cbranch_vccz .LBB0_138
	s_barrier

; #define PG8_STAGE(bufoff, gbase, voff) do { _Pragma("unroll") for (int _i = 0; _i < 2; ++_i) \
;         __builtin_amdgcn_global_load_lds((const unsigned*)((const char*)(gbase) + (voff)[_i]), (LAS unsigned*)(lds + (bufoff) + ldsw + _i * 8192), 16, 0, 0); } while (0)
; #define PG8_LDA(dst, b, h) do { _Pragma("unroll") for (int m = 0; m < 4; ++m) _Pragma("unroll") for (int k = 0; k < 2; ++k) dst[m][k] = *(const LAS bf16x8*)(lds + PG8_SA(b, h) + aoff + m * 2048 + k * 1024); } while (0)
; #define PG8_LDB(dst, b, h) do { _Pragma("unroll") for (int n = 0; n < 2; ++n) _Pragma("unroll") for (int k = 0; k < 2; ++k) dst[n][k] = *(const LAS bf16x8*)(lds + PG8_SB(b, h) + boff + n * 2048 + k * 1024); } while (0)
; #define PG8_MMA(ai, bj, At, Bt) do { __builtin_amdgcn_s_setprio(1); _Pragma("unroll") for (int m = 0; m < 4; ++m) _Pragma("unroll") for (int n = 0; n < 2; ++n) _Pragma("unroll") for (int k = 0; k < 2; ++k) \
;         acc[ai][bj][m][n] = __builtin_amdgcn_mfma_f32_16x16x32_bf16(Bt[n][k], At[m][k], acc[ai][bj][m][n], 0, 0, 0); __builtin_amdgcn_s_setprio(0); } while (0)
; #define PG8_BAR __builtin_amdgcn_s_barrier()
; template <class Epi>
; DI void gemm_phase(LAS unsigned char* lds, const Gemm g, const StaticOrder& S, const Epi& E) {
;     ...
;         const bool has_next = S.next(ui + 1, nxt);
;         const char* nA = has_next ? (const char*)g.A + (size_t)nxt.pm * tstepA + (size_t)nxt.pn * g.a_pn_off * 2 : cA; const char* nB = has_next ? (const char*)g.Bt + (size_t)nxt.pn * tstepB : cB;
;         for (int t = 0; t < nt; t += 2) {
;             const bool last = (t == nt - 2);
;             const char* a1 = cA + (size_t)(t + 1) * kstepA;
;             const char* a2 = last ? nA : cA + (size_t)(t + 2) * kstepA; const char* b2 = last ? nB : cB + (size_t)(t + 2) * kstepB;
;             const char* a3 = a2 + kstepA; const char* b3 = b2 + kstepB;
;             PG8_LDB(B0, 0, 0); PG8_LDB(B1, 0, 1); PG8_SCHED; PG8_LDA(At, 0, 0); PG8_STAGE(PG8_SA(1, 1), a1 + hstepA, voffA);
;             PG8_WAIT_V(8); PG8_WAIT_L(0); PG8_BAR; PG8_MMA(0, 0, At, B0); PG8_MMA(0, 1, At, B1); PG8_BAR; PG8_SCHED;
;     ...
; #pragma unroll
;         for (int a = 0; a < 2; ++a)
; #pragma unroll
;             for (int b = 0; b < 2; ++b)
; #pragma unroll
;                 for (int m = 0; m < 4; ++m)
; #pragma unroll
;                     for (int n = 0; n < 2; ++n) acc[a][b][m][n] = (f32x4){0.f, 0.f, 0.f, 0.f};
.LBB0_274:
	s_ashr_i32 s45, s44, 31
	s_lshl_b64 s[0:1], s[44:45], 15
	s_add_u32 s46, s20, s0
	s_addc_u32 s47, s21, s1
	s_and_b64 s[0:1], s[42:43], exec
	s_cselect_b32 s45, s47, s51
	s_cselect_b32 s90, s46, s50
	s_ashr_i32 s41, s40, 31
	s_lshl_b64 s[0:1], s[40:41], 15
	s_add_u32 s48, s26, s0
	s_addc_u32 s49, s27, s1
	s_and_b64 s[0:1], s[42:43], exec
	s_cselect_b32 s41, s49, s19
	s_cselect_b32 s91, s48, s18
	s_add_u32 s93, s18, 0x40000
	s_addc_u32 s94, s19, 0
	s_add_u32 s50, s50, 0x20c000
	v_mov_b32_e32 v2, 0
	s_addc_u32 s51, s51, 0
	s_mov_b32 s95, -2
	v_mov_b32_e32 v3, v2
	v_mov_b32_e32 v4, v2
	v_mov_b32_e32 v5, v2
	v_mov_b32_e32 v6, v2
	v_mov_b32_e32 v7, v2
	v_mov_b32_e32 v8, v2
	v_mov_b32_e32 v9, v2
	v_mov_b32_e32 v18, v2
	v_mov_b32_e32 v19, v2
	v_mov_b32_e32 v20, v2
	v_mov_b32_e32 v21, v2
	v_mov_b32_e32 v22, v2
	v_mov_b32_e32 v23, v2
	v_mov_b32_e32 v24, v2
	v_mov_b32_e32 v25, v2
	v_mov_b32_e32 v34, v2
	v_mov_b32_e32 v35, v2
	v_mov_b32_e32 v36, v2
	v_mov_b32_e32 v37, v2
	v_mov_b32_e32 v38, v2
	v_mov_b32_e32 v39, v2
	v_mov_b32_e32 v40, v2
	v_mov_b32_e32 v41, v2
	v_mov_b32_e32 v50, v2
	v_mov_b32_e32 v51, v2
	v_mov_b32_e32 v52, v2
	v_mov_b32_e32 v53, v2
	v_mov_b32_e32 v54, v2
	v_mov_b32_e32 v55, v2
	v_mov_b32_e32 v56, v2
	v_mov_b32_e32 v57, v2
	v_mov_b32_e32 v10, v2
	v_mov_b32_e32 v11, v2
	v_mov_b32_e32 v12, v2
	v_mov_b32_e32 v13, v2
	v_mov_b32_e32 v14, v2
	v_mov_b32_e32 v15, v2
	v_mov_b32_e32 v16, v2
	v_mov_b32_e32 v17, v2
	v_mov_b32_e32 v26, v2
	v_mov_b32_e32 v27, v2
	v_mov_b32_e32 v28, v2
	v_mov_b32_e32 v29, v2
	v_mov_b32_e32 v30, v2
	v_mov_b32_e32 v31, v2
	v_mov_b32_e32 v32, v2
	v_mov_b32_e32 v33, v2
	v_mov_b32_e32 v42, v2
	v_mov_b32_e32 v43, v2
	v_mov_b32_e32 v44, v2
	v_mov_b32_e32 v45, v2
	v_mov_b32_e32 v46, v2
	v_mov_b32_e32 v47, v2
	v_mov_b32_e32 v48, v2
	v_mov_b32_e32 v49, v2
	v_mov_b32_e32 v58, v2
	v_mov_b32_e32 v59, v2
	v_mov_b32_e32 v60, v2
	v_mov_b32_e32 v61, v2
	v_mov_b32_e32 v62, v2
	v_mov_b32_e32 v63, v2
	v_mov_b32_e32 v64, v2
	v_mov_b32_e32 v65, v2
	v_mov_b32_e32 v66, v2
	v_mov_b32_e32 v67, v2
	v_mov_b32_e32 v68, v2
	v_mov_b32_e32 v69, v2
	v_mov_b32_e32 v70, v2
	v_mov_b32_e32 v71, v2
	v_mov_b32_e32 v72, v2
	v_mov_b32_e32 v73, v2
	v_mov_b32_e32 v82, v2
	v_mov_b32_e32 v83, v2
	v_mov_b32_e32 v84, v2
	v_mov_b32_e32 v85, v2
	v_mov_b32_e32 v86, v2
	v_mov_b32_e32 v87, v2
	v_mov_b32_e32 v88, v2
	v_mov_b32_e32 v89, v2
	v_mov_b32_e32 v98, v2
	v_mov_b32_e32 v99, v2
	v_mov_b32_e32 v100, v2
	v_mov_b32_e32 v101, v2
	v_mov_b32_e32 v102, v2
	v_mov_b32_e32 v103, v2
	v_mov_b32_e32 v104, v2
	v_mov_b32_e32 v105, v2
	v_mov_b32_e32 v114, v2
	v_mov_b32_e32 v115, v2
	v_mov_b32_e32 v116, v2
	v_mov_b32_e32 v117, v2
	v_mov_b32_e32 v118, v2
	v_mov_b32_e32 v119, v2
	v_mov_b32_e32 v120, v2
	v_mov_b32_e32 v121, v2
	v_mov_b32_e32 v74, v2
	v_mov_b32_e32 v75, v2
	v_mov_b32_e32 v76, v2
	v_mov_b32_e32 v77, v2
	v_mov_b32_e32 v78, v2
	v_mov_b32_e32 v79, v2
	v_mov_b32_e32 v80, v2
	v_mov_b32_e32 v81, v2
	v_mov_b32_e32 v90, v2
	v_mov_b32_e32 v91, v2
	v_mov_b32_e32 v92, v2
	v_mov_b32_e32 v93, v2
	v_mov_b32_e32 v94, v2
	v_mov_b32_e32 v95, v2
	v_mov_b32_e32 v96, v2
	v_mov_b32_e32 v97, v2
	v_mov_b32_e32 v106, v2
	v_mov_b32_e32 v107, v2
	v_mov_b32_e32 v108, v2
	v_mov_b32_e32 v109, v2
	v_mov_b32_e32 v110, v2
	v_mov_b32_e32 v111, v2
	v_mov_b32_e32 v112, v2
	v_mov_b32_e32 v113, v2
	v_mov_b32_e32 v122, v2
	v_mov_b32_e32 v123, v2
	v_mov_b32_e32 v124, v2
	v_mov_b32_e32 v125, v2
	v_mov_b32_e32 v126, v2
	v_mov_b32_e32 v127, v2
	v_mov_b32_e32 v128, v2
	v_mov_b32_e32 v129, v2
	v_readfirstlane_b32 s2, v220
	s_lshr_b32 s2, s2, 8
	s_cmp_eq_u32 s2, 0
	s_cbranch_scc1 .Lsprio_1
	s_setprio 1
.Lsprio_1:
.LBB0_275:
	s_add_u32 s0, s50, 0x204000
	s_addc_u32 s1, s51, 0
	s_cmp_eq_u32 s95, 40
	s_cselect_b32 s22, s90, s0
	s_cselect_b32 s23, s45, s1
	s_cselect_b32 s74, s91, s93
	s_cselect_b32 s75, s41, s94
	s_add_u32 s18, s22, 0x208000
	s_addc_u32 s19, s23, 0
	s_add_i32 s0, 0, 0x10000
	v_add_u32_e32 v146, s0, v150
	s_add_i32 s2, 0, 0x14000
	ds_read_b128 v[142:145], v146
	ds_read_b128 v[152:155], v146 offset:1024
	ds_read_b128 v[156:159], v146 offset:2048
	ds_read_b128 v[160:163], v146 offset:3072
	v_add_u32_e32 v146, s2, v150
	ds_read_b128 v[164:167], v146
	ds_read_b128 v[168:171], v146 offset:1024
	ds_read_b128 v[180:183], v146 offset:2048
	ds_read_b128 v[184:187], v146 offset:3072
	v_lshl_add_u64 v[146:147], s[50:51], 0, v[140:141]
	s_add_i32 m0, s70, 0xc000
	ds_read_b128 v[188:191], v151
	ds_read_b128 v[192:195], v151 offset:1024
	ds_read_b128 v[196:199], v151 offset:2048
	ds_read_b128 v[200:203], v151 offset:3072
	ds_read_b128 v[204:207], v151 offset:4096
	ds_read_b128 v[208:211], v151 offset:5120
	ds_read_b128 v[212:215], v151 offset:6144
	ds_read_b128 v[216:219], v151 offset:7168
	global_load_lds_dwordx4 v[146:147], off
	v_lshl_add_u64 v[146:147], s[50:51], 0, v[138:139]
	s_add_i32 m0, s70, 0xe000
	s_nop 0
	global_load_lds_dwordx4 v[146:147], off
	s_waitcnt vmcnt(8)
	s_waitcnt lgkmcnt(0)
	s_barrier
; #define PG8_STAGE(bufoff, gbase, voff) do { _Pragma("unroll") for (int _i = 0; _i < 2; ++_i) \
;         __builtin_amdgcn_global_load_lds((const unsigned*)((const char*)(gbase) + (voff)[_i]), (LAS unsigned*)(lds + (bufoff) + ldsw + _i * 8192), 16, 0, 0); } while (0)
; #define PG8_LDA(dst, b, h) do { _Pragma("unroll") for (int m = 0; m < 4; ++m) _Pragma("unroll") for (int k = 0; k < 2; ++k) dst[m][k] = *(const LAS bf16x8*)(lds + PG8_SA(b, h) + aoff + m * 2048 + k * 1024); } while (0)
; #define PG8_LDB(dst, b, h) do { _Pragma("unroll") for (int n = 0; n < 2; ++n) _Pragma("unroll") for (int k = 0; k < 2; ++k) dst[n][k] = *(const LAS bf16x8*)(lds + PG8_SB(b, h) + boff + n * 2048 + k * 1024); } while (0)
; #define PG8_MMA(ai, bj, At, Bt) do { __builtin_amdgcn_s_setprio(1); _Pragma("unroll") for (int m = 0; m < 4; ++m) _Pragma("unroll") for (int n = 0; n < 2; ++n) _Pragma("unroll") for (int k = 0; k < 2; ++k) \
;         acc[ai][bj][m][n] = __builtin_amdgcn_mfma_f32_16x16x32_bf16(Bt[n][k], At[m][k], acc[ai][bj][m][n], 0, 0, 0); __builtin_amdgcn_s_setprio(0); } while (0)
; #define PG8_WAIT_V(n) asm volatile("s_waitcnt vmcnt(" #n ")" ::: "memory")
; #define PG8_WAIT_L(n) asm volatile("s_waitcnt lgkmcnt(" #n ")" ::: "memory")
; #define PG8_BAR __builtin_amdgcn_s_barrier()
; #define PG8_SCHED __builtin_amdgcn_sched_barrier(0)
; template <class Epi>
; DI void gemm_phase(LAS unsigned char* lds, const Gemm g, const StaticOrder& S, const Epi& E) {
;     ...
;             PG8_LDB(B0, 0, 0); PG8_LDB(B1, 0, 1); PG8_SCHED; PG8_LDA(At, 0, 0); PG8_STAGE(PG8_SA(1, 1), a1 + hstepA, voffA);
;             PG8_WAIT_V(8); PG8_WAIT_L(0); PG8_BAR; PG8_MMA(0, 0, At, B0); PG8_MMA(0, 1, At, B1); PG8_BAR; PG8_SCHED;
;             PG8_LDA(At, 0, 1); PG8_STAGE(PG8_SB(0, 0), b2, voffB); PG8_STAGE(PG8_SB(0, 1), b2 + hstepB, voffB); PG8_STAGE(PG8_SA(0, 0), a2, voffA);
;             PG8_WAIT_V(8); PG8_WAIT_L(0); PG8_BAR; PG8_MMA(1, 0, At, B0); PG8_MMA(1, 1, At, B1); PG8_BAR; PG8_SCHED;
	s_waitcnt lgkmcnt(0)
	v_mfma_f32_16x16x32_bf16 v[126:129], v[142:145], v[188:191], v[126:129]
	v_mfma_f32_16x16x32_bf16 v[122:125], v[156:159], v[188:191], v[122:125]
	v_mfma_f32_16x16x32_bf16 v[110:113], v[142:145], v[196:199], v[110:113]
	v_mfma_f32_16x16x32_bf16 v[106:109], v[156:159], v[196:199], v[106:109]
	v_mfma_f32_16x16x32_bf16 v[94:97], v[142:145], v[204:207], v[94:97]
	v_mfma_f32_16x16x32_bf16 v[90:93], v[156:159], v[204:207], v[90:93]
	v_mfma_f32_16x16x32_bf16 v[78:81], v[142:145], v[212:215], v[78:81]
	v_mfma_f32_16x16x32_bf16 v[74:77], v[156:159], v[212:215], v[74:77]
	v_mfma_f32_16x16x32_bf16 v[126:129], v[152:155], v[192:195], v[126:129]
	v_mfma_f32_16x16x32_bf16 v[122:125], v[160:163], v[192:195], v[122:125]
	v_mfma_f32_16x16x32_bf16 v[110:113], v[152:155], v[200:203], v[110:113]
	v_mfma_f32_16x16x32_bf16 v[106:109], v[160:163], v[200:203], v[106:109]
	v_mfma_f32_16x16x32_bf16 v[94:97], v[152:155], v[208:211], v[94:97]
	v_mfma_f32_16x16x32_bf16 v[90:93], v[160:163], v[208:211], v[90:93]
	v_mfma_f32_16x16x32_bf16 v[78:81], v[152:155], v[216:219], v[78:81]
	v_mfma_f32_16x16x32_bf16 v[74:77], v[160:163], v[216:219], v[74:77]
	v_mfma_f32_16x16x32_bf16 v[118:121], v[164:167], v[188:191], v[118:121]
	v_mfma_f32_16x16x32_bf16 v[114:117], v[180:183], v[188:191], v[114:117]
	v_mfma_f32_16x16x32_bf16 v[102:105], v[164:167], v[196:199], v[102:105]
	v_mfma_f32_16x16x32_bf16 v[98:101], v[180:183], v[196:199], v[98:101]
	v_mfma_f32_16x16x32_bf16 v[86:89], v[164:167], v[204:207], v[86:89]
	v_mfma_f32_16x16x32_bf16 v[82:85], v[180:183], v[204:207], v[82:85]
	v_mfma_f32_16x16x32_bf16 v[70:73], v[164:167], v[212:215], v[70:73]
	v_mfma_f32_16x16x32_bf16 v[66:69], v[180:183], v[212:215], v[66:69]
	v_mfma_f32_16x16x32_bf16 v[118:121], v[168:171], v[192:195], v[118:121]
	v_mfma_f32_16x16x32_bf16 v[114:117], v[184:187], v[192:195], v[114:117]
	v_mfma_f32_16x16x32_bf16 v[102:105], v[168:171], v[200:203], v[102:105]
	v_mfma_f32_16x16x32_bf16 v[98:101], v[184:187], v[200:203], v[98:101]
	v_mfma_f32_16x16x32_bf16 v[86:89], v[168:171], v[208:211], v[86:89]
	v_mfma_f32_16x16x32_bf16 v[82:85], v[184:187], v[208:211], v[82:85]
	v_mfma_f32_16x16x32_bf16 v[70:73], v[168:171], v[216:219], v[70:73]
	v_mfma_f32_16x16x32_bf16 v[66:69], v[184:187], v[216:219], v[66:69]
	s_barrier
	s_add_i32 s0, s0, s69
	v_lshl_add_u64 v[146:147], s[74:75], 0, v[134:135]
	s_mov_b32 m0, s0
	ds_read_b128 v[188:191], v151 offset:16384
	ds_read_b128 v[192:195], v151 offset:17408
	ds_read_b128 v[196:199], v151 offset:18432
	ds_read_b128 v[200:203], v151 offset:19456
	ds_read_b128 v[204:207], v151 offset:20480
	ds_read_b128 v[208:211], v151 offset:21504
	ds_read_b128 v[212:215], v151 offset:22528
	ds_read_b128 v[216:219], v151 offset:23552
	global_load_lds_dwordx4 v[146:147], off
	s_add_i32 m0, s0, 0x2000
	s_add_u32 s0, s74, 0x4000
	v_lshl_add_u64 v[146:147], s[74:75], 0, v[130:131]
	s_addc_u32 s1, s75, 0
	s_add_i32 s2, s2, s69
	global_load_lds_dwordx4 v[146:147], off
	v_lshl_add_u64 v[146:147], s[0:1], 0, v[134:135]
	s_mov_b32 m0, s2
	s_nop 0
	global_load_lds_dwordx4 v[146:147], off
	v_lshl_add_u64 v[146:147], s[0:1], 0, v[130:131]
	s_add_i32 m0, s2, 0x2000
	s_nop 0
	global_load_lds_dwordx4 v[146:147], off
	v_lshl_add_u64 v[146:147], s[22:23], 0, v[136:137]
	s_mov_b32 m0, s70
	s_nop 0
	global_load_lds_dwordx4 v[146:147], off
	v_lshl_add_u64 v[146:147], s[22:23], 0, v[132:133]
	s_mov_b32 m0, s71
	s_nop 0
	global_load_lds_dwordx4 v[146:147], off
	s_waitcnt vmcnt(8)
	s_waitcnt lgkmcnt(0)
	s_barrier
	s_waitcnt lgkmcnt(0)
	v_mfma_f32_16x16x32_bf16 v[62:65], v[142:145], v[188:191], v[62:65]
	v_mfma_f32_16x16x32_bf16 v[58:61], v[156:159], v[188:191], v[58:61]
	v_mfma_f32_16x16x32_bf16 v[46:49], v[142:145], v[196:199], v[46:49]
	v_mfma_f32_16x16x32_bf16 v[42:45], v[156:159], v[196:199], v[42:45]
	v_mfma_f32_16x16x32_bf16 v[30:33], v[142:145], v[204:207], v[30:33]
	v_mfma_f32_16x16x32_bf16 v[26:29], v[156:159], v[204:207], v[26:29]
	v_mfma_f32_16x16x32_bf16 v[14:17], v[142:145], v[212:215], v[14:17]
	v_mfma_f32_16x16x32_bf16 v[10:13], v[156:159], v[212:215], v[10:13]
	v_mfma_f32_16x16x32_bf16 v[62:65], v[152:155], v[192:195], v[62:65]
	v_mfma_f32_16x16x32_bf16 v[58:61], v[160:163], v[192:195], v[58:61]
	v_mfma_f32_16x16x32_bf16 v[46:49], v[152:155], v[200:203], v[46:49]
	v_mfma_f32_16x16x32_bf16 v[42:45], v[160:163], v[200:203], v[42:45]
	v_mfma_f32_16x16x32_bf16 v[30:33], v[152:155], v[208:211], v[30:33]
	v_mfma_f32_16x16x32_bf16 v[26:29], v[160:163], v[208:211], v[26:29]
	v_mfma_f32_16x16x32_bf16 v[14:17], v[152:155], v[216:219], v[14:17]
	v_mfma_f32_16x16x32_bf16 v[10:13], v[160:163], v[216:219], v[10:13]
	v_mfma_f32_16x16x32_bf16 v[54:57], v[164:167], v[188:191], v[54:57]
	v_mfma_f32_16x16x32_bf16 v[50:53], v[180:183], v[188:191], v[50:53]
	v_mfma_f32_16x16x32_bf16 v[38:41], v[164:167], v[196:199], v[38:41]
	v_mfma_f32_16x16x32_bf16 v[34:37], v[180:183], v[196:199], v[34:37]
	v_mfma_f32_16x16x32_bf16 v[22:25], v[164:167], v[204:207], v[22:25]
	v_mfma_f32_16x16x32_bf16 v[18:21], v[180:183], v[204:207], v[18:21]
	v_mfma_f32_16x16x32_bf16 v[6:9], v[164:167], v[212:215], v[6:9]
	v_mfma_f32_16x16x32_bf16 v[2:5], v[180:183], v[212:215], v[2:5]
	v_mfma_f32_16x16x32_bf16 v[54:57], v[168:171], v[192:195], v[54:57]
	v_mfma_f32_16x16x32_bf16 v[50:53], v[184:187], v[192:195], v[50:53]
	v_mfma_f32_16x16x32_bf16 v[38:41], v[168:171], v[200:203], v[38:41]
	v_mfma_f32_16x16x32_bf16 v[34:37], v[184:187], v[200:203], v[34:37]
	v_mfma_f32_16x16x32_bf16 v[22:25], v[168:171], v[208:211], v[22:25]
	v_mfma_f32_16x16x32_bf16 v[18:21], v[184:187], v[208:211], v[18:21]
	v_mfma_f32_16x16x32_bf16 v[6:9], v[168:171], v[216:219], v[6:9]
	v_mfma_f32_16x16x32_bf16 v[2:5], v[184:187], v[216:219], v[2:5]
	s_barrier
; #define PG8_STAGE(bufoff, gbase, voff) do { _Pragma("unroll") for (int _i = 0; _i < 2; ++_i) \
;         __builtin_amdgcn_global_load_lds((const unsigned*)((const char*)(gbase) + (voff)[_i]), (LAS unsigned*)(lds + (bufoff) + ldsw + _i * 8192), 16, 0, 0); } while (0)
; #define PG8_LDA(dst, b, h) do { _Pragma("unroll") for (int m = 0; m < 4; ++m) _Pragma("unroll") for (int k = 0; k < 2; ++k) dst[m][k] = *(const LAS bf16x8*)(lds + PG8_SA(b, h) + aoff + m * 2048 + k * 1024); } while (0)
; #define PG8_LDB(dst, b, h) do { _Pragma("unroll") for (int n = 0; n < 2; ++n) _Pragma("unroll") for (int k = 0; k < 2; ++k) dst[n][k] = *(const LAS bf16x8*)(lds + PG8_SB(b, h) + boff + n * 2048 + k * 1024); } while (0)
; #define PG8_MMA(ai, bj, At, Bt) do { __builtin_amdgcn_s_setprio(1); _Pragma("unroll") for (int m = 0; m < 4; ++m) _Pragma("unroll") for (int n = 0; n < 2; ++n) _Pragma("unroll") for (int k = 0; k < 2; ++k) \
;         acc[ai][bj][m][n] = __builtin_amdgcn_mfma_f32_16x16x32_bf16(Bt[n][k], At[m][k], acc[ai][bj][m][n], 0, 0, 0); __builtin_amdgcn_s_setprio(0); } while (0)
; #define PG8_WAIT_V(n) asm volatile("s_waitcnt vmcnt(" #n ")" ::: "memory")
; #define PG8_WAIT_L(n) asm volatile("s_waitcnt lgkmcnt(" #n ")" ::: "memory")
; #define PG8_BAR __builtin_amdgcn_s_barrier()
; #define PG8_SCHED __builtin_amdgcn_sched_barrier(0)
; template <class Epi>
; DI void gemm_phase(LAS unsigned char* lds, const Gemm g, const StaticOrder& S, const Epi& E) {
;     ...
;             PG8_LDB(B0, 1, 0); PG8_LDB(B1, 1, 1); PG8_SCHED; PG8_LDA(At, 1, 0); PG8_STAGE(PG8_SA(0, 1), a2 + hstepA, voffA);
;             PG8_WAIT_V(8); PG8_WAIT_L(0); PG8_BAR; PG8_MMA(0, 0, At, B0); PG8_MMA(0, 1, At, B1); PG8_BAR; PG8_SCHED;
	s_add_i32 s2, 0, 0x18000
	v_add_u32_e32 v146, s2, v150
	s_add_i32 s15, 0, 0x1c000
	ds_read_b128 v[142:145], v146
	ds_read_b128 v[152:155], v146 offset:1024
	ds_read_b128 v[156:159], v146 offset:2048
	ds_read_b128 v[160:163], v146 offset:3072
	v_add_u32_e32 v146, s15, v150
	ds_read_b128 v[164:167], v146
	ds_read_b128 v[168:171], v146 offset:1024
	ds_read_b128 v[180:183], v146 offset:2048
	ds_read_b128 v[184:187], v146 offset:3072
	s_add_u32 s0, s22, 0x4000
	s_addc_u32 s1, s23, 0
	s_mov_b32 m0, s72
	v_lshl_add_u64 v[146:147], s[0:1], 0, v[136:137]
	ds_read_b128 v[188:191], v151 offset:32768
	ds_read_b128 v[192:195], v151 offset:33792
	ds_read_b128 v[196:199], v151 offset:34816
	ds_read_b128 v[200:203], v151 offset:35840
	ds_read_b128 v[204:207], v151 offset:36864
	ds_read_b128 v[208:211], v151 offset:37888
	ds_read_b128 v[212:215], v151 offset:38912
	ds_read_b128 v[216:219], v151 offset:39936
	global_load_lds_dwordx4 v[146:147], off
	v_lshl_add_u64 v[146:147], s[0:1], 0, v[132:133]
	s_mov_b32 m0, s73
	s_nop 0
	global_load_lds_dwordx4 v[146:147], off
	s_waitcnt vmcnt(8)
	s_waitcnt lgkmcnt(0)
	s_barrier
	s_waitcnt lgkmcnt(0)
	v_mfma_f32_16x16x32_bf16 v[126:129], v[142:145], v[188:191], v[126:129]
	v_mfma_f32_16x16x32_bf16 v[122:125], v[156:159], v[188:191], v[122:125]
	v_mfma_f32_16x16x32_bf16 v[110:113], v[142:145], v[196:199], v[110:113]
	v_mfma_f32_16x16x32_bf16 v[106:109], v[156:159], v[196:199], v[106:109]
	v_mfma_f32_16x16x32_bf16 v[94:97], v[142:145], v[204:207], v[94:97]
	v_mfma_f32_16x16x32_bf16 v[90:93], v[156:159], v[204:207], v[90:93]
	v_mfma_f32_16x16x32_bf16 v[78:81], v[142:145], v[212:215], v[78:81]
	v_mfma_f32_16x16x32_bf16 v[74:77], v[156:159], v[212:215], v[74:77]
	v_mfma_f32_16x16x32_bf16 v[126:129], v[152:155], v[192:195], v[126:129]
	v_mfma_f32_16x16x32_bf16 v[122:125], v[160:163], v[192:195], v[122:125]
	v_mfma_f32_16x16x32_bf16 v[110:113], v[152:155], v[200:203], v[110:113]
	v_mfma_f32_16x16x32_bf16 v[106:109], v[160:163], v[200:203], v[106:109]
	v_mfma_f32_16x16x32_bf16 v[94:97], v[152:155], v[208:211], v[94:97]
	v_mfma_f32_16x16x32_bf16 v[90:93], v[160:163], v[208:211], v[90:93]
	v_mfma_f32_16x16x32_bf16 v[78:81], v[152:155], v[216:219], v[78:81]
	v_mfma_f32_16x16x32_bf16 v[74:77], v[160:163], v[216:219], v[74:77]
	v_mfma_f32_16x16x32_bf16 v[118:121], v[164:167], v[188:191], v[118:121]
	v_mfma_f32_16x16x32_bf16 v[114:117], v[180:183], v[188:191], v[114:117]
	v_mfma_f32_16x16x32_bf16 v[102:105], v[164:167], v[196:199], v[102:105]
	v_mfma_f32_16x16x32_bf16 v[98:101], v[180:183], v[196:199], v[98:101]
	v_mfma_f32_16x16x32_bf16 v[86:89], v[164:167], v[204:207], v[86:89]
	v_mfma_f32_16x16x32_bf16 v[82:85], v[180:183], v[204:207], v[82:85]
	v_mfma_f32_16x16x32_bf16 v[70:73], v[164:167], v[212:215], v[70:73]
	v_mfma_f32_16x16x32_bf16 v[66:69], v[180:183], v[212:215], v[66:69]
	v_mfma_f32_16x16x32_bf16 v[118:121], v[168:171], v[192:195], v[118:121]
	v_mfma_f32_16x16x32_bf16 v[114:117], v[184:187], v[192:195], v[114:117]
	v_mfma_f32_16x16x32_bf16 v[102:105], v[168:171], v[200:203], v[102:105]
	v_mfma_f32_16x16x32_bf16 v[98:101], v[184:187], v[200:203], v[98:101]
	v_mfma_f32_16x16x32_bf16 v[86:89], v[168:171], v[208:211], v[86:89]
	v_mfma_f32_16x16x32_bf16 v[82:85], v[184:187], v[208:211], v[82:85]
	v_mfma_f32_16x16x32_bf16 v[70:73], v[168:171], v[216:219], v[70:73]
	v_mfma_f32_16x16x32_bf16 v[66:69], v[184:187], v[216:219], v[66:69]
	s_barrier
; #define PG8_STAGE(bufoff, gbase, voff) do { _Pragma("unroll") for (int _i = 0; _i < 2; ++_i) \
;         __builtin_amdgcn_global_load_lds((const unsigned*)((const char*)(gbase) + (voff)[_i]), (LAS unsigned*)(lds + (bufoff) + ldsw + _i * 8192), 16, 0, 0); } while (0)
; #define PG8_LDA(dst, b, h) do { _Pragma("unroll") for (int m = 0; m < 4; ++m) _Pragma("unroll") for (int k = 0; k < 2; ++k) dst[m][k] = *(const LAS bf16x8*)(lds + PG8_SA(b, h) + aoff + m * 2048 + k * 1024); } while (0)
; #define PG8_MMA(ai, bj, At, Bt) do { __builtin_amdgcn_s_setprio(1); _Pragma("unroll") for (int m = 0; m < 4; ++m) _Pragma("unroll") for (int n = 0; n < 2; ++n) _Pragma("unroll") for (int k = 0; k < 2; ++k) \
;         acc[ai][bj][m][n] = __builtin_amdgcn_mfma_f32_16x16x32_bf16(Bt[n][k], At[m][k], acc[ai][bj][m][n], 0, 0, 0); __builtin_amdgcn_s_setprio(0); } while (0)
; #define PG8_WAIT_V(n) asm volatile("s_waitcnt vmcnt(" #n ")" ::: "memory")
; #define PG8_WAIT_L(n) asm volatile("s_waitcnt lgkmcnt(" #n ")" ::: "memory")
; #define PG8_BAR __builtin_amdgcn_s_barrier()
; #define PG8_SCHED __builtin_amdgcn_sched_barrier(0)
; template <class Epi>
; DI void gemm_phase(LAS unsigned char* lds, const Gemm g, const StaticOrder& S, const Epi& E) {
;     ...
;             PG8_LDA(At, 1, 1); PG8_STAGE(PG8_SB(1, 0), b3, voffB); PG8_STAGE(PG8_SB(1, 1), b3 + hstepB, voffB); PG8_STAGE(PG8_SA(1, 0), a3, voffA);
;             PG8_WAIT_V(8); PG8_WAIT_L(0); PG8_BAR; PG8_MMA(1, 0, At, B0); PG8_MMA(1, 1, At, B1); PG8_BAR; PG8_SCHED;
;         }
;         if (wr == 0) PG8_BAR;
	s_add_u32 s0, s74, 0x20000
	s_addc_u32 s1, s75, 0
	s_add_i32 s2, s2, s69
	v_lshl_add_u64 v[146:147], s[0:1], 0, v[134:135]
	s_mov_b32 m0, s2
	ds_read_b128 v[188:191], v151 offset:49152
	ds_read_b128 v[192:195], v151 offset:50176
	ds_read_b128 v[196:199], v151 offset:51200
	ds_read_b128 v[200:203], v151 offset:52224
	ds_read_b128 v[204:207], v151 offset:53248
	ds_read_b128 v[208:211], v151 offset:54272
	ds_read_b128 v[212:215], v151 offset:55296
	ds_read_b128 v[216:219], v151 offset:56320
	global_load_lds_dwordx4 v[146:147], off
	s_add_i32 m0, s2, 0x2000
	v_lshl_add_u64 v[146:147], s[0:1], 0, v[130:131]
	s_add_u32 s0, s74, 0x24000
	s_addc_u32 s1, s75, 0
	s_add_i32 s2, s15, s69
	global_load_lds_dwordx4 v[146:147], off
	v_lshl_add_u64 v[146:147], s[0:1], 0, v[134:135]
	s_mov_b32 m0, s2
	s_nop 0
	global_load_lds_dwordx4 v[146:147], off
	v_lshl_add_u64 v[146:147], s[0:1], 0, v[130:131]
	s_add_i32 m0, s2, 0x2000
	s_nop 0
	global_load_lds_dwordx4 v[146:147], off
	v_lshl_add_u64 v[146:147], s[18:19], 0, v[136:137]
	s_mov_b32 m0, s84
	s_nop 0
	global_load_lds_dwordx4 v[146:147], off
	v_lshl_add_u64 v[146:147], s[18:19], 0, v[132:133]
	s_mov_b32 m0, s85
	s_nop 0
	global_load_lds_dwordx4 v[146:147], off
	s_waitcnt vmcnt(8)
	s_waitcnt lgkmcnt(0)
	s_barrier
	s_waitcnt lgkmcnt(0)
	v_mfma_f32_16x16x32_bf16 v[62:65], v[142:145], v[188:191], v[62:65]
	v_mfma_f32_16x16x32_bf16 v[58:61], v[156:159], v[188:191], v[58:61]
	v_mfma_f32_16x16x32_bf16 v[46:49], v[142:145], v[196:199], v[46:49]
	v_mfma_f32_16x16x32_bf16 v[42:45], v[156:159], v[196:199], v[42:45]
	v_mfma_f32_16x16x32_bf16 v[30:33], v[142:145], v[204:207], v[30:33]
	v_mfma_f32_16x16x32_bf16 v[26:29], v[156:159], v[204:207], v[26:29]
	v_mfma_f32_16x16x32_bf16 v[14:17], v[142:145], v[212:215], v[14:17]
	v_mfma_f32_16x16x32_bf16 v[10:13], v[156:159], v[212:215], v[10:13]
	v_mfma_f32_16x16x32_bf16 v[62:65], v[152:155], v[192:195], v[62:65]
	v_mfma_f32_16x16x32_bf16 v[58:61], v[160:163], v[192:195], v[58:61]
	v_mfma_f32_16x16x32_bf16 v[46:49], v[152:155], v[200:203], v[46:49]
	v_mfma_f32_16x16x32_bf16 v[42:45], v[160:163], v[200:203], v[42:45]
	v_mfma_f32_16x16x32_bf16 v[30:33], v[152:155], v[208:211], v[30:33]
	v_mfma_f32_16x16x32_bf16 v[26:29], v[160:163], v[208:211], v[26:29]
	v_mfma_f32_16x16x32_bf16 v[14:17], v[152:155], v[216:219], v[14:17]
	v_mfma_f32_16x16x32_bf16 v[10:13], v[160:163], v[216:219], v[10:13]
	v_mfma_f32_16x16x32_bf16 v[54:57], v[164:167], v[188:191], v[54:57]
	v_mfma_f32_16x16x32_bf16 v[50:53], v[180:183], v[188:191], v[50:53]
	v_mfma_f32_16x16x32_bf16 v[38:41], v[164:167], v[196:199], v[38:41]
	v_mfma_f32_16x16x32_bf16 v[34:37], v[180:183], v[196:199], v[34:37]
	v_mfma_f32_16x16x32_bf16 v[22:25], v[164:167], v[204:207], v[22:25]
	v_mfma_f32_16x16x32_bf16 v[18:21], v[180:183], v[204:207], v[18:21]
	v_mfma_f32_16x16x32_bf16 v[6:9], v[164:167], v[212:215], v[6:9]
	v_mfma_f32_16x16x32_bf16 v[2:5], v[180:183], v[212:215], v[2:5]
	v_mfma_f32_16x16x32_bf16 v[54:57], v[168:171], v[192:195], v[54:57]
	v_mfma_f32_16x16x32_bf16 v[50:53], v[184:187], v[192:195], v[50:53]
	v_mfma_f32_16x16x32_bf16 v[38:41], v[168:171], v[200:203], v[38:41]
	v_mfma_f32_16x16x32_bf16 v[34:37], v[184:187], v[200:203], v[34:37]
	v_mfma_f32_16x16x32_bf16 v[22:25], v[168:171], v[208:211], v[22:25]
	v_mfma_f32_16x16x32_bf16 v[18:21], v[184:187], v[208:211], v[18:21]
	v_mfma_f32_16x16x32_bf16 v[6:9], v[168:171], v[216:219], v[6:9]
	v_mfma_f32_16x16x32_bf16 v[2:5], v[184:187], v[216:219], v[2:5]
	s_barrier
	s_add_i32 s95, s95, 2
	s_add_u32 s93, s93, 0x40000
	s_addc_u32 s94, s94, 0
	s_add_u32 s50, s50, 0x410000
	s_addc_u32 s51, s51, 0
	s_cmp_gt_u32 s95, 41
	s_cbranch_scc0 .LBB0_275
	s_setprio 0
	s_and_b64 vcc, exec, s[38:39]
	v_readlane_b32 s94, v255, 12
	v_readlane_b32 s95, v255, 13
	s_cbranch_vccz .LBB0_278
	s_barrier

; #define PG8_STAGE(bufoff, gbase, voff) do { _Pragma("unroll") for (int _i = 0; _i < 2; ++_i) \
;         __builtin_amdgcn_global_load_lds((const unsigned*)((const char*)(gbase) + (voff)[_i]), (LAS unsigned*)(lds + (bufoff) + ldsw + _i * 8192), 16, 0, 0); } while (0)
; #define PG8_LDA(dst, b, h) do { _Pragma("unroll") for (int m = 0; m < 4; ++m) _Pragma("unroll") for (int k = 0; k < 2; ++k) dst[m][k] = *(const LAS bf16x8*)(lds + PG8_SA(b, h) + aoff + m * 2048 + k * 1024); } while (0)
; #define PG8_LDB(dst, b, h) do { _Pragma("unroll") for (int n = 0; n < 2; ++n) _Pragma("unroll") for (int k = 0; k < 2; ++k) dst[n][k] = *(const LAS bf16x8*)(lds + PG8_SB(b, h) + boff + n * 2048 + k * 1024); } while (0)
; #define PG8_MMA(ai, bj, At, Bt) do { __builtin_amdgcn_s_setprio(1); _Pragma("unroll") for (int m = 0; m < 4; ++m) _Pragma("unroll") for (int n = 0; n < 2; ++n) _Pragma("unroll") for (int k = 0; k < 2; ++k) \
;         acc[ai][bj][m][n] = __builtin_amdgcn_mfma_f32_16x16x32_bf16(Bt[n][k], At[m][k], acc[ai][bj][m][n], 0, 0, 0); __builtin_amdgcn_s_setprio(0); } while (0)
; #define PG8_BAR __builtin_amdgcn_s_barrier()
; template <class Epi>
; DI void gemm_phase(LAS unsigned char* lds, const Gemm g, const StaticOrder& S, const Epi& E) {
;     ...
;         const bool has_next = S.next(ui + 1, nxt);
;         const char* nA = has_next ? (const char*)g.A + (size_t)nxt.pm * tstepA + (size_t)nxt.pn * g.a_pn_off * 2 : cA; const char* nB = has_next ? (const char*)g.Bt + (size_t)nxt.pn * tstepB : cB;
;         for (int t = 0; t < nt; t += 2) {
;             const bool last = (t == nt - 2);
;             const char* a1 = cA + (size_t)(t + 1) * kstepA;
;             const char* a2 = last ? nA : cA + (size_t)(t + 2) * kstepA; const char* b2 = last ? nB : cB + (size_t)(t + 2) * kstepB;
;             const char* a3 = a2 + kstepA; const char* b3 = b2 + kstepB;
;             PG8_LDB(B0, 0, 0); PG8_LDB(B1, 0, 1); PG8_SCHED; PG8_LDA(At, 0, 0); PG8_STAGE(PG8_SA(1, 1), a1 + hstepA, voffA);
;             PG8_WAIT_V(8); PG8_WAIT_L(0); PG8_BAR; PG8_MMA(0, 0, At, B0); PG8_MMA(0, 1, At, B1); PG8_BAR; PG8_SCHED;
;     ...
; #pragma unroll
;         for (int a = 0; a < 2; ++a)
; #pragma unroll
;             for (int b = 0; b < 2; ++b)
; #pragma unroll
;                 for (int m = 0; m < 4; ++m)
; #pragma unroll
;                     for (int n = 0; n < 2; ++n) acc[a][b][m][n] = (f32x4){0.f, 0.f, 0.f, 0.f};
.LBB0_404:
	s_ashr_i32 s85, s84, 31
	s_lshl_b64 s[22:23], s[84:85], 19
	v_readlane_b32 s38, v255, 32
	v_readlane_b32 s39, v255, 33
	s_add_u32 s74, s38, s22
	s_addc_u32 s75, s39, s23
	s_and_b64 s[22:23], s[42:43], exec
	s_cselect_b32 s45, s75, s19
	s_cselect_b32 s47, s74, s18
	s_ashr_i32 s95, s94, 31
	s_lshl_b64 s[22:23], s[94:95], 19
	s_add_u32 s38, s41, s22
	s_addc_u32 s39, s69, s23
	s_and_b64 s[22:23], s[42:43], exec
	s_cselect_b32 s66, s39, s1
	s_cselect_b32 s85, s38, s0
	s_add_u32 s95, s0, 0x100
	s_addc_u32 vcc_lo, s1, 0
	s_add_u32 s0, s18, 0x40080
	v_mov_b32_e32 v2, 0
	s_addc_u32 s1, s19, 0
	s_mov_b32 vcc_hi, -2
	v_mov_b32_e32 v3, v2
	v_mov_b32_e32 v4, v2
	v_mov_b32_e32 v5, v2
	v_mov_b32_e32 v6, v2
	v_mov_b32_e32 v7, v2
	v_mov_b32_e32 v8, v2
	v_mov_b32_e32 v9, v2
	v_mov_b32_e32 v18, v2
	v_mov_b32_e32 v19, v2
	v_mov_b32_e32 v20, v2
	v_mov_b32_e32 v21, v2
	v_mov_b32_e32 v22, v2
	v_mov_b32_e32 v23, v2
	v_mov_b32_e32 v24, v2
	v_mov_b32_e32 v25, v2
	v_mov_b32_e32 v50, v2
	v_mov_b32_e32 v51, v2
	v_mov_b32_e32 v52, v2
	v_mov_b32_e32 v53, v2
	v_mov_b32_e32 v54, v2
	v_mov_b32_e32 v55, v2
	v_mov_b32_e32 v56, v2
	v_mov_b32_e32 v57, v2
	v_mov_b32_e32 v66, v2
	v_mov_b32_e32 v67, v2
	v_mov_b32_e32 v68, v2
	v_mov_b32_e32 v69, v2
	v_mov_b32_e32 v70, v2
	v_mov_b32_e32 v71, v2
	v_mov_b32_e32 v72, v2
	v_mov_b32_e32 v73, v2
	v_mov_b32_e32 v10, v2
	v_mov_b32_e32 v11, v2
	v_mov_b32_e32 v12, v2
	v_mov_b32_e32 v13, v2
	v_mov_b32_e32 v14, v2
	v_mov_b32_e32 v15, v2
	v_mov_b32_e32 v16, v2
	v_mov_b32_e32 v17, v2
	v_mov_b32_e32 v26, v2
	v_mov_b32_e32 v27, v2
	v_mov_b32_e32 v28, v2
	v_mov_b32_e32 v29, v2
	v_mov_b32_e32 v30, v2
	v_mov_b32_e32 v31, v2
	v_mov_b32_e32 v32, v2
	v_mov_b32_e32 v33, v2
	v_mov_b32_e32 v58, v2
	v_mov_b32_e32 v59, v2
	v_mov_b32_e32 v60, v2
	v_mov_b32_e32 v61, v2
	v_mov_b32_e32 v62, v2
	v_mov_b32_e32 v63, v2
	v_mov_b32_e32 v64, v2
	v_mov_b32_e32 v65, v2
	v_mov_b32_e32 v74, v2
	v_mov_b32_e32 v75, v2
	v_mov_b32_e32 v76, v2
	v_mov_b32_e32 v77, v2
	v_mov_b32_e32 v78, v2
	v_mov_b32_e32 v79, v2
	v_mov_b32_e32 v80, v2
	v_mov_b32_e32 v81, v2
	v_mov_b32_e32 v82, v2
	v_mov_b32_e32 v83, v2
	v_mov_b32_e32 v84, v2
	v_mov_b32_e32 v85, v2
	v_mov_b32_e32 v86, v2
	v_mov_b32_e32 v87, v2
	v_mov_b32_e32 v88, v2
	v_mov_b32_e32 v89, v2
	v_mov_b32_e32 v98, v2
	v_mov_b32_e32 v99, v2
	v_mov_b32_e32 v100, v2
	v_mov_b32_e32 v101, v2
	v_mov_b32_e32 v102, v2
	v_mov_b32_e32 v103, v2
	v_mov_b32_e32 v104, v2
	v_mov_b32_e32 v105, v2
	v_mov_b32_e32 v114, v2
	v_mov_b32_e32 v115, v2
	v_mov_b32_e32 v116, v2
	v_mov_b32_e32 v117, v2
	v_mov_b32_e32 v118, v2
	v_mov_b32_e32 v119, v2
	v_mov_b32_e32 v120, v2
	v_mov_b32_e32 v121, v2
	v_mov_b32_e32 v130, v2
	v_mov_b32_e32 v131, v2
	v_mov_b32_e32 v132, v2
	v_mov_b32_e32 v133, v2
	v_mov_b32_e32 v134, v2
	v_mov_b32_e32 v135, v2
	v_mov_b32_e32 v136, v2
	v_mov_b32_e32 v137, v2
	v_mov_b32_e32 v90, v2
	v_mov_b32_e32 v91, v2
	v_mov_b32_e32 v92, v2
	v_mov_b32_e32 v93, v2
	v_mov_b32_e32 v94, v2
	v_mov_b32_e32 v95, v2
	v_mov_b32_e32 v96, v2
	v_mov_b32_e32 v97, v2
	v_mov_b32_e32 v106, v2
	v_mov_b32_e32 v107, v2
	v_mov_b32_e32 v108, v2
	v_mov_b32_e32 v109, v2
	v_mov_b32_e32 v110, v2
	v_mov_b32_e32 v111, v2
	v_mov_b32_e32 v112, v2
	v_mov_b32_e32 v113, v2
	v_mov_b32_e32 v122, v2
	v_mov_b32_e32 v123, v2
	v_mov_b32_e32 v124, v2
	v_mov_b32_e32 v125, v2
	v_mov_b32_e32 v126, v2
	v_mov_b32_e32 v127, v2
	v_mov_b32_e32 v128, v2
	v_mov_b32_e32 v129, v2
	v_mov_b32_e32 v138, v2
	v_mov_b32_e32 v139, v2
	v_mov_b32_e32 v140, v2
	v_mov_b32_e32 v141, v2
	v_mov_b32_e32 v142, v2
	v_mov_b32_e32 v143, v2
	v_mov_b32_e32 v144, v2
	v_mov_b32_e32 v145, v2
	v_readfirstlane_b32 s2, v220
	s_lshr_b32 s2, s2, 8
	s_cmp_eq_u32 s2, 0
	s_cbranch_scc1 .Lsprio_2
	s_setprio 1
.Lsprio_2:
.LBB0_405:
	s_add_u32 s2, s0, 0xfffc0080
	s_addc_u32 s15, s1, -1
	s_add_i32 s25, 0, 0x10000
	s_cmp_eq_u32 vcc_hi, 12
	s_cselect_b32 s23, s45, s15
	s_cselect_b32 s22, s47, s2
	s_cselect_b32 s19, s66, vcc_lo
	s_cselect_b32 s18, s85, s95
	s_add_i32 s2, 0, 0x14000
	s_waitcnt vmcnt(0) lgkmcnt(0)
	v_add_u32_e32 v46, s25, v193
	v_add_u32_e32 v170, s2, v193
	ds_read_b128 v[34:37], v46
	ds_read_b128 v[38:41], v46 offset:1024
	ds_read_b128 v[42:45], v46 offset:2048
	ds_read_b128 v[46:49], v46 offset:3072
	ds_read_b128 v[158:161], v170
	ds_read_b128 v[162:165], v170 offset:1024
	ds_read_b128 v[166:169], v170 offset:2048
	ds_read_b128 v[180:183], v170 offset:3072
	v_lshl_add_u64 v[170:171], s[0:1], 0, v[156:157]
	s_add_i32 m0, s71, 0xc000
	ds_read_b128 v[184:187], v194
	ds_read_b128 v[188:191], v194 offset:1024
	ds_read_b128 v[196:199], v194 offset:2048
	ds_read_b128 v[200:203], v194 offset:3072
	ds_read_b128 v[204:207], v194 offset:4096
	ds_read_b128 v[208:211], v194 offset:5120
	ds_read_b128 v[212:215], v194 offset:6144
	ds_read_b128 v[216:219], v194 offset:7168
	global_load_lds_dwordx4 v[170:171], off
	v_lshl_add_u64 v[170:171], s[0:1], 0, v[154:155]
	s_add_i32 m0, s71, 0xe000
	s_nop 0
	global_load_lds_dwordx4 v[170:171], off
	s_waitcnt vmcnt(8)
	s_waitcnt lgkmcnt(0)
	s_barrier
; #define PG8_STAGE(bufoff, gbase, voff) do { _Pragma("unroll") for (int _i = 0; _i < 2; ++_i) \
;         __builtin_amdgcn_global_load_lds((const unsigned*)((const char*)(gbase) + (voff)[_i]), (LAS unsigned*)(lds + (bufoff) + ldsw + _i * 8192), 16, 0, 0); } while (0)
; #define PG8_LDA(dst, b, h) do { _Pragma("unroll") for (int m = 0; m < 4; ++m) _Pragma("unroll") for (int k = 0; k < 2; ++k) dst[m][k] = *(const LAS bf16x8*)(lds + PG8_SA(b, h) + aoff + m * 2048 + k * 1024); } while (0)
; #define PG8_LDB(dst, b, h) do { _Pragma("unroll") for (int n = 0; n < 2; ++n) _Pragma("unroll") for (int k = 0; k < 2; ++k) dst[n][k] = *(const LAS bf16x8*)(lds + PG8_SB(b, h) + boff + n * 2048 + k * 1024); } while (0)
; #define PG8_MMA(ai, bj, At, Bt) do { __builtin_amdgcn_s_setprio(1); _Pragma("unroll") for (int m = 0; m < 4; ++m) _Pragma("unroll") for (int n = 0; n < 2; ++n) _Pragma("unroll") for (int k = 0; k < 2; ++k) \
;         acc[ai][bj][m][n] = __builtin_amdgcn_mfma_f32_16x16x32_bf16(Bt[n][k], At[m][k], acc[ai][bj][m][n], 0, 0, 0); __builtin_amdgcn_s_setprio(0); } while (0)
; #define PG8_WAIT_V(n) asm volatile("s_waitcnt vmcnt(" #n ")" ::: "memory")
; #define PG8_WAIT_L(n) asm volatile("s_waitcnt lgkmcnt(" #n ")" ::: "memory")
; #define PG8_BAR __builtin_amdgcn_s_barrier()
; #define PG8_SCHED __builtin_amdgcn_sched_barrier(0)
; template <class Epi>
; DI void gemm_phase(LAS unsigned char* lds, const Gemm g, const StaticOrder& S, const Epi& E) {
;     ...
;             PG8_LDB(B0, 0, 0); PG8_LDB(B1, 0, 1); PG8_SCHED; PG8_LDA(At, 0, 0); PG8_STAGE(PG8_SA(1, 1), a1 + hstepA, voffA);
;             PG8_WAIT_V(8); PG8_WAIT_L(0); PG8_BAR; PG8_MMA(0, 0, At, B0); PG8_MMA(0, 1, At, B1); PG8_BAR; PG8_SCHED;
;             PG8_LDA(At, 0, 1); PG8_STAGE(PG8_SB(0, 0), b2, voffB); PG8_STAGE(PG8_SB(0, 1), b2 + hstepB, voffB); PG8_STAGE(PG8_SA(0, 0), a2, voffA);
;             PG8_WAIT_V(8); PG8_WAIT_L(0); PG8_BAR; PG8_MMA(1, 0, At, B0); PG8_MMA(1, 1, At, B1); PG8_BAR; PG8_SCHED;
	s_waitcnt lgkmcnt(0)
	v_mfma_f32_16x16x32_bf16 v[142:145], v[34:37], v[184:187], v[142:145]
	v_mfma_f32_16x16x32_bf16 v[138:141], v[42:45], v[184:187], v[138:141]
	v_mfma_f32_16x16x32_bf16 v[126:129], v[34:37], v[196:199], v[126:129]
	v_mfma_f32_16x16x32_bf16 v[122:125], v[42:45], v[196:199], v[122:125]
	v_mfma_f32_16x16x32_bf16 v[110:113], v[34:37], v[204:207], v[110:113]
	v_mfma_f32_16x16x32_bf16 v[106:109], v[42:45], v[204:207], v[106:109]
	v_mfma_f32_16x16x32_bf16 v[94:97], v[34:37], v[212:215], v[94:97]
	v_mfma_f32_16x16x32_bf16 v[90:93], v[42:45], v[212:215], v[90:93]
	v_mfma_f32_16x16x32_bf16 v[142:145], v[38:41], v[188:191], v[142:145]
	v_mfma_f32_16x16x32_bf16 v[138:141], v[46:49], v[188:191], v[138:141]
	v_mfma_f32_16x16x32_bf16 v[126:129], v[38:41], v[200:203], v[126:129]
	v_mfma_f32_16x16x32_bf16 v[122:125], v[46:49], v[200:203], v[122:125]
	v_mfma_f32_16x16x32_bf16 v[110:113], v[38:41], v[208:211], v[110:113]
	v_mfma_f32_16x16x32_bf16 v[106:109], v[46:49], v[208:211], v[106:109]
	v_mfma_f32_16x16x32_bf16 v[94:97], v[38:41], v[216:219], v[94:97]
	v_mfma_f32_16x16x32_bf16 v[90:93], v[46:49], v[216:219], v[90:93]
	v_mfma_f32_16x16x32_bf16 v[134:137], v[158:161], v[184:187], v[134:137]
	v_mfma_f32_16x16x32_bf16 v[130:133], v[166:169], v[184:187], v[130:133]
	v_mfma_f32_16x16x32_bf16 v[118:121], v[158:161], v[196:199], v[118:121]
	v_mfma_f32_16x16x32_bf16 v[114:117], v[166:169], v[196:199], v[114:117]
	v_mfma_f32_16x16x32_bf16 v[102:105], v[158:161], v[204:207], v[102:105]
	v_mfma_f32_16x16x32_bf16 v[98:101], v[166:169], v[204:207], v[98:101]
	v_mfma_f32_16x16x32_bf16 v[86:89], v[158:161], v[212:215], v[86:89]
	v_mfma_f32_16x16x32_bf16 v[82:85], v[166:169], v[212:215], v[82:85]
	v_mfma_f32_16x16x32_bf16 v[134:137], v[162:165], v[188:191], v[134:137]
	v_mfma_f32_16x16x32_bf16 v[130:133], v[180:183], v[188:191], v[130:133]
	v_mfma_f32_16x16x32_bf16 v[118:121], v[162:165], v[200:203], v[118:121]
	v_mfma_f32_16x16x32_bf16 v[114:117], v[180:183], v[200:203], v[114:117]
	v_mfma_f32_16x16x32_bf16 v[102:105], v[162:165], v[208:211], v[102:105]
	v_mfma_f32_16x16x32_bf16 v[98:101], v[180:183], v[208:211], v[98:101]
	v_mfma_f32_16x16x32_bf16 v[86:89], v[162:165], v[216:219], v[86:89]
	v_mfma_f32_16x16x32_bf16 v[82:85], v[180:183], v[216:219], v[82:85]
	s_barrier
	s_add_i32 s15, s25, s70
	v_lshl_add_u64 v[170:171], s[18:19], 0, v[148:149]
	s_mov_b32 m0, s15
	ds_read_b128 v[184:187], v194 offset:16384
	ds_read_b128 v[188:191], v194 offset:17408
	ds_read_b128 v[196:199], v194 offset:18432
	ds_read_b128 v[200:203], v194 offset:19456
	ds_read_b128 v[204:207], v194 offset:20480
	ds_read_b128 v[208:211], v194 offset:21504
	ds_read_b128 v[212:215], v194 offset:22528
	ds_read_b128 v[216:219], v194 offset:23552
	global_load_lds_dwordx4 v[170:171], off
	s_add_i32 m0, s15, 0x2000
	s_add_u32 s48, s18, 0x40000
	v_lshl_add_u64 v[238:239], s[18:19], 0, v[152:153]
	s_addc_u32 s49, s19, 0
	s_add_i32 s2, s2, s70
	global_load_lds_dwordx4 v[238:239], off
	v_lshl_add_u64 v[240:241], s[48:49], 0, v[148:149]
	s_mov_b32 m0, s2
	v_lshl_add_u64 v[242:243], s[22:23], 0, v[150:151]
	global_load_lds_dwordx4 v[240:241], off
	v_lshl_add_u64 v[240:241], s[48:49], 0, v[152:153]
	s_add_i32 m0, s2, 0x2000
	s_nop 0
	global_load_lds_dwordx4 v[240:241], off
	v_lshl_add_u64 v[240:241], s[22:23], 0, v[146:147]
	s_mov_b32 m0, s71
	s_nop 0
	global_load_lds_dwordx4 v[240:241], off
	s_mov_b32 m0, s72
	s_nop 0
	global_load_lds_dwordx4 v[242:243], off
	s_waitcnt vmcnt(8)
	s_waitcnt lgkmcnt(0)
	s_barrier
	s_waitcnt lgkmcnt(0)
	v_mfma_f32_16x16x32_bf16 v[78:81], v[34:37], v[184:187], v[78:81]
	v_mfma_f32_16x16x32_bf16 v[74:77], v[42:45], v[184:187], v[74:77]
	v_mfma_f32_16x16x32_bf16 v[62:65], v[34:37], v[196:199], v[62:65]
	v_mfma_f32_16x16x32_bf16 v[58:61], v[42:45], v[196:199], v[58:61]
	v_mfma_f32_16x16x32_bf16 v[30:33], v[34:37], v[204:207], v[30:33]
	v_mfma_f32_16x16x32_bf16 v[26:29], v[42:45], v[204:207], v[26:29]
	v_mfma_f32_16x16x32_bf16 v[14:17], v[34:37], v[212:215], v[14:17]
	v_mfma_f32_16x16x32_bf16 v[10:13], v[42:45], v[212:215], v[10:13]
	v_mfma_f32_16x16x32_bf16 v[78:81], v[38:41], v[188:191], v[78:81]
	v_mfma_f32_16x16x32_bf16 v[74:77], v[46:49], v[188:191], v[74:77]
	v_mfma_f32_16x16x32_bf16 v[62:65], v[38:41], v[200:203], v[62:65]
	v_mfma_f32_16x16x32_bf16 v[58:61], v[46:49], v[200:203], v[58:61]
	v_mfma_f32_16x16x32_bf16 v[30:33], v[38:41], v[208:211], v[30:33]
	v_mfma_f32_16x16x32_bf16 v[26:29], v[46:49], v[208:211], v[26:29]
	v_mfma_f32_16x16x32_bf16 v[14:17], v[38:41], v[216:219], v[14:17]
	v_mfma_f32_16x16x32_bf16 v[10:13], v[46:49], v[216:219], v[10:13]
	v_mfma_f32_16x16x32_bf16 v[22:25], v[158:161], v[204:207], v[22:25]
	v_mfma_f32_16x16x32_bf16 v[18:21], v[166:169], v[204:207], v[18:21]
	v_mfma_f32_16x16x32_bf16 v[6:9], v[158:161], v[212:215], v[6:9]
	v_mfma_f32_16x16x32_bf16 v[2:5], v[166:169], v[212:215], v[2:5]
	v_mfma_f32_16x16x32_bf16 v[34:37], v[158:161], v[184:187], v[70:73]
	v_mfma_f32_16x16x32_bf16 v[38:41], v[166:169], v[184:187], v[66:69]
	v_mfma_f32_16x16x32_bf16 v[42:45], v[158:161], v[196:199], v[54:57]
	v_mfma_f32_16x16x32_bf16 v[46:49], v[166:169], v[196:199], v[50:53]
	v_mfma_f32_16x16x32_bf16 v[22:25], v[162:165], v[208:211], v[22:25]
	v_mfma_f32_16x16x32_bf16 v[18:21], v[180:183], v[208:211], v[18:21]
	v_mfma_f32_16x16x32_bf16 v[6:9], v[162:165], v[216:219], v[6:9]
	v_mfma_f32_16x16x32_bf16 v[2:5], v[180:183], v[216:219], v[2:5]
	v_mfma_f32_16x16x32_bf16 v[34:37], v[162:165], v[188:191], v[34:37]
	v_mfma_f32_16x16x32_bf16 v[38:41], v[180:183], v[188:191], v[38:41]
	v_mfma_f32_16x16x32_bf16 v[42:45], v[162:165], v[200:203], v[42:45]
	v_mfma_f32_16x16x32_bf16 v[46:49], v[180:183], v[200:203], v[46:49]
	s_barrier
; #define PG8_STAGE(bufoff, gbase, voff) do { _Pragma("unroll") for (int _i = 0; _i < 2; ++_i) \
;         __builtin_amdgcn_global_load_lds((const unsigned*)((const char*)(gbase) + (voff)[_i]), (LAS unsigned*)(lds + (bufoff) + ldsw + _i * 8192), 16, 0, 0); } while (0)
; #define PG8_LDA(dst, b, h) do { _Pragma("unroll") for (int m = 0; m < 4; ++m) _Pragma("unroll") for (int k = 0; k < 2; ++k) dst[m][k] = *(const LAS bf16x8*)(lds + PG8_SA(b, h) + aoff + m * 2048 + k * 1024); } while (0)
; #define PG8_LDB(dst, b, h) do { _Pragma("unroll") for (int n = 0; n < 2; ++n) _Pragma("unroll") for (int k = 0; k < 2; ++k) dst[n][k] = *(const LAS bf16x8*)(lds + PG8_SB(b, h) + boff + n * 2048 + k * 1024); } while (0)
; #define PG8_MMA(ai, bj, At, Bt) do { __builtin_amdgcn_s_setprio(1); _Pragma("unroll") for (int m = 0; m < 4; ++m) _Pragma("unroll") for (int n = 0; n < 2; ++n) _Pragma("unroll") for (int k = 0; k < 2; ++k) \
;         acc[ai][bj][m][n] = __builtin_amdgcn_mfma_f32_16x16x32_bf16(Bt[n][k], At[m][k], acc[ai][bj][m][n], 0, 0, 0); __builtin_amdgcn_s_setprio(0); } while (0)
; #define PG8_WAIT_V(n) asm volatile("s_waitcnt vmcnt(" #n ")" ::: "memory")
; #define PG8_WAIT_L(n) asm volatile("s_waitcnt lgkmcnt(" #n ")" ::: "memory")
; #define PG8_BAR __builtin_amdgcn_s_barrier()
; #define PG8_SCHED __builtin_amdgcn_sched_barrier(0)
; template <class Epi>
; DI void gemm_phase(LAS unsigned char* lds, const Gemm g, const StaticOrder& S, const Epi& E) {
;     ...
;             PG8_LDB(B0, 1, 0); PG8_LDB(B1, 1, 1); PG8_SCHED; PG8_LDA(At, 1, 0); PG8_STAGE(PG8_SA(0, 1), a2 + hstepA, voffA);
;             PG8_WAIT_V(8); PG8_WAIT_L(0); PG8_BAR; PG8_MMA(0, 0, At, B0); PG8_MMA(0, 1, At, B1); PG8_BAR; PG8_SCHED;
	s_add_i32 s2, 0, 0x18000
	s_add_i32 s15, 0, 0x1c000
	v_add_u32_e32 v70, s2, v193
	v_add_u32_e32 v180, s15, v193
	ds_read_b128 v[50:53], v70
	ds_read_b128 v[54:57], v70 offset:1024
	ds_read_b128 v[66:69], v70 offset:2048
	ds_read_b128 v[70:73], v70 offset:3072
	ds_read_b128 v[158:161], v180
	ds_read_b128 v[162:165], v180 offset:1024
	ds_read_b128 v[166:169], v180 offset:2048
	ds_read_b128 v[180:183], v180 offset:3072
	s_add_u32 s22, s22, 0x40000
	s_addc_u32 s23, s23, 0
	s_mov_b32 m0, s73
	v_lshl_add_u64 v[244:245], s[22:23], 0, v[146:147]
	ds_read_b128 v[184:187], v194 offset:32768
	ds_read_b128 v[188:191], v194 offset:33792
	ds_read_b128 v[196:199], v194 offset:34816
	ds_read_b128 v[200:203], v194 offset:35840
	ds_read_b128 v[204:207], v194 offset:36864
	ds_read_b128 v[208:211], v194 offset:37888
	ds_read_b128 v[212:215], v194 offset:38912
	ds_read_b128 v[216:219], v194 offset:39936
	global_load_lds_dwordx4 v[244:245], off
	v_lshl_add_u64 v[244:245], s[22:23], 0, v[150:151]
	s_mov_b32 m0, s20
	s_nop 0
	global_load_lds_dwordx4 v[244:245], off
	s_waitcnt vmcnt(8)
	s_waitcnt lgkmcnt(0)
	s_barrier
	s_waitcnt lgkmcnt(0)
	v_mfma_f32_16x16x32_bf16 v[142:145], v[50:53], v[184:187], v[142:145]
	v_mfma_f32_16x16x32_bf16 v[138:141], v[66:69], v[184:187], v[138:141]
	v_mfma_f32_16x16x32_bf16 v[126:129], v[50:53], v[196:199], v[126:129]
	v_mfma_f32_16x16x32_bf16 v[122:125], v[66:69], v[196:199], v[122:125]
	v_mfma_f32_16x16x32_bf16 v[110:113], v[50:53], v[204:207], v[110:113]
	v_mfma_f32_16x16x32_bf16 v[106:109], v[66:69], v[204:207], v[106:109]
	v_mfma_f32_16x16x32_bf16 v[94:97], v[50:53], v[212:215], v[94:97]
	v_mfma_f32_16x16x32_bf16 v[90:93], v[66:69], v[212:215], v[90:93]
	v_mfma_f32_16x16x32_bf16 v[142:145], v[54:57], v[188:191], v[142:145]
	v_mfma_f32_16x16x32_bf16 v[138:141], v[70:73], v[188:191], v[138:141]
	v_mfma_f32_16x16x32_bf16 v[126:129], v[54:57], v[200:203], v[126:129]
	v_mfma_f32_16x16x32_bf16 v[122:125], v[70:73], v[200:203], v[122:125]
	v_mfma_f32_16x16x32_bf16 v[110:113], v[54:57], v[208:211], v[110:113]
	v_mfma_f32_16x16x32_bf16 v[106:109], v[70:73], v[208:211], v[106:109]
	v_mfma_f32_16x16x32_bf16 v[94:97], v[54:57], v[216:219], v[94:97]
	v_mfma_f32_16x16x32_bf16 v[90:93], v[70:73], v[216:219], v[90:93]
	v_mfma_f32_16x16x32_bf16 v[134:137], v[158:161], v[184:187], v[134:137]
	v_mfma_f32_16x16x32_bf16 v[130:133], v[166:169], v[184:187], v[130:133]
	v_mfma_f32_16x16x32_bf16 v[118:121], v[158:161], v[196:199], v[118:121]
	v_mfma_f32_16x16x32_bf16 v[114:117], v[166:169], v[196:199], v[114:117]
	v_mfma_f32_16x16x32_bf16 v[102:105], v[158:161], v[204:207], v[102:105]
	v_mfma_f32_16x16x32_bf16 v[98:101], v[166:169], v[204:207], v[98:101]
	v_mfma_f32_16x16x32_bf16 v[86:89], v[158:161], v[212:215], v[86:89]
	v_mfma_f32_16x16x32_bf16 v[82:85], v[166:169], v[212:215], v[82:85]
	v_mfma_f32_16x16x32_bf16 v[134:137], v[162:165], v[188:191], v[134:137]
	v_mfma_f32_16x16x32_bf16 v[130:133], v[180:183], v[188:191], v[130:133]
	v_mfma_f32_16x16x32_bf16 v[118:121], v[162:165], v[200:203], v[118:121]
	v_mfma_f32_16x16x32_bf16 v[114:117], v[180:183], v[200:203], v[114:117]
	v_mfma_f32_16x16x32_bf16 v[102:105], v[162:165], v[208:211], v[102:105]
	v_mfma_f32_16x16x32_bf16 v[98:101], v[180:183], v[208:211], v[98:101]
	v_mfma_f32_16x16x32_bf16 v[86:89], v[162:165], v[216:219], v[86:89]
	v_mfma_f32_16x16x32_bf16 v[82:85], v[180:183], v[216:219], v[82:85]
	s_barrier
; #define PG8_STAGE(bufoff, gbase, voff) do { _Pragma("unroll") for (int _i = 0; _i < 2; ++_i) \
;         __builtin_amdgcn_global_load_lds((const unsigned*)((const char*)(gbase) + (voff)[_i]), (LAS unsigned*)(lds + (bufoff) + ldsw + _i * 8192), 16, 0, 0); } while (0)
; #define PG8_LDA(dst, b, h) do { _Pragma("unroll") for (int m = 0; m < 4; ++m) _Pragma("unroll") for (int k = 0; k < 2; ++k) dst[m][k] = *(const LAS bf16x8*)(lds + PG8_SA(b, h) + aoff + m * 2048 + k * 1024); } while (0)
; #define PG8_MMA(ai, bj, At, Bt) do { __builtin_amdgcn_s_setprio(1); _Pragma("unroll") for (int m = 0; m < 4; ++m) _Pragma("unroll") for (int n = 0; n < 2; ++n) _Pragma("unroll") for (int k = 0; k < 2; ++k) \
;         acc[ai][bj][m][n] = __builtin_amdgcn_mfma_f32_16x16x32_bf16(Bt[n][k], At[m][k], acc[ai][bj][m][n], 0, 0, 0); __builtin_amdgcn_s_setprio(0); } while (0)
; #define PG8_WAIT_V(n) asm volatile("s_waitcnt vmcnt(" #n ")" ::: "memory")
; #define PG8_WAIT_L(n) asm volatile("s_waitcnt lgkmcnt(" #n ")" ::: "memory")
; #define PG8_BAR __builtin_amdgcn_s_barrier()
; #define PG8_SCHED __builtin_amdgcn_sched_barrier(0)
; template <class Epi>
; DI void gemm_phase(LAS unsigned char* lds, const Gemm g, const StaticOrder& S, const Epi& E) {
;     ...
;             PG8_LDA(At, 1, 1); PG8_STAGE(PG8_SB(1, 0), b3, voffB); PG8_STAGE(PG8_SB(1, 1), b3 + hstepB, voffB); PG8_STAGE(PG8_SA(1, 0), a3, voffA);
;             PG8_WAIT_V(8); PG8_WAIT_L(0); PG8_BAR; PG8_MMA(1, 0, At, B0); PG8_MMA(1, 1, At, B1); PG8_BAR; PG8_SCHED;
;         }
;         if (wr == 0) PG8_BAR;
	s_add_i32 s2, s2, s70
	v_lshl_add_u64 v[170:171], v[170:171], 0, s[6:7]
	s_mov_b32 m0, s2
	ds_read_b128 v[184:187], v194 offset:49152
	ds_read_b128 v[188:191], v194 offset:50176
	ds_read_b128 v[196:199], v194 offset:51200
	ds_read_b128 v[200:203], v194 offset:52224
	ds_read_b128 v[204:207], v194 offset:53248
	ds_read_b128 v[208:211], v194 offset:54272
	ds_read_b128 v[212:215], v194 offset:55296
	ds_read_b128 v[216:219], v194 offset:56320
	global_load_lds_dwordx4 v[170:171], off
	s_add_i32 m0, s2, 0x2000
	s_add_u32 s18, s18, 0x40080
	v_lshl_add_u64 v[170:171], v[238:239], 0, s[6:7]
	s_addc_u32 s19, s19, 0
	s_add_i32 s2, s15, s70
	global_load_lds_dwordx4 v[170:171], off
	v_lshl_add_u64 v[170:171], s[18:19], 0, v[148:149]
	s_mov_b32 m0, s2
	s_nop 0
	global_load_lds_dwordx4 v[170:171], off
	v_lshl_add_u64 v[170:171], s[18:19], 0, v[152:153]
	s_add_i32 m0, s2, 0x2000
	s_nop 0
	global_load_lds_dwordx4 v[170:171], off
	v_lshl_add_u64 v[170:171], v[240:241], 0, s[6:7]
	s_mov_b32 m0, s62
	s_nop 0
	global_load_lds_dwordx4 v[170:171], off
	v_lshl_add_u64 v[170:171], v[242:243], 0, s[6:7]
	s_mov_b32 m0, s78
	s_nop 0
	global_load_lds_dwordx4 v[170:171], off
	s_waitcnt vmcnt(8)
	s_waitcnt lgkmcnt(0)
	s_barrier
	s_waitcnt lgkmcnt(0)
	v_mfma_f32_16x16x32_bf16 v[78:81], v[50:53], v[184:187], v[78:81]
	v_mfma_f32_16x16x32_bf16 v[74:77], v[66:69], v[184:187], v[74:77]
	v_mfma_f32_16x16x32_bf16 v[62:65], v[50:53], v[196:199], v[62:65]
	v_mfma_f32_16x16x32_bf16 v[58:61], v[66:69], v[196:199], v[58:61]
	v_mfma_f32_16x16x32_bf16 v[30:33], v[50:53], v[204:207], v[30:33]
	v_mfma_f32_16x16x32_bf16 v[26:29], v[66:69], v[204:207], v[26:29]
	v_mfma_f32_16x16x32_bf16 v[14:17], v[50:53], v[212:215], v[14:17]
	v_mfma_f32_16x16x32_bf16 v[10:13], v[66:69], v[212:215], v[10:13]
	v_mfma_f32_16x16x32_bf16 v[78:81], v[54:57], v[188:191], v[78:81]
	v_mfma_f32_16x16x32_bf16 v[74:77], v[70:73], v[188:191], v[74:77]
	v_mfma_f32_16x16x32_bf16 v[62:65], v[54:57], v[200:203], v[62:65]
	v_mfma_f32_16x16x32_bf16 v[58:61], v[70:73], v[200:203], v[58:61]
	v_mfma_f32_16x16x32_bf16 v[30:33], v[54:57], v[208:211], v[30:33]
	v_mfma_f32_16x16x32_bf16 v[26:29], v[70:73], v[208:211], v[26:29]
	v_mfma_f32_16x16x32_bf16 v[14:17], v[54:57], v[216:219], v[14:17]
	v_mfma_f32_16x16x32_bf16 v[10:13], v[70:73], v[216:219], v[10:13]
	v_mfma_f32_16x16x32_bf16 v[34:37], v[158:161], v[184:187], v[34:37]
	v_mfma_f32_16x16x32_bf16 v[70:73], v[162:165], v[188:191], v[34:37]
	v_mfma_f32_16x16x32_bf16 v[34:37], v[166:169], v[184:187], v[38:41]
	v_mfma_f32_16x16x32_bf16 v[66:69], v[180:183], v[188:191], v[34:37]
	v_mfma_f32_16x16x32_bf16 v[34:37], v[158:161], v[196:199], v[42:45]
	v_mfma_f32_16x16x32_bf16 v[54:57], v[162:165], v[200:203], v[34:37]
	v_mfma_f32_16x16x32_bf16 v[34:37], v[166:169], v[196:199], v[46:49]
	v_mfma_f32_16x16x32_bf16 v[22:25], v[158:161], v[204:207], v[22:25]
	v_mfma_f32_16x16x32_bf16 v[18:21], v[166:169], v[204:207], v[18:21]
	v_mfma_f32_16x16x32_bf16 v[6:9], v[158:161], v[212:215], v[6:9]
	v_mfma_f32_16x16x32_bf16 v[2:5], v[166:169], v[212:215], v[2:5]
	v_mfma_f32_16x16x32_bf16 v[50:53], v[180:183], v[200:203], v[34:37]
	v_mfma_f32_16x16x32_bf16 v[22:25], v[162:165], v[208:211], v[22:25]
	v_mfma_f32_16x16x32_bf16 v[18:21], v[180:183], v[208:211], v[18:21]
	v_mfma_f32_16x16x32_bf16 v[6:9], v[162:165], v[216:219], v[6:9]
	v_mfma_f32_16x16x32_bf16 v[2:5], v[180:183], v[216:219], v[2:5]
	s_barrier
	s_add_i32 vcc_hi, vcc_hi, 2
	s_add_u32 s95, s95, 0x100
	s_addc_u32 vcc_lo, vcc_lo, 0
	s_add_u32 s0, s0, 0x100
	s_addc_u32 s1, s1, 0
	s_cmp_gt_u32 vcc_hi, 13
	s_cbranch_scc0 .LBB0_405
	s_setprio 0
	s_and_b64 vcc, exec, s[50:51]
	s_movk_i32 s25, 0x440
	s_cbranch_vccz .LBB0_408
	s_barrier

; #define PG8_STAGE(bufoff, gbase, voff) do { _Pragma("unroll") for (int _i = 0; _i < 2; ++_i) \
;         __builtin_amdgcn_global_load_lds((const unsigned*)((const char*)(gbase) + (voff)[_i]), (LAS unsigned*)(lds + (bufoff) + ldsw + _i * 8192), 16, 0, 0); } while (0)
; #define PG8_LDA(dst, b, h) do { _Pragma("unroll") for (int m = 0; m < 4; ++m) _Pragma("unroll") for (int k = 0; k < 2; ++k) dst[m][k] = *(const LAS bf16x8*)(lds + PG8_SA(b, h) + aoff + m * 2048 + k * 1024); } while (0)
; #define PG8_LDB(dst, b, h) do { _Pragma("unroll") for (int n = 0; n < 2; ++n) _Pragma("unroll") for (int k = 0; k < 2; ++k) dst[n][k] = *(const LAS bf16x8*)(lds + PG8_SB(b, h) + boff + n * 2048 + k * 1024); } while (0)
; #define PG8_MMA(ai, bj, At, Bt) do { __builtin_amdgcn_s_setprio(1); _Pragma("unroll") for (int m = 0; m < 4; ++m) _Pragma("unroll") for (int n = 0; n < 2; ++n) _Pragma("unroll") for (int k = 0; k < 2; ++k) \
;         acc[ai][bj][m][n] = __builtin_amdgcn_mfma_f32_16x16x32_bf16(Bt[n][k], At[m][k], acc[ai][bj][m][n], 0, 0, 0); __builtin_amdgcn_s_setprio(0); } while (0)
; #define PG8_BAR __builtin_amdgcn_s_barrier()
; template <class Epi>
; DI void gemm_phase(LAS unsigned char* lds, const Gemm g, const StaticOrder& S, const Epi& E) {
;     ...
;         const bool has_next = S.next(ui + 1, nxt);
;         const char* nA = has_next ? (const char*)g.A + (size_t)nxt.pm * tstepA + (size_t)nxt.pn * g.a_pn_off * 2 : cA; const char* nB = has_next ? (const char*)g.Bt + (size_t)nxt.pn * tstepB : cB;
;         for (int t = 0; t < nt; t += 2) {
;             const bool last = (t == nt - 2);
;             const char* a1 = cA + (size_t)(t + 1) * kstepA;
;             const char* a2 = last ? nA : cA + (size_t)(t + 2) * kstepA; const char* b2 = last ? nB : cB + (size_t)(t + 2) * kstepB;
;             const char* a3 = a2 + kstepA; const char* b3 = b2 + kstepB;
;             PG8_LDB(B0, 0, 0); PG8_LDB(B1, 0, 1); PG8_SCHED; PG8_LDA(At, 0, 0); PG8_STAGE(PG8_SA(1, 1), a1 + hstepA, voffA);
;             PG8_WAIT_V(8); PG8_WAIT_L(0); PG8_BAR; PG8_MMA(0, 0, At, B0); PG8_MMA(0, 1, At, B1); PG8_BAR; PG8_SCHED;
;     ...
; #pragma unroll
;         for (int a = 0; a < 2; ++a)
; #pragma unroll
;             for (int b = 0; b < 2; ++b)
; #pragma unroll
;                 for (int m = 0; m < 4; ++m)
; #pragma unroll
;                     for (int n = 0; n < 2; ++n) acc[a][b][m][n] = (f32x4){0.f, 0.f, 0.f, 0.f};
.LBB0_791:
	s_ashr_i32 s39, s38, 31
	s_lshl_b64 s[22:23], s[38:39], 19
	s_add_u32 s44, s26, s22
	s_addc_u32 s45, s27, s23
	s_and_b64 s[22:23], s[42:43], exec
	s_cselect_b32 s39, s45, s51
	s_cselect_b32 s79, s44, s50
	s_ashr_i32 s37, s36, 31
	s_lshl_b64 s[22:23], s[36:37], 19
	s_add_u32 s46, s28, s22
	s_addc_u32 s47, s29, s23
	s_and_b64 s[22:23], s[42:43], exec
	s_cselect_b32 s37, s47, s19
	s_cselect_b32 s84, s46, s18
	s_add_u32 s85, s18, 0x100
	s_addc_u32 s88, s19, 0
	s_add_u32 s50, s50, 0x40080
	v_mov_b32_e32 v2, 0
	s_addc_u32 s51, s51, 0
	s_mov_b32 s89, -2
	v_mov_b32_e32 v3, v2
	v_mov_b32_e32 v4, v2
	v_mov_b32_e32 v5, v2
	v_mov_b32_e32 v6, v2
	v_mov_b32_e32 v7, v2
	v_mov_b32_e32 v8, v2
	v_mov_b32_e32 v9, v2
	v_mov_b32_e32 v18, v2
	v_mov_b32_e32 v19, v2
	v_mov_b32_e32 v20, v2
	v_mov_b32_e32 v21, v2
	v_mov_b32_e32 v22, v2
	v_mov_b32_e32 v23, v2
	v_mov_b32_e32 v24, v2
	v_mov_b32_e32 v25, v2
	v_mov_b32_e32 v34, v2
	v_mov_b32_e32 v35, v2
	v_mov_b32_e32 v36, v2
	v_mov_b32_e32 v37, v2
	v_mov_b32_e32 v38, v2
	v_mov_b32_e32 v39, v2
	v_mov_b32_e32 v40, v2
	v_mov_b32_e32 v41, v2
	v_mov_b32_e32 v50, v2
	v_mov_b32_e32 v51, v2
	v_mov_b32_e32 v52, v2
	v_mov_b32_e32 v53, v2
	v_mov_b32_e32 v54, v2
	v_mov_b32_e32 v55, v2
	v_mov_b32_e32 v56, v2
	v_mov_b32_e32 v57, v2
	v_mov_b32_e32 v10, v2
	v_mov_b32_e32 v11, v2
	v_mov_b32_e32 v12, v2
	v_mov_b32_e32 v13, v2
	v_mov_b32_e32 v14, v2
	v_mov_b32_e32 v15, v2
	v_mov_b32_e32 v16, v2
	v_mov_b32_e32 v17, v2
	v_mov_b32_e32 v26, v2
	v_mov_b32_e32 v27, v2
	v_mov_b32_e32 v28, v2
	v_mov_b32_e32 v29, v2
	v_mov_b32_e32 v30, v2
	v_mov_b32_e32 v31, v2
	v_mov_b32_e32 v32, v2
	v_mov_b32_e32 v33, v2
	v_mov_b32_e32 v42, v2
	v_mov_b32_e32 v43, v2
	v_mov_b32_e32 v44, v2
	v_mov_b32_e32 v45, v2
	v_mov_b32_e32 v46, v2
	v_mov_b32_e32 v47, v2
	v_mov_b32_e32 v48, v2
	v_mov_b32_e32 v49, v2
	v_mov_b32_e32 v58, v2
	v_mov_b32_e32 v59, v2
	v_mov_b32_e32 v60, v2
	v_mov_b32_e32 v61, v2
	v_mov_b32_e32 v62, v2
	v_mov_b32_e32 v63, v2
	v_mov_b32_e32 v64, v2
	v_mov_b32_e32 v65, v2
	v_mov_b32_e32 v66, v2
	v_mov_b32_e32 v67, v2
	v_mov_b32_e32 v68, v2
	v_mov_b32_e32 v69, v2
	v_mov_b32_e32 v70, v2
	v_mov_b32_e32 v71, v2
	v_mov_b32_e32 v72, v2
	v_mov_b32_e32 v73, v2
	v_mov_b32_e32 v82, v2
	v_mov_b32_e32 v83, v2
	v_mov_b32_e32 v84, v2
	v_mov_b32_e32 v85, v2
	v_mov_b32_e32 v86, v2
	v_mov_b32_e32 v87, v2
	v_mov_b32_e32 v88, v2
	v_mov_b32_e32 v89, v2
	v_mov_b32_e32 v98, v2
	v_mov_b32_e32 v99, v2
	v_mov_b32_e32 v100, v2
	v_mov_b32_e32 v101, v2
	v_mov_b32_e32 v102, v2
	v_mov_b32_e32 v103, v2
	v_mov_b32_e32 v104, v2
	v_mov_b32_e32 v105, v2
	v_mov_b32_e32 v114, v2
	v_mov_b32_e32 v115, v2
	v_mov_b32_e32 v116, v2
	v_mov_b32_e32 v117, v2
	v_mov_b32_e32 v118, v2
	v_mov_b32_e32 v119, v2
	v_mov_b32_e32 v120, v2
	v_mov_b32_e32 v121, v2
	v_mov_b32_e32 v74, v2
	v_mov_b32_e32 v75, v2
	v_mov_b32_e32 v76, v2
	v_mov_b32_e32 v77, v2
	v_mov_b32_e32 v78, v2
	v_mov_b32_e32 v79, v2
	v_mov_b32_e32 v80, v2
	v_mov_b32_e32 v81, v2
	v_mov_b32_e32 v90, v2
	v_mov_b32_e32 v91, v2
	v_mov_b32_e32 v92, v2
	v_mov_b32_e32 v93, v2
	v_mov_b32_e32 v94, v2
	v_mov_b32_e32 v95, v2
	v_mov_b32_e32 v96, v2
	v_mov_b32_e32 v97, v2
	v_mov_b32_e32 v106, v2
	v_mov_b32_e32 v107, v2
	v_mov_b32_e32 v108, v2
	v_mov_b32_e32 v109, v2
	v_mov_b32_e32 v110, v2
	v_mov_b32_e32 v111, v2
	v_mov_b32_e32 v112, v2
	v_mov_b32_e32 v113, v2
	v_mov_b32_e32 v122, v2
	v_mov_b32_e32 v123, v2
	v_mov_b32_e32 v124, v2
	v_mov_b32_e32 v125, v2
	v_mov_b32_e32 v126, v2
	v_mov_b32_e32 v127, v2
	v_mov_b32_e32 v128, v2
	v_mov_b32_e32 v129, v2
	v_readfirstlane_b32 s2, v220
	s_lshr_b32 s2, s2, 8
	s_cmp_eq_u32 s2, 0
	s_cbranch_scc1 .Lsprio_3
	s_setprio 1
.Lsprio_3:
.LBB0_792:
	s_add_u32 s2, s50, 0xfffc0080
	s_addc_u32 s15, s51, -1
	s_cmp_eq_u32 s89, 12
	s_cselect_b32 s23, s39, s15
	s_cselect_b32 s22, s79, s2
	s_cselect_b32 s19, s37, s88
	s_cselect_b32 s18, s84, s85
	s_add_i32 s2, 0, 0x10000
	s_add_i32 s15, 0, 0x14000
	v_add_u32_e32 v158, s2, v152
	v_add_u32_e32 v170, s15, v152
	ds_read_b128 v[142:145], v158
	ds_read_b128 v[146:149], v158 offset:1024
	ds_read_b128 v[154:157], v158 offset:2048
	ds_read_b128 v[158:161], v158 offset:3072
	ds_read_b128 v[162:165], v170
	ds_read_b128 v[166:169], v170 offset:1024
	ds_read_b128 v[180:183], v170 offset:2048
	ds_read_b128 v[184:187], v170 offset:3072
	v_lshl_add_u64 v[170:171], s[50:51], 0, v[140:141]
	s_add_i32 m0, s41, 0xc000
	ds_read_b128 v[188:191], v153
	ds_read_b128 v[192:195], v153 offset:1024
	ds_read_b128 v[196:199], v153 offset:2048
	ds_read_b128 v[200:203], v153 offset:3072
	ds_read_b128 v[204:207], v153 offset:4096
	ds_read_b128 v[208:211], v153 offset:5120
	ds_read_b128 v[212:215], v153 offset:6144
	ds_read_b128 v[216:219], v153 offset:7168
	global_load_lds_dwordx4 v[170:171], off
	v_lshl_add_u64 v[170:171], s[50:51], 0, v[138:139]
	s_add_i32 m0, s41, 0xe000
	s_nop 0
	global_load_lds_dwordx4 v[170:171], off
	s_waitcnt vmcnt(8)
	s_waitcnt lgkmcnt(0)
	s_barrier
; #define PG8_STAGE(bufoff, gbase, voff) do { _Pragma("unroll") for (int _i = 0; _i < 2; ++_i) \
;         __builtin_amdgcn_global_load_lds((const unsigned*)((const char*)(gbase) + (voff)[_i]), (LAS unsigned*)(lds + (bufoff) + ldsw + _i * 8192), 16, 0, 0); } while (0)
; #define PG8_LDA(dst, b, h) do { _Pragma("unroll") for (int m = 0; m < 4; ++m) _Pragma("unroll") for (int k = 0; k < 2; ++k) dst[m][k] = *(const LAS bf16x8*)(lds + PG8_SA(b, h) + aoff + m * 2048 + k * 1024); } while (0)
; #define PG8_LDB(dst, b, h) do { _Pragma("unroll") for (int n = 0; n < 2; ++n) _Pragma("unroll") for (int k = 0; k < 2; ++k) dst[n][k] = *(const LAS bf16x8*)(lds + PG8_SB(b, h) + boff + n * 2048 + k * 1024); } while (0)
; #define PG8_MMA(ai, bj, At, Bt) do { __builtin_amdgcn_s_setprio(1); _Pragma("unroll") for (int m = 0; m < 4; ++m) _Pragma("unroll") for (int n = 0; n < 2; ++n) _Pragma("unroll") for (int k = 0; k < 2; ++k) \
;         acc[ai][bj][m][n] = __builtin_amdgcn_mfma_f32_16x16x32_bf16(Bt[n][k], At[m][k], acc[ai][bj][m][n], 0, 0, 0); __builtin_amdgcn_s_setprio(0); } while (0)
; #define PG8_WAIT_V(n) asm volatile("s_waitcnt vmcnt(" #n ")" ::: "memory")
; #define PG8_WAIT_L(n) asm volatile("s_waitcnt lgkmcnt(" #n ")" ::: "memory")
; #define PG8_BAR __builtin_amdgcn_s_barrier()
; #define PG8_SCHED __builtin_amdgcn_sched_barrier(0)
; template <class Epi>
; DI void gemm_phase(LAS unsigned char* lds, const Gemm g, const StaticOrder& S, const Epi& E) {
;     ...
;             PG8_LDB(B0, 0, 0); PG8_LDB(B1, 0, 1); PG8_SCHED; PG8_LDA(At, 0, 0); PG8_STAGE(PG8_SA(1, 1), a1 + hstepA, voffA);
;             PG8_WAIT_V(8); PG8_WAIT_L(0); PG8_BAR; PG8_MMA(0, 0, At, B0); PG8_MMA(0, 1, At, B1); PG8_BAR; PG8_SCHED;
;             PG8_LDA(At, 0, 1); PG8_STAGE(PG8_SB(0, 0), b2, voffB); PG8_STAGE(PG8_SB(0, 1), b2 + hstepB, voffB); PG8_STAGE(PG8_SA(0, 0), a2, voffA);
;             PG8_WAIT_V(8); PG8_WAIT_L(0); PG8_BAR; PG8_MMA(1, 0, At, B0); PG8_MMA(1, 1, At, B1); PG8_BAR; PG8_SCHED;
	s_waitcnt lgkmcnt(0)
	v_mfma_f32_16x16x32_bf16 v[126:129], v[142:145], v[188:191], v[126:129]
	v_mfma_f32_16x16x32_bf16 v[122:125], v[154:157], v[188:191], v[122:125]
	v_mfma_f32_16x16x32_bf16 v[110:113], v[142:145], v[196:199], v[110:113]
	v_mfma_f32_16x16x32_bf16 v[106:109], v[154:157], v[196:199], v[106:109]
	v_mfma_f32_16x16x32_bf16 v[94:97], v[142:145], v[204:207], v[94:97]
	v_mfma_f32_16x16x32_bf16 v[90:93], v[154:157], v[204:207], v[90:93]
	v_mfma_f32_16x16x32_bf16 v[78:81], v[142:145], v[212:215], v[78:81]
	v_mfma_f32_16x16x32_bf16 v[74:77], v[154:157], v[212:215], v[74:77]
	v_mfma_f32_16x16x32_bf16 v[126:129], v[146:149], v[192:195], v[126:129]
	v_mfma_f32_16x16x32_bf16 v[122:125], v[158:161], v[192:195], v[122:125]
	v_mfma_f32_16x16x32_bf16 v[110:113], v[146:149], v[200:203], v[110:113]
	v_mfma_f32_16x16x32_bf16 v[106:109], v[158:161], v[200:203], v[106:109]
	v_mfma_f32_16x16x32_bf16 v[94:97], v[146:149], v[208:211], v[94:97]
	v_mfma_f32_16x16x32_bf16 v[90:93], v[158:161], v[208:211], v[90:93]
	v_mfma_f32_16x16x32_bf16 v[78:81], v[146:149], v[216:219], v[78:81]
	v_mfma_f32_16x16x32_bf16 v[74:77], v[158:161], v[216:219], v[74:77]
	v_mfma_f32_16x16x32_bf16 v[118:121], v[162:165], v[188:191], v[118:121]
	v_mfma_f32_16x16x32_bf16 v[114:117], v[180:183], v[188:191], v[114:117]
	v_mfma_f32_16x16x32_bf16 v[102:105], v[162:165], v[196:199], v[102:105]
	v_mfma_f32_16x16x32_bf16 v[98:101], v[180:183], v[196:199], v[98:101]
	v_mfma_f32_16x16x32_bf16 v[86:89], v[162:165], v[204:207], v[86:89]
	v_mfma_f32_16x16x32_bf16 v[82:85], v[180:183], v[204:207], v[82:85]
	v_mfma_f32_16x16x32_bf16 v[70:73], v[162:165], v[212:215], v[70:73]
	v_mfma_f32_16x16x32_bf16 v[66:69], v[180:183], v[212:215], v[66:69]
	v_mfma_f32_16x16x32_bf16 v[118:121], v[166:169], v[192:195], v[118:121]
	v_mfma_f32_16x16x32_bf16 v[114:117], v[184:187], v[192:195], v[114:117]
	v_mfma_f32_16x16x32_bf16 v[102:105], v[166:169], v[200:203], v[102:105]
	v_mfma_f32_16x16x32_bf16 v[98:101], v[184:187], v[200:203], v[98:101]
	v_mfma_f32_16x16x32_bf16 v[86:89], v[166:169], v[208:211], v[86:89]
	v_mfma_f32_16x16x32_bf16 v[82:85], v[184:187], v[208:211], v[82:85]
	v_mfma_f32_16x16x32_bf16 v[70:73], v[166:169], v[216:219], v[70:73]
	v_mfma_f32_16x16x32_bf16 v[66:69], v[184:187], v[216:219], v[66:69]
	s_barrier
	s_add_i32 s2, s2, s40
	v_lshl_add_u64 v[170:171], s[18:19], 0, v[134:135]
	s_mov_b32 m0, s2
	ds_read_b128 v[188:191], v153 offset:16384
	ds_read_b128 v[192:195], v153 offset:17408
	ds_read_b128 v[196:199], v153 offset:18432
	ds_read_b128 v[200:203], v153 offset:19456
	ds_read_b128 v[204:207], v153 offset:20480
	ds_read_b128 v[208:211], v153 offset:21504
	ds_read_b128 v[212:215], v153 offset:22528
	ds_read_b128 v[216:219], v153 offset:23552
	global_load_lds_dwordx4 v[170:171], off
	s_add_i32 m0, s2, 0x2000
	s_add_u32 s48, s18, 0x40000
	v_lshl_add_u64 v[238:239], s[18:19], 0, v[130:131]
	s_addc_u32 s49, s19, 0
	s_add_i32 s2, s15, s40
	global_load_lds_dwordx4 v[238:239], off
	v_lshl_add_u64 v[240:241], s[48:49], 0, v[134:135]
	s_mov_b32 m0, s2
	v_lshl_add_u64 v[242:243], s[22:23], 0, v[132:133]
	global_load_lds_dwordx4 v[240:241], off
	v_lshl_add_u64 v[240:241], s[48:49], 0, v[130:131]
	s_add_i32 m0, s2, 0x2000
	s_nop 0
	global_load_lds_dwordx4 v[240:241], off
	v_lshl_add_u64 v[240:241], s[22:23], 0, v[136:137]
	s_mov_b32 m0, s41
	s_nop 0
	global_load_lds_dwordx4 v[240:241], off
	s_mov_b32 m0, s62
	s_nop 0
	global_load_lds_dwordx4 v[242:243], off
	s_waitcnt vmcnt(8)
	s_waitcnt lgkmcnt(0)
	s_barrier
	s_waitcnt lgkmcnt(0)
	v_mfma_f32_16x16x32_bf16 v[62:65], v[142:145], v[188:191], v[62:65]
	v_mfma_f32_16x16x32_bf16 v[58:61], v[154:157], v[188:191], v[58:61]
	v_mfma_f32_16x16x32_bf16 v[46:49], v[142:145], v[196:199], v[46:49]
	v_mfma_f32_16x16x32_bf16 v[42:45], v[154:157], v[196:199], v[42:45]
	v_mfma_f32_16x16x32_bf16 v[30:33], v[142:145], v[204:207], v[30:33]
	v_mfma_f32_16x16x32_bf16 v[26:29], v[154:157], v[204:207], v[26:29]
	v_mfma_f32_16x16x32_bf16 v[14:17], v[142:145], v[212:215], v[14:17]
	v_mfma_f32_16x16x32_bf16 v[10:13], v[154:157], v[212:215], v[10:13]
	v_mfma_f32_16x16x32_bf16 v[62:65], v[146:149], v[192:195], v[62:65]
	v_mfma_f32_16x16x32_bf16 v[58:61], v[158:161], v[192:195], v[58:61]
	v_mfma_f32_16x16x32_bf16 v[46:49], v[146:149], v[200:203], v[46:49]
	v_mfma_f32_16x16x32_bf16 v[42:45], v[158:161], v[200:203], v[42:45]
	v_mfma_f32_16x16x32_bf16 v[30:33], v[146:149], v[208:211], v[30:33]
	v_mfma_f32_16x16x32_bf16 v[26:29], v[158:161], v[208:211], v[26:29]
	v_mfma_f32_16x16x32_bf16 v[14:17], v[146:149], v[216:219], v[14:17]
	v_mfma_f32_16x16x32_bf16 v[10:13], v[158:161], v[216:219], v[10:13]
	v_mfma_f32_16x16x32_bf16 v[54:57], v[162:165], v[188:191], v[54:57]
	v_mfma_f32_16x16x32_bf16 v[50:53], v[180:183], v[188:191], v[50:53]
	v_mfma_f32_16x16x32_bf16 v[38:41], v[162:165], v[196:199], v[38:41]
	v_mfma_f32_16x16x32_bf16 v[34:37], v[180:183], v[196:199], v[34:37]
	v_mfma_f32_16x16x32_bf16 v[22:25], v[162:165], v[204:207], v[22:25]
	v_mfma_f32_16x16x32_bf16 v[18:21], v[180:183], v[204:207], v[18:21]
	v_mfma_f32_16x16x32_bf16 v[6:9], v[162:165], v[212:215], v[6:9]
	v_mfma_f32_16x16x32_bf16 v[2:5], v[180:183], v[212:215], v[2:5]
	v_mfma_f32_16x16x32_bf16 v[54:57], v[166:169], v[192:195], v[54:57]
	v_mfma_f32_16x16x32_bf16 v[50:53], v[184:187], v[192:195], v[50:53]
	v_mfma_f32_16x16x32_bf16 v[38:41], v[166:169], v[200:203], v[38:41]
	v_mfma_f32_16x16x32_bf16 v[34:37], v[184:187], v[200:203], v[34:37]
	v_mfma_f32_16x16x32_bf16 v[22:25], v[166:169], v[208:211], v[22:25]
	v_mfma_f32_16x16x32_bf16 v[18:21], v[184:187], v[208:211], v[18:21]
	v_mfma_f32_16x16x32_bf16 v[6:9], v[166:169], v[216:219], v[6:9]
	v_mfma_f32_16x16x32_bf16 v[2:5], v[184:187], v[216:219], v[2:5]
	s_barrier
; #define PG8_STAGE(bufoff, gbase, voff) do { _Pragma("unroll") for (int _i = 0; _i < 2; ++_i) \
;         __builtin_amdgcn_global_load_lds((const unsigned*)((const char*)(gbase) + (voff)[_i]), (LAS unsigned*)(lds + (bufoff) + ldsw + _i * 8192), 16, 0, 0); } while (0)
; #define PG8_LDA(dst, b, h) do { _Pragma("unroll") for (int m = 0; m < 4; ++m) _Pragma("unroll") for (int k = 0; k < 2; ++k) dst[m][k] = *(const LAS bf16x8*)(lds + PG8_SA(b, h) + aoff + m * 2048 + k * 1024); } while (0)
; #define PG8_LDB(dst, b, h) do { _Pragma("unroll") for (int n = 0; n < 2; ++n) _Pragma("unroll") for (int k = 0; k < 2; ++k) dst[n][k] = *(const LAS bf16x8*)(lds + PG8_SB(b, h) + boff + n * 2048 + k * 1024); } while (0)
; #define PG8_MMA(ai, bj, At, Bt) do { __builtin_amdgcn_s_setprio(1); _Pragma("unroll") for (int m = 0; m < 4; ++m) _Pragma("unroll") for (int n = 0; n < 2; ++n) _Pragma("unroll") for (int k = 0; k < 2; ++k) \
;         acc[ai][bj][m][n] = __builtin_amdgcn_mfma_f32_16x16x32_bf16(Bt[n][k], At[m][k], acc[ai][bj][m][n], 0, 0, 0); __builtin_amdgcn_s_setprio(0); } while (0)
; #define PG8_WAIT_V(n) asm volatile("s_waitcnt vmcnt(" #n ")" ::: "memory")
; #define PG8_WAIT_L(n) asm volatile("s_waitcnt lgkmcnt(" #n ")" ::: "memory")
; #define PG8_BAR __builtin_amdgcn_s_barrier()
; #define PG8_SCHED __builtin_amdgcn_sched_barrier(0)
; template <class Epi>
; DI void gemm_phase(LAS unsigned char* lds, const Gemm g, const StaticOrder& S, const Epi& E) {
;     ...
;             PG8_LDB(B0, 1, 0); PG8_LDB(B1, 1, 1); PG8_SCHED; PG8_LDA(At, 1, 0); PG8_STAGE(PG8_SA(0, 1), a2 + hstepA, voffA);
;             PG8_WAIT_V(8); PG8_WAIT_L(0); PG8_BAR; PG8_MMA(0, 0, At, B0); PG8_MMA(0, 1, At, B1); PG8_BAR; PG8_SCHED;
	s_add_i32 s2, 0, 0x18000
	s_add_i32 s15, 0, 0x1c000
	v_add_u32_e32 v158, s2, v152
	v_add_u32_e32 v184, s15, v152
	ds_read_b128 v[142:145], v158
	ds_read_b128 v[146:149], v158 offset:1024
	ds_read_b128 v[154:157], v158 offset:2048
	ds_read_b128 v[158:161], v158 offset:3072
	ds_read_b128 v[162:165], v184
	ds_read_b128 v[166:169], v184 offset:1024
	ds_read_b128 v[180:183], v184 offset:2048
	ds_read_b128 v[184:187], v184 offset:3072
	s_add_u32 s22, s22, 0x40000
	s_addc_u32 s23, s23, 0
	s_mov_b32 m0, s69
	v_lshl_add_u64 v[244:245], s[22:23], 0, v[136:137]
	ds_read_b128 v[188:191], v153 offset:32768
	ds_read_b128 v[192:195], v153 offset:33792
	ds_read_b128 v[196:199], v153 offset:34816
	ds_read_b128 v[200:203], v153 offset:35840
	ds_read_b128 v[204:207], v153 offset:36864
	ds_read_b128 v[208:211], v153 offset:37888
	ds_read_b128 v[212:215], v153 offset:38912
	ds_read_b128 v[216:219], v153 offset:39936
	global_load_lds_dwordx4 v[244:245], off
	v_lshl_add_u64 v[244:245], s[22:23], 0, v[132:133]
	s_mov_b32 m0, s70
	s_nop 0
	global_load_lds_dwordx4 v[244:245], off
	s_waitcnt vmcnt(8)
	s_waitcnt lgkmcnt(0)
	s_barrier
	s_waitcnt lgkmcnt(0)
	v_mfma_f32_16x16x32_bf16 v[126:129], v[142:145], v[188:191], v[126:129]
	v_mfma_f32_16x16x32_bf16 v[122:125], v[154:157], v[188:191], v[122:125]
	v_mfma_f32_16x16x32_bf16 v[110:113], v[142:145], v[196:199], v[110:113]
	v_mfma_f32_16x16x32_bf16 v[106:109], v[154:157], v[196:199], v[106:109]
	v_mfma_f32_16x16x32_bf16 v[94:97], v[142:145], v[204:207], v[94:97]
	v_mfma_f32_16x16x32_bf16 v[90:93], v[154:157], v[204:207], v[90:93]
	v_mfma_f32_16x16x32_bf16 v[78:81], v[142:145], v[212:215], v[78:81]
	v_mfma_f32_16x16x32_bf16 v[74:77], v[154:157], v[212:215], v[74:77]
	v_mfma_f32_16x16x32_bf16 v[126:129], v[146:149], v[192:195], v[126:129]
	v_mfma_f32_16x16x32_bf16 v[122:125], v[158:161], v[192:195], v[122:125]
	v_mfma_f32_16x16x32_bf16 v[110:113], v[146:149], v[200:203], v[110:113]
	v_mfma_f32_16x16x32_bf16 v[106:109], v[158:161], v[200:203], v[106:109]
	v_mfma_f32_16x16x32_bf16 v[94:97], v[146:149], v[208:211], v[94:97]
	v_mfma_f32_16x16x32_bf16 v[90:93], v[158:161], v[208:211], v[90:93]
	v_mfma_f32_16x16x32_bf16 v[78:81], v[146:149], v[216:219], v[78:81]
	v_mfma_f32_16x16x32_bf16 v[74:77], v[158:161], v[216:219], v[74:77]
	v_mfma_f32_16x16x32_bf16 v[118:121], v[162:165], v[188:191], v[118:121]
	v_mfma_f32_16x16x32_bf16 v[114:117], v[180:183], v[188:191], v[114:117]
	v_mfma_f32_16x16x32_bf16 v[102:105], v[162:165], v[196:199], v[102:105]
	v_mfma_f32_16x16x32_bf16 v[98:101], v[180:183], v[196:199], v[98:101]
	v_mfma_f32_16x16x32_bf16 v[86:89], v[162:165], v[204:207], v[86:89]
	v_mfma_f32_16x16x32_bf16 v[82:85], v[180:183], v[204:207], v[82:85]
	v_mfma_f32_16x16x32_bf16 v[70:73], v[162:165], v[212:215], v[70:73]
	v_mfma_f32_16x16x32_bf16 v[66:69], v[180:183], v[212:215], v[66:69]
	v_mfma_f32_16x16x32_bf16 v[118:121], v[166:169], v[192:195], v[118:121]
	v_mfma_f32_16x16x32_bf16 v[114:117], v[184:187], v[192:195], v[114:117]
	v_mfma_f32_16x16x32_bf16 v[102:105], v[166:169], v[200:203], v[102:105]
	v_mfma_f32_16x16x32_bf16 v[98:101], v[184:187], v[200:203], v[98:101]
	v_mfma_f32_16x16x32_bf16 v[86:89], v[166:169], v[208:211], v[86:89]
	v_mfma_f32_16x16x32_bf16 v[82:85], v[184:187], v[208:211], v[82:85]
	v_mfma_f32_16x16x32_bf16 v[70:73], v[166:169], v[216:219], v[70:73]
	v_mfma_f32_16x16x32_bf16 v[66:69], v[184:187], v[216:219], v[66:69]
	s_barrier
; #define PG8_STAGE(bufoff, gbase, voff) do { _Pragma("unroll") for (int _i = 0; _i < 2; ++_i) \
;         __builtin_amdgcn_global_load_lds((const unsigned*)((const char*)(gbase) + (voff)[_i]), (LAS unsigned*)(lds + (bufoff) + ldsw + _i * 8192), 16, 0, 0); } while (0)
; #define PG8_LDA(dst, b, h) do { _Pragma("unroll") for (int m = 0; m < 4; ++m) _Pragma("unroll") for (int k = 0; k < 2; ++k) dst[m][k] = *(const LAS bf16x8*)(lds + PG8_SA(b, h) + aoff + m * 2048 + k * 1024); } while (0)
; #define PG8_MMA(ai, bj, At, Bt) do { __builtin_amdgcn_s_setprio(1); _Pragma("unroll") for (int m = 0; m < 4; ++m) _Pragma("unroll") for (int n = 0; n < 2; ++n) _Pragma("unroll") for (int k = 0; k < 2; ++k) \
;         acc[ai][bj][m][n] = __builtin_amdgcn_mfma_f32_16x16x32_bf16(Bt[n][k], At[m][k], acc[ai][bj][m][n], 0, 0, 0); __builtin_amdgcn_s_setprio(0); } while (0)
; #define PG8_WAIT_V(n) asm volatile("s_waitcnt vmcnt(" #n ")" ::: "memory")
; #define PG8_WAIT_L(n) asm volatile("s_waitcnt lgkmcnt(" #n ")" ::: "memory")
; #define PG8_BAR __builtin_amdgcn_s_barrier()
; #define PG8_SCHED __builtin_amdgcn_sched_barrier(0)
; template <class Epi>
; DI void gemm_phase(LAS unsigned char* lds, const Gemm g, const StaticOrder& S, const Epi& E) {
;     ...
;             PG8_LDA(At, 1, 1); PG8_STAGE(PG8_SB(1, 0), b3, voffB); PG8_STAGE(PG8_SB(1, 1), b3 + hstepB, voffB); PG8_STAGE(PG8_SA(1, 0), a3, voffA);
;             PG8_WAIT_V(8); PG8_WAIT_L(0); PG8_BAR; PG8_MMA(1, 0, At, B0); PG8_MMA(1, 1, At, B1); PG8_BAR; PG8_SCHED;
;         }
;         if (wr == 0) PG8_BAR;
	s_add_i32 s2, s2, s40
	v_lshl_add_u64 v[170:171], v[170:171], 0, s[6:7]
	s_mov_b32 m0, s2
	ds_read_b128 v[188:191], v153 offset:49152
	ds_read_b128 v[192:195], v153 offset:50176
	ds_read_b128 v[196:199], v153 offset:51200
	ds_read_b128 v[200:203], v153 offset:52224
	ds_read_b128 v[204:207], v153 offset:53248
	ds_read_b128 v[208:211], v153 offset:54272
	ds_read_b128 v[212:215], v153 offset:55296
	ds_read_b128 v[216:219], v153 offset:56320
	global_load_lds_dwordx4 v[170:171], off
	s_add_i32 m0, s2, 0x2000
	s_add_u32 s18, s18, 0x40080
	v_lshl_add_u64 v[170:171], v[238:239], 0, s[6:7]
	s_addc_u32 s19, s19, 0
	s_add_i32 s2, s15, s40
	global_load_lds_dwordx4 v[170:171], off
	v_lshl_add_u64 v[170:171], s[18:19], 0, v[134:135]
	s_mov_b32 m0, s2
	s_nop 0
	global_load_lds_dwordx4 v[170:171], off
	v_lshl_add_u64 v[170:171], s[18:19], 0, v[130:131]
	s_add_i32 m0, s2, 0x2000
	s_nop 0
	global_load_lds_dwordx4 v[170:171], off
	v_lshl_add_u64 v[170:171], v[240:241], 0, s[6:7]
	s_mov_b32 m0, s73
	s_nop 0
	global_load_lds_dwordx4 v[170:171], off
	v_lshl_add_u64 v[170:171], v[242:243], 0, s[6:7]
	s_mov_b32 m0, s74
	s_nop 0
	global_load_lds_dwordx4 v[170:171], off
	s_waitcnt vmcnt(8)
	s_waitcnt lgkmcnt(0)
	s_barrier
	s_waitcnt lgkmcnt(0)
	v_mfma_f32_16x16x32_bf16 v[62:65], v[142:145], v[188:191], v[62:65]
	v_mfma_f32_16x16x32_bf16 v[58:61], v[154:157], v[188:191], v[58:61]
	v_mfma_f32_16x16x32_bf16 v[46:49], v[142:145], v[196:199], v[46:49]
	v_mfma_f32_16x16x32_bf16 v[42:45], v[154:157], v[196:199], v[42:45]
	v_mfma_f32_16x16x32_bf16 v[30:33], v[142:145], v[204:207], v[30:33]
	v_mfma_f32_16x16x32_bf16 v[26:29], v[154:157], v[204:207], v[26:29]
	v_mfma_f32_16x16x32_bf16 v[14:17], v[142:145], v[212:215], v[14:17]
	v_mfma_f32_16x16x32_bf16 v[10:13], v[154:157], v[212:215], v[10:13]
	v_mfma_f32_16x16x32_bf16 v[62:65], v[146:149], v[192:195], v[62:65]
	v_mfma_f32_16x16x32_bf16 v[58:61], v[158:161], v[192:195], v[58:61]
	v_mfma_f32_16x16x32_bf16 v[46:49], v[146:149], v[200:203], v[46:49]
	v_mfma_f32_16x16x32_bf16 v[42:45], v[158:161], v[200:203], v[42:45]
	v_mfma_f32_16x16x32_bf16 v[30:33], v[146:149], v[208:211], v[30:33]
	v_mfma_f32_16x16x32_bf16 v[26:29], v[158:161], v[208:211], v[26:29]
	v_mfma_f32_16x16x32_bf16 v[14:17], v[146:149], v[216:219], v[14:17]
	v_mfma_f32_16x16x32_bf16 v[10:13], v[158:161], v[216:219], v[10:13]
	v_mfma_f32_16x16x32_bf16 v[54:57], v[162:165], v[188:191], v[54:57]
	v_mfma_f32_16x16x32_bf16 v[50:53], v[180:183], v[188:191], v[50:53]
	v_mfma_f32_16x16x32_bf16 v[38:41], v[162:165], v[196:199], v[38:41]
	v_mfma_f32_16x16x32_bf16 v[34:37], v[180:183], v[196:199], v[34:37]
	v_mfma_f32_16x16x32_bf16 v[22:25], v[162:165], v[204:207], v[22:25]
	v_mfma_f32_16x16x32_bf16 v[18:21], v[180:183], v[204:207], v[18:21]
	v_mfma_f32_16x16x32_bf16 v[6:9], v[162:165], v[212:215], v[6:9]
	v_mfma_f32_16x16x32_bf16 v[2:5], v[180:183], v[212:215], v[2:5]
	v_mfma_f32_16x16x32_bf16 v[54:57], v[166:169], v[192:195], v[54:57]
	v_mfma_f32_16x16x32_bf16 v[50:53], v[184:187], v[192:195], v[50:53]
	v_mfma_f32_16x16x32_bf16 v[38:41], v[166:169], v[200:203], v[38:41]
	v_mfma_f32_16x16x32_bf16 v[34:37], v[184:187], v[200:203], v[34:37]
	v_mfma_f32_16x16x32_bf16 v[22:25], v[166:169], v[208:211], v[22:25]
	v_mfma_f32_16x16x32_bf16 v[18:21], v[184:187], v[208:211], v[18:21]
	v_mfma_f32_16x16x32_bf16 v[6:9], v[166:169], v[216:219], v[6:9]
	v_mfma_f32_16x16x32_bf16 v[2:5], v[184:187], v[216:219], v[2:5]
	s_barrier
	s_add_i32 s89, s89, 2
	s_add_u32 s85, s85, 0x100
	s_addc_u32 s88, s88, 0
	s_add_u32 s50, s50, 0x100
	s_addc_u32 s51, s51, 0
	s_cmp_gt_u32 s89, 13
	s_cbranch_scc0 .LBB0_792
	s_setprio 0
	s_and_b64 vcc, exec, s[34:35]
	s_movk_i32 s88, 0x7f
	v_readlane_b32 s89, v255, 19
	s_mov_b32 s84, 0xbcf5c28f
	s_cbranch_vccz .LBB0_795
	s_barrier

; #define PG8_STAGE(bufoff, gbase, voff) do { _Pragma("unroll") for (int _i = 0; _i < 2; ++_i) \
;         __builtin_amdgcn_global_load_lds((const unsigned*)((const char*)(gbase) + (voff)[_i]), (LAS unsigned*)(lds + (bufoff) + ldsw + _i * 8192), 16, 0, 0); } while (0)
; #define PG8_LDA(dst, b, h) do { _Pragma("unroll") for (int m = 0; m < 4; ++m) _Pragma("unroll") for (int k = 0; k < 2; ++k) dst[m][k] = *(const LAS bf16x8*)(lds + PG8_SA(b, h) + aoff + m * 2048 + k * 1024); } while (0)
; #define PG8_LDB(dst, b, h) do { _Pragma("unroll") for (int n = 0; n < 2; ++n) _Pragma("unroll") for (int k = 0; k < 2; ++k) dst[n][k] = *(const LAS bf16x8*)(lds + PG8_SB(b, h) + boff + n * 2048 + k * 1024); } while (0)
; #define PG8_MMA(ai, bj, At, Bt) do { __builtin_amdgcn_s_setprio(1); _Pragma("unroll") for (int m = 0; m < 4; ++m) _Pragma("unroll") for (int n = 0; n < 2; ++n) _Pragma("unroll") for (int k = 0; k < 2; ++k) \
;         acc[ai][bj][m][n] = __builtin_amdgcn_mfma_f32_16x16x32_bf16(Bt[n][k], At[m][k], acc[ai][bj][m][n], 0, 0, 0); __builtin_amdgcn_s_setprio(0); } while (0)
; template <class Epi>
; DI void gemm_phase(LAS unsigned char* lds, const Gemm g, const StaticOrder& S, const Epi& E) {
;     ...
;         const bool has_next = S.next(ui + 1, nxt);
;         const char* nA = has_next ? (const char*)g.A + (size_t)nxt.pm * tstepA + (size_t)nxt.pn * g.a_pn_off * 2 : cA; const char* nB = has_next ? (const char*)g.Bt + (size_t)nxt.pn * tstepB : cB;
;         for (int t = 0; t < nt; t += 2) {
;             const bool last = (t == nt - 2);
;             const char* a1 = cA + (size_t)(t + 1) * kstepA;
;             const char* a2 = last ? nA : cA + (size_t)(t + 2) * kstepA; const char* b2 = last ? nB : cB + (size_t)(t + 2) * kstepB;
;             const char* a3 = a2 + kstepA; const char* b3 = b2 + kstepB;
;             PG8_LDB(B0, 0, 0); PG8_LDB(B1, 0, 1); PG8_SCHED; PG8_LDA(At, 0, 0); PG8_STAGE(PG8_SA(1, 1), a1 + hstepA, voffA);
;             PG8_WAIT_V(8); PG8_WAIT_L(0); PG8_BAR; PG8_MMA(0, 0, At, B0); PG8_MMA(0, 1, At, B1); PG8_BAR; PG8_SCHED;
;     ...
; #pragma unroll
;         for (int a = 0; a < 2; ++a)
; #pragma unroll
;             for (int b = 0; b < 2; ++b)
; #pragma unroll
;                 for (int m = 0; m < 4; ++m)
; #pragma unroll
;                     for (int n = 0; n < 2; ++n) acc[a][b][m][n] = (f32x4){0.f, 0.f, 0.f, 0.f};
;         cur = nxt; cA = nA; cB = nB; ++ui;
.LBB0_979:
	s_ashr_i32 s51, s50, 31
	s_lshl_b64 s[22:23], s[50:51], 19
	s_add_u32 s88, s74, s22
	s_addc_u32 s89, s75, s23
	s_and_b64 s[22:23], s[42:43], exec
	s_cselect_b32 s24, s89, s47
	s_cselect_b32 s45, s88, s46
	s_ashr_i32 s37, s36, 31
	s_lshl_b64 s[22:23], s[36:37], 19
	s_add_u32 s92, s84, s22
	s_addc_u32 s93, s85, s23
	s_and_b64 s[22:23], s[42:43], exec
	s_cselect_b32 s37, s93, s19
	s_cselect_b32 s48, s92, s18
	s_add_u32 s49, s18, 0x100
	s_addc_u32 s51, s19, 0
	s_add_u32 s46, s46, 0x40080
	v_mov_b32_e32 v2, 0
	s_addc_u32 s47, s47, 0
	s_mov_b32 s66, -2
	v_mov_b32_e32 v3, v2
	v_mov_b32_e32 v4, v2
	v_mov_b32_e32 v5, v2
	v_mov_b32_e32 v6, v2
	v_mov_b32_e32 v7, v2
	v_mov_b32_e32 v8, v2
	v_mov_b32_e32 v9, v2
	v_mov_b32_e32 v18, v2
	v_mov_b32_e32 v19, v2
	v_mov_b32_e32 v20, v2
	v_mov_b32_e32 v21, v2
	v_mov_b32_e32 v22, v2
	v_mov_b32_e32 v23, v2
	v_mov_b32_e32 v24, v2
	v_mov_b32_e32 v25, v2
	v_mov_b32_e32 v34, v2
	v_mov_b32_e32 v35, v2
	v_mov_b32_e32 v36, v2
	v_mov_b32_e32 v37, v2
	v_mov_b32_e32 v38, v2
	v_mov_b32_e32 v39, v2
	v_mov_b32_e32 v40, v2
	v_mov_b32_e32 v41, v2
	v_mov_b32_e32 v50, v2
	v_mov_b32_e32 v51, v2
	v_mov_b32_e32 v52, v2
	v_mov_b32_e32 v53, v2
	v_mov_b32_e32 v54, v2
	v_mov_b32_e32 v55, v2
	v_mov_b32_e32 v56, v2
	v_mov_b32_e32 v57, v2
	v_mov_b32_e32 v10, v2
	v_mov_b32_e32 v11, v2
	v_mov_b32_e32 v12, v2
	v_mov_b32_e32 v13, v2
	v_mov_b32_e32 v14, v2
	v_mov_b32_e32 v15, v2
	v_mov_b32_e32 v16, v2
	v_mov_b32_e32 v17, v2
	v_mov_b32_e32 v26, v2
	v_mov_b32_e32 v27, v2
	v_mov_b32_e32 v28, v2
	v_mov_b32_e32 v29, v2
	v_mov_b32_e32 v30, v2
	v_mov_b32_e32 v31, v2
	v_mov_b32_e32 v32, v2
	v_mov_b32_e32 v33, v2
	v_mov_b32_e32 v42, v2
	v_mov_b32_e32 v43, v2
	v_mov_b32_e32 v44, v2
	v_mov_b32_e32 v45, v2
	v_mov_b32_e32 v46, v2
	v_mov_b32_e32 v47, v2
	v_mov_b32_e32 v48, v2
	v_mov_b32_e32 v49, v2
	v_mov_b32_e32 v58, v2
	v_mov_b32_e32 v59, v2
	v_mov_b32_e32 v60, v2
	v_mov_b32_e32 v61, v2
	v_mov_b32_e32 v62, v2
	v_mov_b32_e32 v63, v2
	v_mov_b32_e32 v64, v2
	v_mov_b32_e32 v65, v2
	v_mov_b32_e32 v66, v2
	v_mov_b32_e32 v67, v2
	v_mov_b32_e32 v68, v2
	v_mov_b32_e32 v69, v2
	v_mov_b32_e32 v70, v2
	v_mov_b32_e32 v71, v2
	v_mov_b32_e32 v72, v2
	v_mov_b32_e32 v73, v2
	v_mov_b32_e32 v82, v2
	v_mov_b32_e32 v83, v2
	v_mov_b32_e32 v84, v2
	v_mov_b32_e32 v85, v2
	v_mov_b32_e32 v86, v2
	v_mov_b32_e32 v87, v2
	v_mov_b32_e32 v88, v2
	v_mov_b32_e32 v89, v2
	v_mov_b32_e32 v98, v2
	v_mov_b32_e32 v99, v2
	v_mov_b32_e32 v100, v2
	v_mov_b32_e32 v101, v2
	v_mov_b32_e32 v102, v2
	v_mov_b32_e32 v103, v2
	v_mov_b32_e32 v104, v2
	v_mov_b32_e32 v105, v2
	v_mov_b32_e32 v114, v2
	v_mov_b32_e32 v115, v2
	v_mov_b32_e32 v116, v2
	v_mov_b32_e32 v117, v2
	v_mov_b32_e32 v118, v2
	v_mov_b32_e32 v119, v2
	v_mov_b32_e32 v120, v2
	v_mov_b32_e32 v121, v2
	v_mov_b32_e32 v74, v2
	v_mov_b32_e32 v75, v2
	v_mov_b32_e32 v76, v2
	v_mov_b32_e32 v77, v2
	v_mov_b32_e32 v78, v2
	v_mov_b32_e32 v79, v2
	v_mov_b32_e32 v80, v2
	v_mov_b32_e32 v81, v2
	v_mov_b32_e32 v90, v2
	v_mov_b32_e32 v91, v2
	v_mov_b32_e32 v92, v2
	v_mov_b32_e32 v93, v2
	v_mov_b32_e32 v94, v2
	v_mov_b32_e32 v95, v2
	v_mov_b32_e32 v96, v2
	v_mov_b32_e32 v97, v2
	v_mov_b32_e32 v106, v2
	v_mov_b32_e32 v107, v2
	v_mov_b32_e32 v108, v2
	v_mov_b32_e32 v109, v2
	v_mov_b32_e32 v110, v2
	v_mov_b32_e32 v111, v2
	v_mov_b32_e32 v112, v2
	v_mov_b32_e32 v113, v2
	v_mov_b32_e32 v122, v2
	v_mov_b32_e32 v123, v2
	v_mov_b32_e32 v124, v2
	v_mov_b32_e32 v125, v2
	v_mov_b32_e32 v126, v2
	v_mov_b32_e32 v127, v2
	v_mov_b32_e32 v128, v2
	v_mov_b32_e32 v129, v2
	v_readfirstlane_b32 s2, v220
	s_lshr_b32 s2, s2, 8
	s_cmp_eq_u32 s2, 0
	s_cbranch_scc1 .Lsprio_4
	s_setprio 1
.Lsprio_4:
.LBB0_980:
	s_add_u32 s2, s46, 0xfffc0080
	s_addc_u32 s15, s47, -1
	s_add_i32 s25, 0, 0x10000
	s_cmp_eq_u32 s66, 12
	s_cselect_b32 s23, s24, s15
	s_cselect_b32 s22, s45, s2
	s_cselect_b32 s19, s37, s51
	s_cselect_b32 s18, s48, s49
	s_add_i32 s2, 0, 0x14000
	v_add_u32_e32 v154, s25, v159
	v_add_u32_e32 v161, s2, v159
	ds_read_b128 v[130:133], v154
	ds_read_b128 v[146:149], v154 offset:1024
	ds_read_b128 v[150:153], v154 offset:2048
	ds_read_b128 v[154:157], v154 offset:3072
	ds_read_b128 v[162:165], v161
	ds_read_b128 v[166:169], v161 offset:1024
	ds_read_b128 v[180:183], v161 offset:2048
	ds_read_b128 v[184:187], v161 offset:3072
	v_lshl_add_u64 v[170:171], s[46:47], 0, v[144:145]
	s_add_i32 m0, s39, 0xc000
	ds_read_b128 v[188:191], v160
	ds_read_b128 v[192:195], v160 offset:1024
	ds_read_b128 v[196:199], v160 offset:2048
	ds_read_b128 v[200:203], v160 offset:3072
	ds_read_b128 v[204:207], v160 offset:4096
	ds_read_b128 v[208:211], v160 offset:5120
	ds_read_b128 v[212:215], v160 offset:6144
	ds_read_b128 v[216:219], v160 offset:7168
	global_load_lds_dwordx4 v[170:171], off
	v_lshl_add_u64 v[170:171], s[46:47], 0, v[142:143]
	s_add_i32 m0, s39, 0xe000
	s_nop 0
	global_load_lds_dwordx4 v[170:171], off
	s_waitcnt vmcnt(8)
	s_waitcnt lgkmcnt(0)
	s_barrier
; #define PG8_STAGE(bufoff, gbase, voff) do { _Pragma("unroll") for (int _i = 0; _i < 2; ++_i) \
;         __builtin_amdgcn_global_load_lds((const unsigned*)((const char*)(gbase) + (voff)[_i]), (LAS unsigned*)(lds + (bufoff) + ldsw + _i * 8192), 16, 0, 0); } while (0)
; #define PG8_LDA(dst, b, h) do { _Pragma("unroll") for (int m = 0; m < 4; ++m) _Pragma("unroll") for (int k = 0; k < 2; ++k) dst[m][k] = *(const LAS bf16x8*)(lds + PG8_SA(b, h) + aoff + m * 2048 + k * 1024); } while (0)
; #define PG8_MMA(ai, bj, At, Bt) do { __builtin_amdgcn_s_setprio(1); _Pragma("unroll") for (int m = 0; m < 4; ++m) _Pragma("unroll") for (int n = 0; n < 2; ++n) _Pragma("unroll") for (int k = 0; k < 2; ++k) \
;         acc[ai][bj][m][n] = __builtin_amdgcn_mfma_f32_16x16x32_bf16(Bt[n][k], At[m][k], acc[ai][bj][m][n], 0, 0, 0); __builtin_amdgcn_s_setprio(0); } while (0)
; #define PG8_WAIT_V(n) asm volatile("s_waitcnt vmcnt(" #n ")" ::: "memory")
; #define PG8_WAIT_L(n) asm volatile("s_waitcnt lgkmcnt(" #n ")" ::: "memory")
; #define PG8_BAR __builtin_amdgcn_s_barrier()
; #define PG8_SCHED __builtin_amdgcn_sched_barrier(0)
; template <class Epi>
; DI void gemm_phase(LAS unsigned char* lds, const Gemm g, const StaticOrder& S, const Epi& E) {
;     ...
;             PG8_WAIT_V(8); PG8_WAIT_L(0); PG8_BAR; PG8_MMA(0, 0, At, B0); PG8_MMA(0, 1, At, B1); PG8_BAR; PG8_SCHED;
;             PG8_LDA(At, 0, 1); PG8_STAGE(PG8_SB(0, 0), b2, voffB); PG8_STAGE(PG8_SB(0, 1), b2 + hstepB, voffB); PG8_STAGE(PG8_SA(0, 0), a2, voffA);
;             PG8_WAIT_V(8); PG8_WAIT_L(0); PG8_BAR; PG8_MMA(1, 0, At, B0); PG8_MMA(1, 1, At, B1); PG8_BAR; PG8_SCHED;
	s_waitcnt lgkmcnt(0)
	v_mfma_f32_16x16x32_bf16 v[126:129], v[130:133], v[188:191], v[126:129]
	v_mfma_f32_16x16x32_bf16 v[122:125], v[150:153], v[188:191], v[122:125]
	v_mfma_f32_16x16x32_bf16 v[110:113], v[130:133], v[196:199], v[110:113]
	v_mfma_f32_16x16x32_bf16 v[106:109], v[150:153], v[196:199], v[106:109]
	v_mfma_f32_16x16x32_bf16 v[94:97], v[130:133], v[204:207], v[94:97]
	v_mfma_f32_16x16x32_bf16 v[90:93], v[150:153], v[204:207], v[90:93]
	v_mfma_f32_16x16x32_bf16 v[78:81], v[130:133], v[212:215], v[78:81]
	v_mfma_f32_16x16x32_bf16 v[74:77], v[150:153], v[212:215], v[74:77]
	v_mfma_f32_16x16x32_bf16 v[126:129], v[146:149], v[192:195], v[126:129]
	v_mfma_f32_16x16x32_bf16 v[122:125], v[154:157], v[192:195], v[122:125]
	v_mfma_f32_16x16x32_bf16 v[110:113], v[146:149], v[200:203], v[110:113]
	v_mfma_f32_16x16x32_bf16 v[106:109], v[154:157], v[200:203], v[106:109]
	v_mfma_f32_16x16x32_bf16 v[94:97], v[146:149], v[208:211], v[94:97]
	v_mfma_f32_16x16x32_bf16 v[90:93], v[154:157], v[208:211], v[90:93]
	v_mfma_f32_16x16x32_bf16 v[78:81], v[146:149], v[216:219], v[78:81]
	v_mfma_f32_16x16x32_bf16 v[74:77], v[154:157], v[216:219], v[74:77]
	v_mfma_f32_16x16x32_bf16 v[118:121], v[162:165], v[188:191], v[118:121]
	v_mfma_f32_16x16x32_bf16 v[114:117], v[180:183], v[188:191], v[114:117]
	v_mfma_f32_16x16x32_bf16 v[102:105], v[162:165], v[196:199], v[102:105]
	v_mfma_f32_16x16x32_bf16 v[98:101], v[180:183], v[196:199], v[98:101]
	v_mfma_f32_16x16x32_bf16 v[86:89], v[162:165], v[204:207], v[86:89]
	v_mfma_f32_16x16x32_bf16 v[82:85], v[180:183], v[204:207], v[82:85]
	v_mfma_f32_16x16x32_bf16 v[70:73], v[162:165], v[212:215], v[70:73]
	v_mfma_f32_16x16x32_bf16 v[66:69], v[180:183], v[212:215], v[66:69]
	v_mfma_f32_16x16x32_bf16 v[118:121], v[166:169], v[192:195], v[118:121]
	v_mfma_f32_16x16x32_bf16 v[114:117], v[184:187], v[192:195], v[114:117]
	v_mfma_f32_16x16x32_bf16 v[102:105], v[166:169], v[200:203], v[102:105]
	v_mfma_f32_16x16x32_bf16 v[98:101], v[184:187], v[200:203], v[98:101]
	v_mfma_f32_16x16x32_bf16 v[86:89], v[166:169], v[208:211], v[86:89]
	v_mfma_f32_16x16x32_bf16 v[82:85], v[184:187], v[208:211], v[82:85]
	v_mfma_f32_16x16x32_bf16 v[70:73], v[166:169], v[216:219], v[70:73]
	v_mfma_f32_16x16x32_bf16 v[66:69], v[184:187], v[216:219], v[66:69]
	s_barrier
	s_add_i32 s15, s25, s90
	v_lshl_add_u64 v[170:171], s[18:19], 0, v[136:137]
	s_mov_b32 m0, s15
	ds_read_b128 v[188:191], v160 offset:16384
	ds_read_b128 v[192:195], v160 offset:17408
	ds_read_b128 v[196:199], v160 offset:18432
	ds_read_b128 v[200:203], v160 offset:19456
	ds_read_b128 v[204:207], v160 offset:20480
	ds_read_b128 v[208:211], v160 offset:21504
	ds_read_b128 v[212:215], v160 offset:22528
	ds_read_b128 v[216:219], v160 offset:23552
	global_load_lds_dwordx4 v[170:171], off
	s_add_i32 m0, s15, 0x2000
	s_add_u32 s68, s18, 0x40000
	v_lshl_add_u64 v[238:239], s[18:19], 0, v[140:141]
	s_addc_u32 s69, s19, 0
	s_add_i32 s2, s2, s90
	global_load_lds_dwordx4 v[238:239], off
	v_lshl_add_u64 v[240:241], s[68:69], 0, v[136:137]
	s_mov_b32 m0, s2
	v_lshl_add_u64 v[242:243], s[22:23], 0, v[138:139]
	global_load_lds_dwordx4 v[240:241], off
	v_lshl_add_u64 v[240:241], s[68:69], 0, v[140:141]
	s_add_i32 m0, s2, 0x2000
	s_nop 0
	global_load_lds_dwordx4 v[240:241], off
	v_lshl_add_u64 v[240:241], s[22:23], 0, v[134:135]
	s_mov_b32 m0, s39
	s_nop 0
	global_load_lds_dwordx4 v[240:241], off
	s_mov_b32 m0, s91
	s_nop 0
	global_load_lds_dwordx4 v[242:243], off
	s_waitcnt vmcnt(8)
	s_waitcnt lgkmcnt(0)
	s_barrier
	s_waitcnt lgkmcnt(0)
	v_mfma_f32_16x16x32_bf16 v[62:65], v[130:133], v[188:191], v[62:65]
	v_mfma_f32_16x16x32_bf16 v[58:61], v[150:153], v[188:191], v[58:61]
	v_mfma_f32_16x16x32_bf16 v[46:49], v[130:133], v[196:199], v[46:49]
	v_mfma_f32_16x16x32_bf16 v[42:45], v[150:153], v[196:199], v[42:45]
	v_mfma_f32_16x16x32_bf16 v[30:33], v[130:133], v[204:207], v[30:33]
	v_mfma_f32_16x16x32_bf16 v[26:29], v[150:153], v[204:207], v[26:29]
	v_mfma_f32_16x16x32_bf16 v[14:17], v[130:133], v[212:215], v[14:17]
	v_mfma_f32_16x16x32_bf16 v[10:13], v[150:153], v[212:215], v[10:13]
	v_mfma_f32_16x16x32_bf16 v[62:65], v[146:149], v[192:195], v[62:65]
	v_mfma_f32_16x16x32_bf16 v[58:61], v[154:157], v[192:195], v[58:61]
	v_mfma_f32_16x16x32_bf16 v[46:49], v[146:149], v[200:203], v[46:49]
	v_mfma_f32_16x16x32_bf16 v[42:45], v[154:157], v[200:203], v[42:45]
	v_mfma_f32_16x16x32_bf16 v[30:33], v[146:149], v[208:211], v[30:33]
	v_mfma_f32_16x16x32_bf16 v[26:29], v[154:157], v[208:211], v[26:29]
	v_mfma_f32_16x16x32_bf16 v[14:17], v[146:149], v[216:219], v[14:17]
	v_mfma_f32_16x16x32_bf16 v[10:13], v[154:157], v[216:219], v[10:13]
	v_mfma_f32_16x16x32_bf16 v[54:57], v[162:165], v[188:191], v[54:57]
	v_mfma_f32_16x16x32_bf16 v[50:53], v[180:183], v[188:191], v[50:53]
	v_mfma_f32_16x16x32_bf16 v[38:41], v[162:165], v[196:199], v[38:41]
	v_mfma_f32_16x16x32_bf16 v[34:37], v[180:183], v[196:199], v[34:37]
	v_mfma_f32_16x16x32_bf16 v[22:25], v[162:165], v[204:207], v[22:25]
	v_mfma_f32_16x16x32_bf16 v[18:21], v[180:183], v[204:207], v[18:21]
	v_mfma_f32_16x16x32_bf16 v[6:9], v[162:165], v[212:215], v[6:9]
	v_mfma_f32_16x16x32_bf16 v[2:5], v[180:183], v[212:215], v[2:5]
	v_mfma_f32_16x16x32_bf16 v[54:57], v[166:169], v[192:195], v[54:57]
	v_mfma_f32_16x16x32_bf16 v[50:53], v[184:187], v[192:195], v[50:53]
	v_mfma_f32_16x16x32_bf16 v[38:41], v[166:169], v[200:203], v[38:41]
	v_mfma_f32_16x16x32_bf16 v[34:37], v[184:187], v[200:203], v[34:37]
	v_mfma_f32_16x16x32_bf16 v[22:25], v[166:169], v[208:211], v[22:25]
	v_mfma_f32_16x16x32_bf16 v[18:21], v[184:187], v[208:211], v[18:21]
	v_mfma_f32_16x16x32_bf16 v[6:9], v[166:169], v[216:219], v[6:9]
	v_mfma_f32_16x16x32_bf16 v[2:5], v[184:187], v[216:219], v[2:5]
	s_barrier
; #define PG8_STAGE(bufoff, gbase, voff) do { _Pragma("unroll") for (int _i = 0; _i < 2; ++_i) \
;         __builtin_amdgcn_global_load_lds((const unsigned*)((const char*)(gbase) + (voff)[_i]), (LAS unsigned*)(lds + (bufoff) + ldsw + _i * 8192), 16, 0, 0); } while (0)
; #define PG8_LDA(dst, b, h) do { _Pragma("unroll") for (int m = 0; m < 4; ++m) _Pragma("unroll") for (int k = 0; k < 2; ++k) dst[m][k] = *(const LAS bf16x8*)(lds + PG8_SA(b, h) + aoff + m * 2048 + k * 1024); } while (0)
; #define PG8_LDB(dst, b, h) do { _Pragma("unroll") for (int n = 0; n < 2; ++n) _Pragma("unroll") for (int k = 0; k < 2; ++k) dst[n][k] = *(const LAS bf16x8*)(lds + PG8_SB(b, h) + boff + n * 2048 + k * 1024); } while (0)
; #define PG8_MMA(ai, bj, At, Bt) do { __builtin_amdgcn_s_setprio(1); _Pragma("unroll") for (int m = 0; m < 4; ++m) _Pragma("unroll") for (int n = 0; n < 2; ++n) _Pragma("unroll") for (int k = 0; k < 2; ++k) \
;         acc[ai][bj][m][n] = __builtin_amdgcn_mfma_f32_16x16x32_bf16(Bt[n][k], At[m][k], acc[ai][bj][m][n], 0, 0, 0); __builtin_amdgcn_s_setprio(0); } while (0)
; #define PG8_WAIT_V(n) asm volatile("s_waitcnt vmcnt(" #n ")" ::: "memory")
; #define PG8_WAIT_L(n) asm volatile("s_waitcnt lgkmcnt(" #n ")" ::: "memory")
; #define PG8_BAR __builtin_amdgcn_s_barrier()
; #define PG8_SCHED __builtin_amdgcn_sched_barrier(0)
; template <class Epi>
; DI void gemm_phase(LAS unsigned char* lds, const Gemm g, const StaticOrder& S, const Epi& E) {
;     ...
;             PG8_LDB(B0, 1, 0); PG8_LDB(B1, 1, 1); PG8_SCHED; PG8_LDA(At, 1, 0); PG8_STAGE(PG8_SA(0, 1), a2 + hstepA, voffA);
;             PG8_WAIT_V(8); PG8_WAIT_L(0); PG8_BAR; PG8_MMA(0, 0, At, B0); PG8_MMA(0, 1, At, B1); PG8_BAR; PG8_SCHED;
	s_add_i32 s2, 0, 0x18000
	s_add_i32 s15, 0, 0x1c000
	v_add_u32_e32 v154, s2, v159
	v_add_u32_e32 v161, s15, v159
	ds_read_b128 v[130:133], v154
	ds_read_b128 v[146:149], v154 offset:1024
	ds_read_b128 v[150:153], v154 offset:2048
	ds_read_b128 v[154:157], v154 offset:3072
	ds_read_b128 v[162:165], v161
	ds_read_b128 v[166:169], v161 offset:1024
	ds_read_b128 v[180:183], v161 offset:2048
	ds_read_b128 v[184:187], v161 offset:3072
	s_add_u32 s22, s22, 0x40000
	s_addc_u32 s23, s23, 0
	s_mov_b32 m0, s94
	v_lshl_add_u64 v[244:245], s[22:23], 0, v[134:135]
	ds_read_b128 v[188:191], v160 offset:32768
	ds_read_b128 v[192:195], v160 offset:33792
	ds_read_b128 v[196:199], v160 offset:34816
	ds_read_b128 v[200:203], v160 offset:35840
	ds_read_b128 v[204:207], v160 offset:36864
	ds_read_b128 v[208:211], v160 offset:37888
	ds_read_b128 v[212:215], v160 offset:38912
	ds_read_b128 v[216:219], v160 offset:39936
	global_load_lds_dwordx4 v[244:245], off
	v_lshl_add_u64 v[244:245], s[22:23], 0, v[138:139]
	s_mov_b32 m0, s95
	s_nop 0
	global_load_lds_dwordx4 v[244:245], off
	s_waitcnt vmcnt(8)
	s_waitcnt lgkmcnt(0)
	s_barrier
	s_waitcnt lgkmcnt(0)
	v_mfma_f32_16x16x32_bf16 v[126:129], v[130:133], v[188:191], v[126:129]
	v_mfma_f32_16x16x32_bf16 v[122:125], v[150:153], v[188:191], v[122:125]
	v_mfma_f32_16x16x32_bf16 v[110:113], v[130:133], v[196:199], v[110:113]
	v_mfma_f32_16x16x32_bf16 v[106:109], v[150:153], v[196:199], v[106:109]
	v_mfma_f32_16x16x32_bf16 v[94:97], v[130:133], v[204:207], v[94:97]
	v_mfma_f32_16x16x32_bf16 v[90:93], v[150:153], v[204:207], v[90:93]
	v_mfma_f32_16x16x32_bf16 v[78:81], v[130:133], v[212:215], v[78:81]
	v_mfma_f32_16x16x32_bf16 v[74:77], v[150:153], v[212:215], v[74:77]
	v_mfma_f32_16x16x32_bf16 v[126:129], v[146:149], v[192:195], v[126:129]
	v_mfma_f32_16x16x32_bf16 v[122:125], v[154:157], v[192:195], v[122:125]
	v_mfma_f32_16x16x32_bf16 v[110:113], v[146:149], v[200:203], v[110:113]
	v_mfma_f32_16x16x32_bf16 v[106:109], v[154:157], v[200:203], v[106:109]
	v_mfma_f32_16x16x32_bf16 v[94:97], v[146:149], v[208:211], v[94:97]
	v_mfma_f32_16x16x32_bf16 v[90:93], v[154:157], v[208:211], v[90:93]
	v_mfma_f32_16x16x32_bf16 v[78:81], v[146:149], v[216:219], v[78:81]
	v_mfma_f32_16x16x32_bf16 v[74:77], v[154:157], v[216:219], v[74:77]
	v_mfma_f32_16x16x32_bf16 v[118:121], v[162:165], v[188:191], v[118:121]
	v_mfma_f32_16x16x32_bf16 v[114:117], v[180:183], v[188:191], v[114:117]
	v_mfma_f32_16x16x32_bf16 v[102:105], v[162:165], v[196:199], v[102:105]
	v_mfma_f32_16x16x32_bf16 v[98:101], v[180:183], v[196:199], v[98:101]
	v_mfma_f32_16x16x32_bf16 v[86:89], v[162:165], v[204:207], v[86:89]
	v_mfma_f32_16x16x32_bf16 v[82:85], v[180:183], v[204:207], v[82:85]
	v_mfma_f32_16x16x32_bf16 v[70:73], v[162:165], v[212:215], v[70:73]
	v_mfma_f32_16x16x32_bf16 v[66:69], v[180:183], v[212:215], v[66:69]
	v_mfma_f32_16x16x32_bf16 v[118:121], v[166:169], v[192:195], v[118:121]
	v_mfma_f32_16x16x32_bf16 v[114:117], v[184:187], v[192:195], v[114:117]
	v_mfma_f32_16x16x32_bf16 v[102:105], v[166:169], v[200:203], v[102:105]
	v_mfma_f32_16x16x32_bf16 v[98:101], v[184:187], v[200:203], v[98:101]
	v_mfma_f32_16x16x32_bf16 v[86:89], v[166:169], v[208:211], v[86:89]
	v_mfma_f32_16x16x32_bf16 v[82:85], v[184:187], v[208:211], v[82:85]
	v_mfma_f32_16x16x32_bf16 v[70:73], v[166:169], v[216:219], v[70:73]
	v_mfma_f32_16x16x32_bf16 v[66:69], v[184:187], v[216:219], v[66:69]
	s_barrier
; #define PG8_STAGE(bufoff, gbase, voff) do { _Pragma("unroll") for (int _i = 0; _i < 2; ++_i) \
;         __builtin_amdgcn_global_load_lds((const unsigned*)((const char*)(gbase) + (voff)[_i]), (LAS unsigned*)(lds + (bufoff) + ldsw + _i * 8192), 16, 0, 0); } while (0)
; #define PG8_LDA(dst, b, h) do { _Pragma("unroll") for (int m = 0; m < 4; ++m) _Pragma("unroll") for (int k = 0; k < 2; ++k) dst[m][k] = *(const LAS bf16x8*)(lds + PG8_SA(b, h) + aoff + m * 2048 + k * 1024); } while (0)
; #define PG8_MMA(ai, bj, At, Bt) do { __builtin_amdgcn_s_setprio(1); _Pragma("unroll") for (int m = 0; m < 4; ++m) _Pragma("unroll") for (int n = 0; n < 2; ++n) _Pragma("unroll") for (int k = 0; k < 2; ++k) \
;         acc[ai][bj][m][n] = __builtin_amdgcn_mfma_f32_16x16x32_bf16(Bt[n][k], At[m][k], acc[ai][bj][m][n], 0, 0, 0); __builtin_amdgcn_s_setprio(0); } while (0)
; #define PG8_WAIT_V(n) asm volatile("s_waitcnt vmcnt(" #n ")" ::: "memory")
; #define PG8_WAIT_L(n) asm volatile("s_waitcnt lgkmcnt(" #n ")" ::: "memory")
; #define PG8_BAR __builtin_amdgcn_s_barrier()
; #define PG8_SCHED __builtin_amdgcn_sched_barrier(0)
; template <class Epi>
; DI void gemm_phase(LAS unsigned char* lds, const Gemm g, const StaticOrder& S, const Epi& E) {
;     ...
;             PG8_LDA(At, 1, 1); PG8_STAGE(PG8_SB(1, 0), b3, voffB); PG8_STAGE(PG8_SB(1, 1), b3 + hstepB, voffB); PG8_STAGE(PG8_SA(1, 0), a3, voffA);
;             PG8_WAIT_V(8); PG8_WAIT_L(0); PG8_BAR; PG8_MMA(1, 0, At, B0); PG8_MMA(1, 1, At, B1); PG8_BAR; PG8_SCHED;
;         }
;         if (wr == 0) PG8_BAR;
	s_add_i32 s2, s2, s90
	v_lshl_add_u64 v[170:171], v[170:171], 0, s[6:7]
	s_mov_b32 m0, s2
	ds_read_b128 v[188:191], v160 offset:49152
	ds_read_b128 v[192:195], v160 offset:50176
	ds_read_b128 v[196:199], v160 offset:51200
	ds_read_b128 v[200:203], v160 offset:52224
	ds_read_b128 v[204:207], v160 offset:53248
	ds_read_b128 v[208:211], v160 offset:54272
	ds_read_b128 v[212:215], v160 offset:55296
	ds_read_b128 v[216:219], v160 offset:56320
	global_load_lds_dwordx4 v[170:171], off
	s_add_i32 m0, s2, 0x2000
	s_add_u32 s18, s18, 0x40080
	v_lshl_add_u64 v[170:171], v[238:239], 0, s[6:7]
	s_addc_u32 s19, s19, 0
	s_add_i32 s2, s15, s90
	global_load_lds_dwordx4 v[170:171], off
	v_lshl_add_u64 v[170:171], s[18:19], 0, v[136:137]
	s_mov_b32 m0, s2
	s_nop 0
	global_load_lds_dwordx4 v[170:171], off
	v_lshl_add_u64 v[170:171], s[18:19], 0, v[140:141]
	s_add_i32 m0, s2, 0x2000
	s_nop 0
	global_load_lds_dwordx4 v[170:171], off
	v_lshl_add_u64 v[170:171], v[240:241], 0, s[6:7]
	s_mov_b32 m0, s96
	s_nop 0
	global_load_lds_dwordx4 v[170:171], off
	v_lshl_add_u64 v[170:171], v[242:243], 0, s[6:7]
	s_mov_b32 m0, s97
	s_nop 0
	global_load_lds_dwordx4 v[170:171], off
	s_waitcnt vmcnt(8)
	s_waitcnt lgkmcnt(0)
	s_barrier
	s_waitcnt lgkmcnt(0)
	v_mfma_f32_16x16x32_bf16 v[62:65], v[130:133], v[188:191], v[62:65]
	v_mfma_f32_16x16x32_bf16 v[58:61], v[150:153], v[188:191], v[58:61]
	v_mfma_f32_16x16x32_bf16 v[46:49], v[130:133], v[196:199], v[46:49]
	v_mfma_f32_16x16x32_bf16 v[42:45], v[150:153], v[196:199], v[42:45]
	v_mfma_f32_16x16x32_bf16 v[30:33], v[130:133], v[204:207], v[30:33]
	v_mfma_f32_16x16x32_bf16 v[26:29], v[150:153], v[204:207], v[26:29]
	v_mfma_f32_16x16x32_bf16 v[14:17], v[130:133], v[212:215], v[14:17]
	v_mfma_f32_16x16x32_bf16 v[10:13], v[150:153], v[212:215], v[10:13]
	v_mfma_f32_16x16x32_bf16 v[62:65], v[146:149], v[192:195], v[62:65]
	v_mfma_f32_16x16x32_bf16 v[58:61], v[154:157], v[192:195], v[58:61]
	v_mfma_f32_16x16x32_bf16 v[46:49], v[146:149], v[200:203], v[46:49]
	v_mfma_f32_16x16x32_bf16 v[42:45], v[154:157], v[200:203], v[42:45]
	v_mfma_f32_16x16x32_bf16 v[30:33], v[146:149], v[208:211], v[30:33]
	v_mfma_f32_16x16x32_bf16 v[26:29], v[154:157], v[208:211], v[26:29]
	v_mfma_f32_16x16x32_bf16 v[14:17], v[146:149], v[216:219], v[14:17]
	v_mfma_f32_16x16x32_bf16 v[10:13], v[154:157], v[216:219], v[10:13]
	v_mfma_f32_16x16x32_bf16 v[54:57], v[162:165], v[188:191], v[54:57]
	v_mfma_f32_16x16x32_bf16 v[50:53], v[180:183], v[188:191], v[50:53]
	v_mfma_f32_16x16x32_bf16 v[38:41], v[162:165], v[196:199], v[38:41]
	v_mfma_f32_16x16x32_bf16 v[34:37], v[180:183], v[196:199], v[34:37]
	v_mfma_f32_16x16x32_bf16 v[22:25], v[162:165], v[204:207], v[22:25]
	v_mfma_f32_16x16x32_bf16 v[18:21], v[180:183], v[204:207], v[18:21]
	v_mfma_f32_16x16x32_bf16 v[6:9], v[162:165], v[212:215], v[6:9]
	v_mfma_f32_16x16x32_bf16 v[2:5], v[180:183], v[212:215], v[2:5]
	v_mfma_f32_16x16x32_bf16 v[54:57], v[166:169], v[192:195], v[54:57]
	v_mfma_f32_16x16x32_bf16 v[50:53], v[184:187], v[192:195], v[50:53]
	v_mfma_f32_16x16x32_bf16 v[38:41], v[166:169], v[200:203], v[38:41]
	v_mfma_f32_16x16x32_bf16 v[34:37], v[184:187], v[200:203], v[34:37]
	v_mfma_f32_16x16x32_bf16 v[22:25], v[166:169], v[208:211], v[22:25]
	v_mfma_f32_16x16x32_bf16 v[18:21], v[184:187], v[208:211], v[18:21]
	v_mfma_f32_16x16x32_bf16 v[6:9], v[166:169], v[216:219], v[6:9]
	v_mfma_f32_16x16x32_bf16 v[2:5], v[184:187], v[216:219], v[2:5]
	s_barrier
	s_add_i32 s66, s66, 2
	s_add_u32 s49, s49, 0x100
	s_addc_u32 s51, s51, 0
	s_add_u32 s46, s46, 0x100
	s_addc_u32 s47, s47, 0
	s_cmp_gt_u32 s66, 13
	s_cbranch_scc0 .LBB0_980
	s_setprio 0
	s_and_b64 vcc, exec, s[34:35]
	s_cbranch_vccz .LBB0_983
	s_barrier

; #define PG8_STAGE(bufoff, gbase, voff) do { _Pragma("unroll") for (int _i = 0; _i < 2; ++_i) \
;         __builtin_amdgcn_global_load_lds((const unsigned*)((const char*)(gbase) + (voff)[_i]), (LAS unsigned*)(lds + (bufoff) + ldsw + _i * 8192), 16, 0, 0); } while (0)
; #define PG8_LDA(dst, b, h) do { _Pragma("unroll") for (int m = 0; m < 4; ++m) _Pragma("unroll") for (int k = 0; k < 2; ++k) dst[m][k] = *(const LAS bf16x8*)(lds + PG8_SA(b, h) + aoff + m * 2048 + k * 1024); } while (0)
; #define PG8_LDB(dst, b, h) do { _Pragma("unroll") for (int n = 0; n < 2; ++n) _Pragma("unroll") for (int k = 0; k < 2; ++k) dst[n][k] = *(const LAS bf16x8*)(lds + PG8_SB(b, h) + boff + n * 2048 + k * 1024); } while (0)
; #define PG8_MMA(ai, bj, At, Bt) do { __builtin_amdgcn_s_setprio(1); _Pragma("unroll") for (int m = 0; m < 4; ++m) _Pragma("unroll") for (int n = 0; n < 2; ++n) _Pragma("unroll") for (int k = 0; k < 2; ++k) \
;         acc[ai][bj][m][n] = __builtin_amdgcn_mfma_f32_16x16x32_bf16(Bt[n][k], At[m][k], acc[ai][bj][m][n], 0, 0, 0); __builtin_amdgcn_s_setprio(0); } while (0)
; template <class Epi>
; DI void gemm_phase(LAS unsigned char* lds, const Gemm g, const StaticOrder& S, const Epi& E) {
;     ...
;         const bool has_next = S.next(ui + 1, nxt);
;         const char* nA = has_next ? (const char*)g.A + (size_t)nxt.pm * tstepA + (size_t)nxt.pn * g.a_pn_off * 2 : cA; const char* nB = has_next ? (const char*)g.Bt + (size_t)nxt.pn * tstepB : cB;
;         for (int t = 0; t < nt; t += 2) {
;             const bool last = (t == nt - 2);
;             const char* a1 = cA + (size_t)(t + 1) * kstepA;
;             const char* a2 = last ? nA : cA + (size_t)(t + 2) * kstepA; const char* b2 = last ? nB : cB + (size_t)(t + 2) * kstepB;
;             const char* a3 = a2 + kstepA; const char* b3 = b2 + kstepB;
;             PG8_LDB(B0, 0, 0); PG8_LDB(B1, 0, 1); PG8_SCHED; PG8_LDA(At, 0, 0); PG8_STAGE(PG8_SA(1, 1), a1 + hstepA, voffA);
;             PG8_WAIT_V(8); PG8_WAIT_L(0); PG8_BAR; PG8_MMA(0, 0, At, B0); PG8_MMA(0, 1, At, B1); PG8_BAR; PG8_SCHED;
;     ...
; #pragma unroll
;         for (int a = 0; a < 2; ++a)
; #pragma unroll
;             for (int b = 0; b < 2; ++b)
; #pragma unroll
;                 for (int m = 0; m < 4; ++m)
; #pragma unroll
;                     for (int n = 0; n < 2; ++n) acc[a][b][m][n] = (f32x4){0.f, 0.f, 0.f, 0.f};
;         cur = nxt; cA = nA; cB = nB; ++ui;
.LBB0_2049:
	s_add_u32 s75, s44, 0x100
	v_mov_b32_e32 v2, 0
	s_addc_u32 s78, s45, 0
	s_mov_b32 s79, -2
	v_mov_b32_e32 v3, v2
	v_mov_b32_e32 v4, v2
	v_mov_b32_e32 v5, v2
	v_mov_b32_e32 v6, v2
	v_mov_b32_e32 v7, v2
	v_mov_b32_e32 v8, v2
	v_mov_b32_e32 v9, v2
	v_mov_b32_e32 v18, v2
	v_mov_b32_e32 v19, v2
	v_mov_b32_e32 v20, v2
	v_mov_b32_e32 v21, v2
	v_mov_b32_e32 v22, v2
	v_mov_b32_e32 v23, v2
	v_mov_b32_e32 v24, v2
	v_mov_b32_e32 v25, v2
	v_mov_b32_e32 v34, v2
	v_mov_b32_e32 v35, v2
	v_mov_b32_e32 v36, v2
	v_mov_b32_e32 v37, v2
	v_mov_b32_e32 v38, v2
	v_mov_b32_e32 v39, v2
	v_mov_b32_e32 v40, v2
	v_mov_b32_e32 v41, v2
	v_mov_b32_e32 v50, v2
	v_mov_b32_e32 v51, v2
	v_mov_b32_e32 v52, v2
	v_mov_b32_e32 v53, v2
	v_mov_b32_e32 v54, v2
	v_mov_b32_e32 v55, v2
	v_mov_b32_e32 v56, v2
	v_mov_b32_e32 v57, v2
	v_mov_b32_e32 v10, v2
	v_mov_b32_e32 v11, v2
	v_mov_b32_e32 v12, v2
	v_mov_b32_e32 v13, v2
	v_mov_b32_e32 v14, v2
	v_mov_b32_e32 v15, v2
	v_mov_b32_e32 v16, v2
	v_mov_b32_e32 v17, v2
	v_mov_b32_e32 v26, v2
	v_mov_b32_e32 v27, v2
	v_mov_b32_e32 v28, v2
	v_mov_b32_e32 v29, v2
	v_mov_b32_e32 v30, v2
	v_mov_b32_e32 v31, v2
	v_mov_b32_e32 v32, v2
	v_mov_b32_e32 v33, v2
	v_mov_b32_e32 v42, v2
	v_mov_b32_e32 v43, v2
	v_mov_b32_e32 v44, v2
	v_mov_b32_e32 v45, v2
	v_mov_b32_e32 v46, v2
	v_mov_b32_e32 v47, v2
	v_mov_b32_e32 v48, v2
	v_mov_b32_e32 v49, v2
	v_mov_b32_e32 v58, v2
	v_mov_b32_e32 v59, v2
	v_mov_b32_e32 v60, v2
	v_mov_b32_e32 v61, v2
	v_mov_b32_e32 v62, v2
	v_mov_b32_e32 v63, v2
	v_mov_b32_e32 v64, v2
	v_mov_b32_e32 v65, v2
	v_mov_b32_e32 v66, v2
	v_mov_b32_e32 v67, v2
	v_mov_b32_e32 v68, v2
	v_mov_b32_e32 v69, v2
	v_mov_b32_e32 v70, v2
	v_mov_b32_e32 v71, v2
	v_mov_b32_e32 v72, v2
	v_mov_b32_e32 v73, v2
	v_mov_b32_e32 v82, v2
	v_mov_b32_e32 v83, v2
	v_mov_b32_e32 v84, v2
	v_mov_b32_e32 v85, v2
	v_mov_b32_e32 v86, v2
	v_mov_b32_e32 v87, v2
	v_mov_b32_e32 v88, v2
	v_mov_b32_e32 v89, v2
	v_mov_b32_e32 v98, v2
	v_mov_b32_e32 v99, v2
	v_mov_b32_e32 v100, v2
	v_mov_b32_e32 v101, v2
	v_mov_b32_e32 v102, v2
	v_mov_b32_e32 v103, v2
	v_mov_b32_e32 v104, v2
	v_mov_b32_e32 v105, v2
	v_mov_b32_e32 v114, v2
	v_mov_b32_e32 v115, v2
	v_mov_b32_e32 v116, v2
	v_mov_b32_e32 v117, v2
	v_mov_b32_e32 v118, v2
	v_mov_b32_e32 v119, v2
	v_mov_b32_e32 v120, v2
	v_mov_b32_e32 v121, v2
	v_mov_b32_e32 v74, v2
	v_mov_b32_e32 v75, v2
	v_mov_b32_e32 v76, v2
	v_mov_b32_e32 v77, v2
	v_mov_b32_e32 v78, v2
	v_mov_b32_e32 v79, v2
	v_mov_b32_e32 v80, v2
	v_mov_b32_e32 v81, v2
	v_mov_b32_e32 v90, v2
	v_mov_b32_e32 v91, v2
	v_mov_b32_e32 v92, v2
	v_mov_b32_e32 v93, v2
	v_mov_b32_e32 v94, v2
	v_mov_b32_e32 v95, v2
	v_mov_b32_e32 v96, v2
	v_mov_b32_e32 v97, v2
	v_mov_b32_e32 v106, v2
	v_mov_b32_e32 v107, v2
	v_mov_b32_e32 v108, v2
	v_mov_b32_e32 v109, v2
	v_mov_b32_e32 v110, v2
	v_mov_b32_e32 v111, v2
	v_mov_b32_e32 v112, v2
	v_mov_b32_e32 v113, v2
	v_mov_b32_e32 v122, v2
	v_mov_b32_e32 v123, v2
	v_mov_b32_e32 v124, v2
	v_mov_b32_e32 v125, v2
	v_mov_b32_e32 v126, v2
	v_mov_b32_e32 v127, v2
	v_mov_b32_e32 v128, v2
	v_mov_b32_e32 v129, v2
	v_readfirstlane_b32 s2, v220
	s_lshr_b32 s2, s2, 8
	s_cmp_eq_u32 s2, 0
	s_cbranch_scc1 .Lsprio_5
	s_setprio 1
.Lsprio_5:
.LBB0_2050:
	s_add_u32 s44, s18, 0x100
	s_addc_u32 s45, s19, 0
	s_cmp_eq_u32 s79, 16
	s_cselect_b32 s23, s1, s45
	s_cselect_b32 s22, s0, s44
	s_cselect_b32 s47, s39, s78
	s_cselect_b32 s46, s38, s75
	s_add_i32 s2, 0, 0x10000
	s_add_i32 s15, 0, 0x14000
	v_add_u32_e32 v158, s2, v152
	v_add_u32_e32 v170, s15, v152
	ds_read_b128 v[142:145], v158
	ds_read_b128 v[146:149], v158 offset:1024
	ds_read_b128 v[154:157], v158 offset:2048
	ds_read_b128 v[158:161], v158 offset:3072
	ds_read_b128 v[162:165], v170
	ds_read_b128 v[166:169], v170 offset:1024
	ds_read_b128 v[180:183], v170 offset:2048
	ds_read_b128 v[184:187], v170 offset:3072
	v_lshl_add_u64 v[170:171], s[18:19], 0, v[140:141]
	s_add_i32 m0, s41, 0xc000
	ds_read_b128 v[188:191], v153
	ds_read_b128 v[192:195], v153 offset:1024
	ds_read_b128 v[196:199], v153 offset:2048
	ds_read_b128 v[200:203], v153 offset:3072
	ds_read_b128 v[204:207], v153 offset:4096
	ds_read_b128 v[208:211], v153 offset:5120
	ds_read_b128 v[212:215], v153 offset:6144
	ds_read_b128 v[216:219], v153 offset:7168
	global_load_lds_dwordx4 v[170:171], off
	v_lshl_add_u64 v[170:171], s[18:19], 0, v[138:139]
	s_add_i32 m0, s41, 0xe000
	s_nop 0
	global_load_lds_dwordx4 v[170:171], off
	s_waitcnt vmcnt(8)
	s_waitcnt lgkmcnt(0)
	s_barrier
	s_waitcnt lgkmcnt(0)
	v_mfma_f32_16x16x32_bf16 v[126:129], v[142:145], v[188:191], v[126:129]
	v_mfma_f32_16x16x32_bf16 v[122:125], v[154:157], v[188:191], v[122:125]
	v_mfma_f32_16x16x32_bf16 v[110:113], v[142:145], v[196:199], v[110:113]
	v_mfma_f32_16x16x32_bf16 v[106:109], v[154:157], v[196:199], v[106:109]
	v_mfma_f32_16x16x32_bf16 v[94:97], v[142:145], v[204:207], v[94:97]
	v_mfma_f32_16x16x32_bf16 v[90:93], v[154:157], v[204:207], v[90:93]
	v_mfma_f32_16x16x32_bf16 v[78:81], v[142:145], v[212:215], v[78:81]
	v_mfma_f32_16x16x32_bf16 v[74:77], v[154:157], v[212:215], v[74:77]
	v_mfma_f32_16x16x32_bf16 v[126:129], v[146:149], v[192:195], v[126:129]
	v_mfma_f32_16x16x32_bf16 v[122:125], v[158:161], v[192:195], v[122:125]
	v_mfma_f32_16x16x32_bf16 v[110:113], v[146:149], v[200:203], v[110:113]
	v_mfma_f32_16x16x32_bf16 v[106:109], v[158:161], v[200:203], v[106:109]
	v_mfma_f32_16x16x32_bf16 v[94:97], v[146:149], v[208:211], v[94:97]
	v_mfma_f32_16x16x32_bf16 v[90:93], v[158:161], v[208:211], v[90:93]
	v_mfma_f32_16x16x32_bf16 v[78:81], v[146:149], v[216:219], v[78:81]
	v_mfma_f32_16x16x32_bf16 v[74:77], v[158:161], v[216:219], v[74:77]
	v_mfma_f32_16x16x32_bf16 v[118:121], v[162:165], v[188:191], v[118:121]
	v_mfma_f32_16x16x32_bf16 v[114:117], v[180:183], v[188:191], v[114:117]
	v_mfma_f32_16x16x32_bf16 v[102:105], v[162:165], v[196:199], v[102:105]
	v_mfma_f32_16x16x32_bf16 v[98:101], v[180:183], v[196:199], v[98:101]
	v_mfma_f32_16x16x32_bf16 v[86:89], v[162:165], v[204:207], v[86:89]
	v_mfma_f32_16x16x32_bf16 v[82:85], v[180:183], v[204:207], v[82:85]
	v_mfma_f32_16x16x32_bf16 v[70:73], v[162:165], v[212:215], v[70:73]
	v_mfma_f32_16x16x32_bf16 v[66:69], v[180:183], v[212:215], v[66:69]
	v_mfma_f32_16x16x32_bf16 v[118:121], v[166:169], v[192:195], v[118:121]
	v_mfma_f32_16x16x32_bf16 v[114:117], v[184:187], v[192:195], v[114:117]
	v_mfma_f32_16x16x32_bf16 v[102:105], v[166:169], v[200:203], v[102:105]
	v_mfma_f32_16x16x32_bf16 v[98:101], v[184:187], v[200:203], v[98:101]
	v_mfma_f32_16x16x32_bf16 v[86:89], v[166:169], v[208:211], v[86:89]
	v_mfma_f32_16x16x32_bf16 v[82:85], v[184:187], v[208:211], v[82:85]
	v_mfma_f32_16x16x32_bf16 v[70:73], v[166:169], v[216:219], v[70:73]
	v_mfma_f32_16x16x32_bf16 v[66:69], v[184:187], v[216:219], v[66:69]
	s_barrier
; #define PG8_STAGE(bufoff, gbase, voff) do { _Pragma("unroll") for (int _i = 0; _i < 2; ++_i) \
;         __builtin_amdgcn_global_load_lds((const unsigned*)((const char*)(gbase) + (voff)[_i]), (LAS unsigned*)(lds + (bufoff) + ldsw + _i * 8192), 16, 0, 0); } while (0)
; #define PG8_LDA(dst, b, h) do { _Pragma("unroll") for (int m = 0; m < 4; ++m) _Pragma("unroll") for (int k = 0; k < 2; ++k) dst[m][k] = *(const LAS bf16x8*)(lds + PG8_SA(b, h) + aoff + m * 2048 + k * 1024); } while (0)
; #define PG8_LDB(dst, b, h) do { _Pragma("unroll") for (int n = 0; n < 2; ++n) _Pragma("unroll") for (int k = 0; k < 2; ++k) dst[n][k] = *(const LAS bf16x8*)(lds + PG8_SB(b, h) + boff + n * 2048 + k * 1024); } while (0)
; #define PG8_MMA(ai, bj, At, Bt) do { __builtin_amdgcn_s_setprio(1); _Pragma("unroll") for (int m = 0; m < 4; ++m) _Pragma("unroll") for (int n = 0; n < 2; ++n) _Pragma("unroll") for (int k = 0; k < 2; ++k) \
;         acc[ai][bj][m][n] = __builtin_amdgcn_mfma_f32_16x16x32_bf16(Bt[n][k], At[m][k], acc[ai][bj][m][n], 0, 0, 0); __builtin_amdgcn_s_setprio(0); } while (0)
; #define PG8_WAIT_V(n) asm volatile("s_waitcnt vmcnt(" #n ")" ::: "memory")
; #define PG8_WAIT_L(n) asm volatile("s_waitcnt lgkmcnt(" #n ")" ::: "memory")
; #define PG8_BAR __builtin_amdgcn_s_barrier()
; #define PG8_SCHED __builtin_amdgcn_sched_barrier(0)
; template <class Epi>
; DI void gemm_phase(LAS unsigned char* lds, const Gemm g, const StaticOrder& S, const Epi& E) {
;     ...
;             PG8_LDA(At, 0, 1); PG8_STAGE(PG8_SB(0, 0), b2, voffB); PG8_STAGE(PG8_SB(0, 1), b2 + hstepB, voffB); PG8_STAGE(PG8_SA(0, 0), a2, voffA);
;             PG8_WAIT_V(8); PG8_WAIT_L(0); PG8_BAR; PG8_MMA(1, 0, At, B0); PG8_MMA(1, 1, At, B1); PG8_BAR; PG8_SCHED;
;             PG8_LDB(B0, 1, 0); PG8_LDB(B1, 1, 1); PG8_SCHED; PG8_LDA(At, 1, 0); PG8_STAGE(PG8_SA(0, 1), a2 + hstepA, voffA);
	s_add_i32 s2, s2, s40
	v_lshl_add_u64 v[170:171], s[46:47], 0, v[134:135]
	s_mov_b32 m0, s2
	ds_read_b128 v[188:191], v153 offset:16384
	ds_read_b128 v[192:195], v153 offset:17408
	ds_read_b128 v[196:199], v153 offset:18432
	ds_read_b128 v[200:203], v153 offset:19456
	ds_read_b128 v[204:207], v153 offset:20480
	ds_read_b128 v[208:211], v153 offset:21504
	ds_read_b128 v[212:215], v153 offset:22528
	ds_read_b128 v[216:219], v153 offset:23552
	global_load_lds_dwordx4 v[170:171], off
	s_add_i32 m0, s2, 0x2000
	s_add_u32 s18, s46, 0x50000
	v_lshl_add_u64 v[238:239], s[46:47], 0, v[130:131]
	s_addc_u32 s19, s47, 0
	s_add_i32 s2, s15, s40
	global_load_lds_dwordx4 v[238:239], off
	v_lshl_add_u64 v[240:241], s[18:19], 0, v[134:135]
	s_mov_b32 m0, s2
	v_lshl_add_u64 v[242:243], s[22:23], 0, v[132:133]
	global_load_lds_dwordx4 v[240:241], off
	v_lshl_add_u64 v[240:241], s[18:19], 0, v[130:131]
	s_add_i32 m0, s2, 0x2000
	s_nop 0
	global_load_lds_dwordx4 v[240:241], off
	v_lshl_add_u64 v[240:241], s[22:23], 0, v[136:137]
	s_mov_b32 m0, s41
	s_nop 0
	global_load_lds_dwordx4 v[240:241], off
	s_mov_b32 m0, s48
	s_nop 0
	global_load_lds_dwordx4 v[242:243], off
	s_waitcnt vmcnt(8)
	s_waitcnt lgkmcnt(0)
	s_barrier
	s_waitcnt lgkmcnt(0)
	v_mfma_f32_16x16x32_bf16 v[62:65], v[142:145], v[188:191], v[62:65]
	v_mfma_f32_16x16x32_bf16 v[58:61], v[154:157], v[188:191], v[58:61]
	v_mfma_f32_16x16x32_bf16 v[46:49], v[142:145], v[196:199], v[46:49]
	v_mfma_f32_16x16x32_bf16 v[42:45], v[154:157], v[196:199], v[42:45]
	v_mfma_f32_16x16x32_bf16 v[30:33], v[142:145], v[204:207], v[30:33]
	v_mfma_f32_16x16x32_bf16 v[26:29], v[154:157], v[204:207], v[26:29]
	v_mfma_f32_16x16x32_bf16 v[14:17], v[142:145], v[212:215], v[14:17]
	v_mfma_f32_16x16x32_bf16 v[10:13], v[154:157], v[212:215], v[10:13]
	v_mfma_f32_16x16x32_bf16 v[62:65], v[146:149], v[192:195], v[62:65]
	v_mfma_f32_16x16x32_bf16 v[58:61], v[158:161], v[192:195], v[58:61]
	v_mfma_f32_16x16x32_bf16 v[46:49], v[146:149], v[200:203], v[46:49]
	v_mfma_f32_16x16x32_bf16 v[42:45], v[158:161], v[200:203], v[42:45]
	v_mfma_f32_16x16x32_bf16 v[30:33], v[146:149], v[208:211], v[30:33]
	v_mfma_f32_16x16x32_bf16 v[26:29], v[158:161], v[208:211], v[26:29]
	v_mfma_f32_16x16x32_bf16 v[14:17], v[146:149], v[216:219], v[14:17]
	v_mfma_f32_16x16x32_bf16 v[10:13], v[158:161], v[216:219], v[10:13]
	v_mfma_f32_16x16x32_bf16 v[54:57], v[162:165], v[188:191], v[54:57]
	v_mfma_f32_16x16x32_bf16 v[50:53], v[180:183], v[188:191], v[50:53]
	v_mfma_f32_16x16x32_bf16 v[38:41], v[162:165], v[196:199], v[38:41]
	v_mfma_f32_16x16x32_bf16 v[34:37], v[180:183], v[196:199], v[34:37]
	v_mfma_f32_16x16x32_bf16 v[22:25], v[162:165], v[204:207], v[22:25]
	v_mfma_f32_16x16x32_bf16 v[18:21], v[180:183], v[204:207], v[18:21]
	v_mfma_f32_16x16x32_bf16 v[6:9], v[162:165], v[212:215], v[6:9]
	v_mfma_f32_16x16x32_bf16 v[2:5], v[180:183], v[212:215], v[2:5]
	v_mfma_f32_16x16x32_bf16 v[54:57], v[166:169], v[192:195], v[54:57]
	v_mfma_f32_16x16x32_bf16 v[50:53], v[184:187], v[192:195], v[50:53]
	v_mfma_f32_16x16x32_bf16 v[38:41], v[166:169], v[200:203], v[38:41]
	v_mfma_f32_16x16x32_bf16 v[34:37], v[184:187], v[200:203], v[34:37]
	v_mfma_f32_16x16x32_bf16 v[22:25], v[166:169], v[208:211], v[22:25]
	v_mfma_f32_16x16x32_bf16 v[18:21], v[184:187], v[208:211], v[18:21]
	v_mfma_f32_16x16x32_bf16 v[6:9], v[166:169], v[216:219], v[6:9]
	v_mfma_f32_16x16x32_bf16 v[2:5], v[184:187], v[216:219], v[2:5]
	s_barrier
	s_add_i32 s2, 0, 0x18000
	s_add_i32 s15, 0, 0x1c000
	v_add_u32_e32 v158, s2, v152
	v_add_u32_e32 v184, s15, v152
	ds_read_b128 v[142:145], v158
	ds_read_b128 v[146:149], v158 offset:1024
	ds_read_b128 v[154:157], v158 offset:2048
	ds_read_b128 v[158:161], v158 offset:3072
	ds_read_b128 v[162:165], v184
	ds_read_b128 v[166:169], v184 offset:1024
	ds_read_b128 v[180:183], v184 offset:2048
	ds_read_b128 v[184:187], v184 offset:3072
	s_add_u32 s18, s22, 0x50000
	s_addc_u32 s19, s23, 0
	s_mov_b32 m0, s49
	v_lshl_add_u64 v[244:245], s[18:19], 0, v[136:137]
	ds_read_b128 v[188:191], v153 offset:32768
	ds_read_b128 v[192:195], v153 offset:33792
	ds_read_b128 v[196:199], v153 offset:34816
	ds_read_b128 v[200:203], v153 offset:35840
	ds_read_b128 v[204:207], v153 offset:36864
	ds_read_b128 v[208:211], v153 offset:37888
	ds_read_b128 v[212:215], v153 offset:38912
	ds_read_b128 v[216:219], v153 offset:39936
	global_load_lds_dwordx4 v[244:245], off
	v_lshl_add_u64 v[244:245], s[18:19], 0, v[132:133]
	s_mov_b32 m0, s50
	s_nop 0
	global_load_lds_dwordx4 v[244:245], off
	s_waitcnt vmcnt(8)
	s_waitcnt lgkmcnt(0)
	s_barrier
; #define PG8_STAGE(bufoff, gbase, voff) do { _Pragma("unroll") for (int _i = 0; _i < 2; ++_i) \
;         __builtin_amdgcn_global_load_lds((const unsigned*)((const char*)(gbase) + (voff)[_i]), (LAS unsigned*)(lds + (bufoff) + ldsw + _i * 8192), 16, 0, 0); } while (0)
; #define PG8_LDA(dst, b, h) do { _Pragma("unroll") for (int m = 0; m < 4; ++m) _Pragma("unroll") for (int k = 0; k < 2; ++k) dst[m][k] = *(const LAS bf16x8*)(lds + PG8_SA(b, h) + aoff + m * 2048 + k * 1024); } while (0)
; #define PG8_MMA(ai, bj, At, Bt) do { __builtin_amdgcn_s_setprio(1); _Pragma("unroll") for (int m = 0; m < 4; ++m) _Pragma("unroll") for (int n = 0; n < 2; ++n) _Pragma("unroll") for (int k = 0; k < 2; ++k) \
;         acc[ai][bj][m][n] = __builtin_amdgcn_mfma_f32_16x16x32_bf16(Bt[n][k], At[m][k], acc[ai][bj][m][n], 0, 0, 0); __builtin_amdgcn_s_setprio(0); } while (0)
; #define PG8_WAIT_V(n) asm volatile("s_waitcnt vmcnt(" #n ")" ::: "memory")
; #define PG8_WAIT_L(n) asm volatile("s_waitcnt lgkmcnt(" #n ")" ::: "memory")
; #define PG8_BAR __builtin_amdgcn_s_barrier()
; #define PG8_SCHED __builtin_amdgcn_sched_barrier(0)
; template <class Epi>
; DI void gemm_phase(LAS unsigned char* lds, const Gemm g, const StaticOrder& S, const Epi& E) {
;     ...
;             PG8_WAIT_V(8); PG8_WAIT_L(0); PG8_BAR; PG8_MMA(0, 0, At, B0); PG8_MMA(0, 1, At, B1); PG8_BAR; PG8_SCHED;
;             PG8_LDA(At, 1, 1); PG8_STAGE(PG8_SB(1, 0), b3, voffB); PG8_STAGE(PG8_SB(1, 1), b3 + hstepB, voffB); PG8_STAGE(PG8_SA(1, 0), a3, voffA);
;             PG8_WAIT_V(8); PG8_WAIT_L(0); PG8_BAR; PG8_MMA(1, 0, At, B0); PG8_MMA(1, 1, At, B1); PG8_BAR; PG8_SCHED;
;         }
;         if (wr == 0) PG8_BAR;
	s_waitcnt lgkmcnt(0)
	v_mfma_f32_16x16x32_bf16 v[126:129], v[142:145], v[188:191], v[126:129]
	v_mfma_f32_16x16x32_bf16 v[122:125], v[154:157], v[188:191], v[122:125]
	v_mfma_f32_16x16x32_bf16 v[110:113], v[142:145], v[196:199], v[110:113]
	v_mfma_f32_16x16x32_bf16 v[106:109], v[154:157], v[196:199], v[106:109]
	v_mfma_f32_16x16x32_bf16 v[94:97], v[142:145], v[204:207], v[94:97]
	v_mfma_f32_16x16x32_bf16 v[90:93], v[154:157], v[204:207], v[90:93]
	v_mfma_f32_16x16x32_bf16 v[78:81], v[142:145], v[212:215], v[78:81]
	v_mfma_f32_16x16x32_bf16 v[74:77], v[154:157], v[212:215], v[74:77]
	v_mfma_f32_16x16x32_bf16 v[126:129], v[146:149], v[192:195], v[126:129]
	v_mfma_f32_16x16x32_bf16 v[122:125], v[158:161], v[192:195], v[122:125]
	v_mfma_f32_16x16x32_bf16 v[110:113], v[146:149], v[200:203], v[110:113]
	v_mfma_f32_16x16x32_bf16 v[106:109], v[158:161], v[200:203], v[106:109]
	v_mfma_f32_16x16x32_bf16 v[94:97], v[146:149], v[208:211], v[94:97]
	v_mfma_f32_16x16x32_bf16 v[90:93], v[158:161], v[208:211], v[90:93]
	v_mfma_f32_16x16x32_bf16 v[78:81], v[146:149], v[216:219], v[78:81]
	v_mfma_f32_16x16x32_bf16 v[74:77], v[158:161], v[216:219], v[74:77]
	v_mfma_f32_16x16x32_bf16 v[118:121], v[162:165], v[188:191], v[118:121]
	v_mfma_f32_16x16x32_bf16 v[114:117], v[180:183], v[188:191], v[114:117]
	v_mfma_f32_16x16x32_bf16 v[102:105], v[162:165], v[196:199], v[102:105]
	v_mfma_f32_16x16x32_bf16 v[98:101], v[180:183], v[196:199], v[98:101]
	v_mfma_f32_16x16x32_bf16 v[86:89], v[162:165], v[204:207], v[86:89]
	v_mfma_f32_16x16x32_bf16 v[82:85], v[180:183], v[204:207], v[82:85]
	v_mfma_f32_16x16x32_bf16 v[70:73], v[162:165], v[212:215], v[70:73]
	v_mfma_f32_16x16x32_bf16 v[66:69], v[180:183], v[212:215], v[66:69]
	v_mfma_f32_16x16x32_bf16 v[118:121], v[166:169], v[192:195], v[118:121]
	v_mfma_f32_16x16x32_bf16 v[114:117], v[184:187], v[192:195], v[114:117]
	v_mfma_f32_16x16x32_bf16 v[102:105], v[166:169], v[200:203], v[102:105]
	v_mfma_f32_16x16x32_bf16 v[98:101], v[184:187], v[200:203], v[98:101]
	v_mfma_f32_16x16x32_bf16 v[86:89], v[166:169], v[208:211], v[86:89]
	v_mfma_f32_16x16x32_bf16 v[82:85], v[184:187], v[208:211], v[82:85]
	v_mfma_f32_16x16x32_bf16 v[70:73], v[166:169], v[216:219], v[70:73]
	v_mfma_f32_16x16x32_bf16 v[66:69], v[184:187], v[216:219], v[66:69]
	s_barrier
	s_add_i32 s2, s2, s40
	v_lshl_add_u64 v[170:171], v[170:171], 0, s[6:7]
	s_mov_b32 m0, s2
	ds_read_b128 v[188:191], v153 offset:49152
	ds_read_b128 v[192:195], v153 offset:50176
	ds_read_b128 v[196:199], v153 offset:51200
	ds_read_b128 v[200:203], v153 offset:52224
	ds_read_b128 v[204:207], v153 offset:53248
	ds_read_b128 v[208:211], v153 offset:54272
	ds_read_b128 v[212:215], v153 offset:55296
	ds_read_b128 v[216:219], v153 offset:56320
	global_load_lds_dwordx4 v[170:171], off
	s_add_i32 m0, s2, 0x2000
	s_add_u32 s18, s46, 0x50080
	v_lshl_add_u64 v[170:171], v[238:239], 0, s[6:7]
	s_addc_u32 s19, s47, 0
	s_add_i32 s2, s15, s40
	global_load_lds_dwordx4 v[170:171], off
	v_lshl_add_u64 v[170:171], s[18:19], 0, v[134:135]
	s_mov_b32 m0, s2
	s_nop 0
	global_load_lds_dwordx4 v[170:171], off
	v_lshl_add_u64 v[170:171], s[18:19], 0, v[130:131]
	s_add_i32 m0, s2, 0x2000
	s_nop 0
	global_load_lds_dwordx4 v[170:171], off
	v_lshl_add_u64 v[170:171], v[240:241], 0, s[6:7]
	s_mov_b32 m0, s69
	s_nop 0
	global_load_lds_dwordx4 v[170:171], off
	v_lshl_add_u64 v[170:171], v[242:243], 0, s[6:7]
	s_mov_b32 m0, s70
	s_nop 0
	global_load_lds_dwordx4 v[170:171], off
	s_waitcnt vmcnt(8)
	s_waitcnt lgkmcnt(0)
	s_barrier
	s_waitcnt lgkmcnt(0)
	v_mfma_f32_16x16x32_bf16 v[62:65], v[142:145], v[188:191], v[62:65]
	v_mfma_f32_16x16x32_bf16 v[58:61], v[154:157], v[188:191], v[58:61]
	v_mfma_f32_16x16x32_bf16 v[46:49], v[142:145], v[196:199], v[46:49]
	v_mfma_f32_16x16x32_bf16 v[42:45], v[154:157], v[196:199], v[42:45]
	v_mfma_f32_16x16x32_bf16 v[30:33], v[142:145], v[204:207], v[30:33]
	v_mfma_f32_16x16x32_bf16 v[26:29], v[154:157], v[204:207], v[26:29]
	v_mfma_f32_16x16x32_bf16 v[14:17], v[142:145], v[212:215], v[14:17]
	v_mfma_f32_16x16x32_bf16 v[10:13], v[154:157], v[212:215], v[10:13]
	v_mfma_f32_16x16x32_bf16 v[62:65], v[146:149], v[192:195], v[62:65]
	v_mfma_f32_16x16x32_bf16 v[58:61], v[158:161], v[192:195], v[58:61]
	v_mfma_f32_16x16x32_bf16 v[46:49], v[146:149], v[200:203], v[46:49]
	v_mfma_f32_16x16x32_bf16 v[42:45], v[158:161], v[200:203], v[42:45]
	v_mfma_f32_16x16x32_bf16 v[30:33], v[146:149], v[208:211], v[30:33]
	v_mfma_f32_16x16x32_bf16 v[26:29], v[158:161], v[208:211], v[26:29]
	v_mfma_f32_16x16x32_bf16 v[14:17], v[146:149], v[216:219], v[14:17]
	v_mfma_f32_16x16x32_bf16 v[10:13], v[158:161], v[216:219], v[10:13]
	v_mfma_f32_16x16x32_bf16 v[54:57], v[162:165], v[188:191], v[54:57]
	v_mfma_f32_16x16x32_bf16 v[50:53], v[180:183], v[188:191], v[50:53]
	v_mfma_f32_16x16x32_bf16 v[38:41], v[162:165], v[196:199], v[38:41]
	v_mfma_f32_16x16x32_bf16 v[34:37], v[180:183], v[196:199], v[34:37]
	v_mfma_f32_16x16x32_bf16 v[22:25], v[162:165], v[204:207], v[22:25]
	v_mfma_f32_16x16x32_bf16 v[18:21], v[180:183], v[204:207], v[18:21]
	v_mfma_f32_16x16x32_bf16 v[6:9], v[162:165], v[212:215], v[6:9]
	v_mfma_f32_16x16x32_bf16 v[2:5], v[180:183], v[212:215], v[2:5]
	v_mfma_f32_16x16x32_bf16 v[54:57], v[166:169], v[192:195], v[54:57]
	v_mfma_f32_16x16x32_bf16 v[50:53], v[184:187], v[192:195], v[50:53]
	v_mfma_f32_16x16x32_bf16 v[38:41], v[166:169], v[200:203], v[38:41]
	v_mfma_f32_16x16x32_bf16 v[34:37], v[184:187], v[200:203], v[34:37]
	v_mfma_f32_16x16x32_bf16 v[22:25], v[166:169], v[208:211], v[22:25]
	v_mfma_f32_16x16x32_bf16 v[18:21], v[184:187], v[208:211], v[18:21]
	v_mfma_f32_16x16x32_bf16 v[6:9], v[166:169], v[216:219], v[6:9]
	v_mfma_f32_16x16x32_bf16 v[2:5], v[184:187], v[216:219], v[2:5]
	s_barrier
	s_add_i32 s79, s79, 2
	s_add_u32 s75, s75, 0x100
	s_addc_u32 s78, s78, 0
	s_cmp_gt_u32 s79, 17
	s_mov_b64 s[18:19], s[44:45]
	s_cbranch_scc0 .LBB0_2050
	s_setprio 0
	s_and_b64 vcc, exec, s[36:37]
	s_cbranch_vccz .LBB0_2053
	s_barrier

; #define PG8_STAGE(bufoff, gbase, voff) do { _Pragma("unroll") for (int _i = 0; _i < 2; ++_i) \
;         __builtin_amdgcn_global_load_lds((const unsigned*)((const char*)(gbase) + (voff)[_i]), (LAS unsigned*)(lds + (bufoff) + ldsw + _i * 8192), 16, 0, 0); } while (0)
; #define PG8_LDA(dst, b, h) do { _Pragma("unroll") for (int m = 0; m < 4; ++m) _Pragma("unroll") for (int k = 0; k < 2; ++k) dst[m][k] = *(const LAS bf16x8*)(lds + PG8_SA(b, h) + aoff + m * 2048 + k * 1024); } while (0)
; #define PG8_LDB(dst, b, h) do { _Pragma("unroll") for (int n = 0; n < 2; ++n) _Pragma("unroll") for (int k = 0; k < 2; ++k) dst[n][k] = *(const LAS bf16x8*)(lds + PG8_SB(b, h) + boff + n * 2048 + k * 1024); } while (0)
; #define PG8_MMA(ai, bj, At, Bt) do { __builtin_amdgcn_s_setprio(1); _Pragma("unroll") for (int m = 0; m < 4; ++m) _Pragma("unroll") for (int n = 0; n < 2; ++n) _Pragma("unroll") for (int k = 0; k < 2; ++k) \
;         acc[ai][bj][m][n] = __builtin_amdgcn_mfma_f32_16x16x32_bf16(Bt[n][k], At[m][k], acc[ai][bj][m][n], 0, 0, 0); __builtin_amdgcn_s_setprio(0); } while (0)
; template <class Epi>
; DI void gemm_phase(LAS unsigned char* lds, const Gemm g, const StaticOrder& S, const Epi& E) {
;     ...
;         const bool has_next = S.next(ui + 1, nxt);
;         const char* nA = has_next ? (const char*)g.A + (size_t)nxt.pm * tstepA + (size_t)nxt.pn * g.a_pn_off * 2 : cA; const char* nB = has_next ? (const char*)g.Bt + (size_t)nxt.pn * tstepB : cB;
;         for (int t = 0; t < nt; t += 2) {
;             const bool last = (t == nt - 2);
;             const char* a1 = cA + (size_t)(t + 1) * kstepA;
;             const char* a2 = last ? nA : cA + (size_t)(t + 2) * kstepA; const char* b2 = last ? nB : cB + (size_t)(t + 2) * kstepB;
;             const char* a3 = a2 + kstepA; const char* b3 = b2 + kstepB;
;             PG8_LDB(B0, 0, 0); PG8_LDB(B1, 0, 1); PG8_SCHED; PG8_LDA(At, 0, 0); PG8_STAGE(PG8_SA(1, 1), a1 + hstepA, voffA);
;             PG8_WAIT_V(8); PG8_WAIT_L(0); PG8_BAR; PG8_MMA(0, 0, At, B0); PG8_MMA(0, 1, At, B1); PG8_BAR; PG8_SCHED;
;     ...
; #pragma unroll
;         for (int a = 0; a < 2; ++a)
; #pragma unroll
;             for (int b = 0; b < 2; ++b)
; #pragma unroll
;                 for (int m = 0; m < 4; ++m)
; #pragma unroll
;                     for (int n = 0; n < 2; ++n) acc[a][b][m][n] = (f32x4){0.f, 0.f, 0.f, 0.f};
;         cur = nxt; cA = nA; cB = nB; ++ui;
.LBB0_2161:
	s_ashr_i32 s31, s30, 31
	s_lshl_b64 s[22:23], s[30:31], 19
	s_add_u32 s34, s47, s22
	s_addc_u32 s35, s48, s23
	s_and_b64 s[22:23], s[40:41], exec
	s_cselect_b32 s31, s35, s39
	s_cselect_b32 s84, s34, s38
	s_ashr_i32 s29, s28, 31
	s_lshl_b64 s[22:23], s[28:29], 19
	s_add_u32 s36, s49, s22
	s_addc_u32 s37, s50, s23
	s_and_b64 s[22:23], s[40:41], exec
	s_cselect_b32 s29, s37, s19
	s_cselect_b32 s85, s36, s18
	s_add_u32 s88, s18, 0x100
	s_addc_u32 s89, s19, 0
	s_add_u32 s38, s38, 0x40080
	v_mov_b32_e32 v2, 0
	s_addc_u32 s39, s39, 0
	s_mov_b32 s90, -2
	v_mov_b32_e32 v3, v2
	v_mov_b32_e32 v4, v2
	v_mov_b32_e32 v5, v2
	v_mov_b32_e32 v6, v2
	v_mov_b32_e32 v7, v2
	v_mov_b32_e32 v8, v2
	v_mov_b32_e32 v9, v2
	v_mov_b32_e32 v18, v2
	v_mov_b32_e32 v19, v2
	v_mov_b32_e32 v20, v2
	v_mov_b32_e32 v21, v2
	v_mov_b32_e32 v22, v2
	v_mov_b32_e32 v23, v2
	v_mov_b32_e32 v24, v2
	v_mov_b32_e32 v25, v2
	v_mov_b32_e32 v34, v2
	v_mov_b32_e32 v35, v2
	v_mov_b32_e32 v36, v2
	v_mov_b32_e32 v37, v2
	v_mov_b32_e32 v38, v2
	v_mov_b32_e32 v39, v2
	v_mov_b32_e32 v40, v2
	v_mov_b32_e32 v41, v2
	v_mov_b32_e32 v50, v2
	v_mov_b32_e32 v51, v2
	v_mov_b32_e32 v52, v2
	v_mov_b32_e32 v53, v2
	v_mov_b32_e32 v54, v2
	v_mov_b32_e32 v55, v2
	v_mov_b32_e32 v56, v2
	v_mov_b32_e32 v57, v2
	v_mov_b32_e32 v10, v2
	v_mov_b32_e32 v11, v2
	v_mov_b32_e32 v12, v2
	v_mov_b32_e32 v13, v2
	v_mov_b32_e32 v14, v2
	v_mov_b32_e32 v15, v2
	v_mov_b32_e32 v16, v2
	v_mov_b32_e32 v17, v2
	v_mov_b32_e32 v26, v2
	v_mov_b32_e32 v27, v2
	v_mov_b32_e32 v28, v2
	v_mov_b32_e32 v29, v2
	v_mov_b32_e32 v30, v2
	v_mov_b32_e32 v31, v2
	v_mov_b32_e32 v32, v2
	v_mov_b32_e32 v33, v2
	v_mov_b32_e32 v42, v2
	v_mov_b32_e32 v43, v2
	v_mov_b32_e32 v44, v2
	v_mov_b32_e32 v45, v2
	v_mov_b32_e32 v46, v2
	v_mov_b32_e32 v47, v2
	v_mov_b32_e32 v48, v2
	v_mov_b32_e32 v49, v2
	v_mov_b32_e32 v58, v2
	v_mov_b32_e32 v59, v2
	v_mov_b32_e32 v60, v2
	v_mov_b32_e32 v61, v2
	v_mov_b32_e32 v62, v2
	v_mov_b32_e32 v63, v2
	v_mov_b32_e32 v64, v2
	v_mov_b32_e32 v65, v2
	v_mov_b32_e32 v66, v2
	v_mov_b32_e32 v67, v2
	v_mov_b32_e32 v68, v2
	v_mov_b32_e32 v69, v2
	v_mov_b32_e32 v70, v2
	v_mov_b32_e32 v71, v2
	v_mov_b32_e32 v72, v2
	v_mov_b32_e32 v73, v2
	v_mov_b32_e32 v82, v2
	v_mov_b32_e32 v83, v2
	v_mov_b32_e32 v84, v2
	v_mov_b32_e32 v85, v2
	v_mov_b32_e32 v86, v2
	v_mov_b32_e32 v87, v2
	v_mov_b32_e32 v88, v2
	v_mov_b32_e32 v89, v2
	v_mov_b32_e32 v98, v2
	v_mov_b32_e32 v99, v2
	v_mov_b32_e32 v100, v2
	v_mov_b32_e32 v101, v2
	v_mov_b32_e32 v102, v2
	v_mov_b32_e32 v103, v2
	v_mov_b32_e32 v104, v2
	v_mov_b32_e32 v105, v2
	v_mov_b32_e32 v114, v2
	v_mov_b32_e32 v115, v2
	v_mov_b32_e32 v116, v2
	v_mov_b32_e32 v117, v2
	v_mov_b32_e32 v118, v2
	v_mov_b32_e32 v119, v2
	v_mov_b32_e32 v120, v2
	v_mov_b32_e32 v121, v2
	v_mov_b32_e32 v74, v2
	v_mov_b32_e32 v75, v2
	v_mov_b32_e32 v76, v2
	v_mov_b32_e32 v77, v2
	v_mov_b32_e32 v78, v2
	v_mov_b32_e32 v79, v2
	v_mov_b32_e32 v80, v2
	v_mov_b32_e32 v81, v2
	v_mov_b32_e32 v90, v2
	v_mov_b32_e32 v91, v2
	v_mov_b32_e32 v92, v2
	v_mov_b32_e32 v93, v2
	v_mov_b32_e32 v94, v2
	v_mov_b32_e32 v95, v2
	v_mov_b32_e32 v96, v2
	v_mov_b32_e32 v97, v2
	v_mov_b32_e32 v106, v2
	v_mov_b32_e32 v107, v2
	v_mov_b32_e32 v108, v2
	v_mov_b32_e32 v109, v2
	v_mov_b32_e32 v110, v2
	v_mov_b32_e32 v111, v2
	v_mov_b32_e32 v112, v2
	v_mov_b32_e32 v113, v2
	v_mov_b32_e32 v122, v2
	v_mov_b32_e32 v123, v2
	v_mov_b32_e32 v124, v2
	v_mov_b32_e32 v125, v2
	v_mov_b32_e32 v126, v2
	v_mov_b32_e32 v127, v2
	v_mov_b32_e32 v128, v2
	v_mov_b32_e32 v129, v2
	v_readfirstlane_b32 s2, v220
	s_lshr_b32 s2, s2, 8
	s_cmp_eq_u32 s2, 0
	s_cbranch_scc1 .Lsprio_6
	s_setprio 1
.Lsprio_6:
.LBB0_2162:
	s_add_u32 s2, s38, 0xfffc0080
	s_addc_u32 s15, s39, -1
	s_add_i32 s25, 0, 0x10000
	s_cmp_eq_u32 s90, 12
	s_cselect_b32 s23, s31, s15
	s_cselect_b32 s22, s84, s2
	s_cselect_b32 s19, s29, s89
	s_cselect_b32 s18, s85, s88
	s_add_i32 s2, 0, 0x14000
	v_add_u32_e32 v158, s25, v148
	v_add_u32_e32 v170, s2, v148
	ds_read_b128 v[142:145], v158
	ds_read_b128 v[150:153], v158 offset:1024
	ds_read_b128 v[154:157], v158 offset:2048
	ds_read_b128 v[158:161], v158 offset:3072
	ds_read_b128 v[162:165], v170
	ds_read_b128 v[166:169], v170 offset:1024
	ds_read_b128 v[180:183], v170 offset:2048
	ds_read_b128 v[184:187], v170 offset:3072
	v_lshl_add_u64 v[170:171], s[38:39], 0, v[140:141]
	s_add_i32 m0, s62, 0xc000
	ds_read_b128 v[188:191], v149
	ds_read_b128 v[192:195], v149 offset:1024
	ds_read_b128 v[196:199], v149 offset:2048
	ds_read_b128 v[200:203], v149 offset:3072
	ds_read_b128 v[204:207], v149 offset:4096
	ds_read_b128 v[208:211], v149 offset:5120
	ds_read_b128 v[212:215], v149 offset:6144
	ds_read_b128 v[216:219], v149 offset:7168
	global_load_lds_dwordx4 v[170:171], off
	v_lshl_add_u64 v[170:171], s[38:39], 0, v[138:139]
	s_add_i32 m0, s62, 0xe000
	s_nop 0
	global_load_lds_dwordx4 v[170:171], off
	s_waitcnt vmcnt(8)
	s_waitcnt lgkmcnt(0)
	s_barrier
; #define PG8_STAGE(bufoff, gbase, voff) do { _Pragma("unroll") for (int _i = 0; _i < 2; ++_i) \
;         __builtin_amdgcn_global_load_lds((const unsigned*)((const char*)(gbase) + (voff)[_i]), (LAS unsigned*)(lds + (bufoff) + ldsw + _i * 8192), 16, 0, 0); } while (0)
; #define PG8_LDA(dst, b, h) do { _Pragma("unroll") for (int m = 0; m < 4; ++m) _Pragma("unroll") for (int k = 0; k < 2; ++k) dst[m][k] = *(const LAS bf16x8*)(lds + PG8_SA(b, h) + aoff + m * 2048 + k * 1024); } while (0)
; #define PG8_MMA(ai, bj, At, Bt) do { __builtin_amdgcn_s_setprio(1); _Pragma("unroll") for (int m = 0; m < 4; ++m) _Pragma("unroll") for (int n = 0; n < 2; ++n) _Pragma("unroll") for (int k = 0; k < 2; ++k) \
;         acc[ai][bj][m][n] = __builtin_amdgcn_mfma_f32_16x16x32_bf16(Bt[n][k], At[m][k], acc[ai][bj][m][n], 0, 0, 0); __builtin_amdgcn_s_setprio(0); } while (0)
; #define PG8_WAIT_V(n) asm volatile("s_waitcnt vmcnt(" #n ")" ::: "memory")
; #define PG8_WAIT_L(n) asm volatile("s_waitcnt lgkmcnt(" #n ")" ::: "memory")
; #define PG8_BAR __builtin_amdgcn_s_barrier()
; #define PG8_SCHED __builtin_amdgcn_sched_barrier(0)
; template <class Epi>
; DI void gemm_phase(LAS unsigned char* lds, const Gemm g, const StaticOrder& S, const Epi& E) {
;     ...
;             PG8_WAIT_V(8); PG8_WAIT_L(0); PG8_BAR; PG8_MMA(0, 0, At, B0); PG8_MMA(0, 1, At, B1); PG8_BAR; PG8_SCHED;
;             PG8_LDA(At, 0, 1); PG8_STAGE(PG8_SB(0, 0), b2, voffB); PG8_STAGE(PG8_SB(0, 1), b2 + hstepB, voffB); PG8_STAGE(PG8_SA(0, 0), a2, voffA);
;             PG8_WAIT_V(8); PG8_WAIT_L(0); PG8_BAR; PG8_MMA(1, 0, At, B0); PG8_MMA(1, 1, At, B1); PG8_BAR; PG8_SCHED;
	s_waitcnt lgkmcnt(0)
	v_mfma_f32_16x16x32_bf16 v[126:129], v[142:145], v[188:191], v[126:129]
	v_mfma_f32_16x16x32_bf16 v[122:125], v[154:157], v[188:191], v[122:125]
	v_mfma_f32_16x16x32_bf16 v[110:113], v[142:145], v[196:199], v[110:113]
	v_mfma_f32_16x16x32_bf16 v[106:109], v[154:157], v[196:199], v[106:109]
	v_mfma_f32_16x16x32_bf16 v[94:97], v[142:145], v[204:207], v[94:97]
	v_mfma_f32_16x16x32_bf16 v[90:93], v[154:157], v[204:207], v[90:93]
	v_mfma_f32_16x16x32_bf16 v[78:81], v[142:145], v[212:215], v[78:81]
	v_mfma_f32_16x16x32_bf16 v[74:77], v[154:157], v[212:215], v[74:77]
	v_mfma_f32_16x16x32_bf16 v[126:129], v[150:153], v[192:195], v[126:129]
	v_mfma_f32_16x16x32_bf16 v[122:125], v[158:161], v[192:195], v[122:125]
	v_mfma_f32_16x16x32_bf16 v[110:113], v[150:153], v[200:203], v[110:113]
	v_mfma_f32_16x16x32_bf16 v[106:109], v[158:161], v[200:203], v[106:109]
	v_mfma_f32_16x16x32_bf16 v[94:97], v[150:153], v[208:211], v[94:97]
	v_mfma_f32_16x16x32_bf16 v[90:93], v[158:161], v[208:211], v[90:93]
	v_mfma_f32_16x16x32_bf16 v[78:81], v[150:153], v[216:219], v[78:81]
	v_mfma_f32_16x16x32_bf16 v[74:77], v[158:161], v[216:219], v[74:77]
	v_mfma_f32_16x16x32_bf16 v[118:121], v[162:165], v[188:191], v[118:121]
	v_mfma_f32_16x16x32_bf16 v[114:117], v[180:183], v[188:191], v[114:117]
	v_mfma_f32_16x16x32_bf16 v[102:105], v[162:165], v[196:199], v[102:105]
	v_mfma_f32_16x16x32_bf16 v[98:101], v[180:183], v[196:199], v[98:101]
	v_mfma_f32_16x16x32_bf16 v[86:89], v[162:165], v[204:207], v[86:89]
	v_mfma_f32_16x16x32_bf16 v[82:85], v[180:183], v[204:207], v[82:85]
	v_mfma_f32_16x16x32_bf16 v[70:73], v[162:165], v[212:215], v[70:73]
	v_mfma_f32_16x16x32_bf16 v[66:69], v[180:183], v[212:215], v[66:69]
	v_mfma_f32_16x16x32_bf16 v[118:121], v[166:169], v[192:195], v[118:121]
	v_mfma_f32_16x16x32_bf16 v[114:117], v[184:187], v[192:195], v[114:117]
	v_mfma_f32_16x16x32_bf16 v[102:105], v[166:169], v[200:203], v[102:105]
	v_mfma_f32_16x16x32_bf16 v[98:101], v[184:187], v[200:203], v[98:101]
	v_mfma_f32_16x16x32_bf16 v[86:89], v[166:169], v[208:211], v[86:89]
	v_mfma_f32_16x16x32_bf16 v[82:85], v[184:187], v[208:211], v[82:85]
	v_mfma_f32_16x16x32_bf16 v[70:73], v[166:169], v[216:219], v[70:73]
	v_mfma_f32_16x16x32_bf16 v[66:69], v[184:187], v[216:219], v[66:69]
	s_barrier
	s_add_i32 s15, s25, s51
	v_lshl_add_u64 v[170:171], s[18:19], 0, v[134:135]
	s_mov_b32 m0, s15
	ds_read_b128 v[188:191], v149 offset:16384
	ds_read_b128 v[192:195], v149 offset:17408
	ds_read_b128 v[196:199], v149 offset:18432
	ds_read_b128 v[200:203], v149 offset:19456
	ds_read_b128 v[204:207], v149 offset:20480
	ds_read_b128 v[208:211], v149 offset:21504
	ds_read_b128 v[212:215], v149 offset:22528
	ds_read_b128 v[216:219], v149 offset:23552
	global_load_lds_dwordx4 v[170:171], off
	s_add_i32 m0, s15, 0x2000
	s_add_u32 s92, s18, 0x40000
	v_lshl_add_u64 v[238:239], s[18:19], 0, v[130:131]
	s_addc_u32 s93, s19, 0
	s_add_i32 s2, s2, s51
	global_load_lds_dwordx4 v[238:239], off
	v_lshl_add_u64 v[240:241], s[92:93], 0, v[134:135]
	s_mov_b32 m0, s2
	v_lshl_add_u64 v[242:243], s[22:23], 0, v[132:133]
	global_load_lds_dwordx4 v[240:241], off
	v_lshl_add_u64 v[240:241], s[92:93], 0, v[130:131]
	s_add_i32 m0, s2, 0x2000
	s_nop 0
	global_load_lds_dwordx4 v[240:241], off
	v_lshl_add_u64 v[240:241], s[22:23], 0, v[136:137]
	s_mov_b32 m0, s62
	s_nop 0
	global_load_lds_dwordx4 v[240:241], off
	s_mov_b32 m0, s69
	s_nop 0
	global_load_lds_dwordx4 v[242:243], off
	s_waitcnt vmcnt(8)
	s_waitcnt lgkmcnt(0)
	s_barrier
	s_waitcnt lgkmcnt(0)
	v_mfma_f32_16x16x32_bf16 v[62:65], v[142:145], v[188:191], v[62:65]
	v_mfma_f32_16x16x32_bf16 v[58:61], v[154:157], v[188:191], v[58:61]
	v_mfma_f32_16x16x32_bf16 v[46:49], v[142:145], v[196:199], v[46:49]
	v_mfma_f32_16x16x32_bf16 v[42:45], v[154:157], v[196:199], v[42:45]
	v_mfma_f32_16x16x32_bf16 v[30:33], v[142:145], v[204:207], v[30:33]
	v_mfma_f32_16x16x32_bf16 v[26:29], v[154:157], v[204:207], v[26:29]
	v_mfma_f32_16x16x32_bf16 v[14:17], v[142:145], v[212:215], v[14:17]
	v_mfma_f32_16x16x32_bf16 v[10:13], v[154:157], v[212:215], v[10:13]
	v_mfma_f32_16x16x32_bf16 v[62:65], v[150:153], v[192:195], v[62:65]
	v_mfma_f32_16x16x32_bf16 v[58:61], v[158:161], v[192:195], v[58:61]
	v_mfma_f32_16x16x32_bf16 v[46:49], v[150:153], v[200:203], v[46:49]
	v_mfma_f32_16x16x32_bf16 v[42:45], v[158:161], v[200:203], v[42:45]
	v_mfma_f32_16x16x32_bf16 v[30:33], v[150:153], v[208:211], v[30:33]
	v_mfma_f32_16x16x32_bf16 v[26:29], v[158:161], v[208:211], v[26:29]
	v_mfma_f32_16x16x32_bf16 v[14:17], v[150:153], v[216:219], v[14:17]
	v_mfma_f32_16x16x32_bf16 v[10:13], v[158:161], v[216:219], v[10:13]
	v_mfma_f32_16x16x32_bf16 v[54:57], v[162:165], v[188:191], v[54:57]
	v_mfma_f32_16x16x32_bf16 v[50:53], v[180:183], v[188:191], v[50:53]
	v_mfma_f32_16x16x32_bf16 v[38:41], v[162:165], v[196:199], v[38:41]
	v_mfma_f32_16x16x32_bf16 v[34:37], v[180:183], v[196:199], v[34:37]
	v_mfma_f32_16x16x32_bf16 v[22:25], v[162:165], v[204:207], v[22:25]
	v_mfma_f32_16x16x32_bf16 v[18:21], v[180:183], v[204:207], v[18:21]
	v_mfma_f32_16x16x32_bf16 v[6:9], v[162:165], v[212:215], v[6:9]
	v_mfma_f32_16x16x32_bf16 v[2:5], v[180:183], v[212:215], v[2:5]
	v_mfma_f32_16x16x32_bf16 v[54:57], v[166:169], v[192:195], v[54:57]
	v_mfma_f32_16x16x32_bf16 v[50:53], v[184:187], v[192:195], v[50:53]
	v_mfma_f32_16x16x32_bf16 v[38:41], v[166:169], v[200:203], v[38:41]
	v_mfma_f32_16x16x32_bf16 v[34:37], v[184:187], v[200:203], v[34:37]
	v_mfma_f32_16x16x32_bf16 v[22:25], v[166:169], v[208:211], v[22:25]
	v_mfma_f32_16x16x32_bf16 v[18:21], v[184:187], v[208:211], v[18:21]
	v_mfma_f32_16x16x32_bf16 v[6:9], v[166:169], v[216:219], v[6:9]
	v_mfma_f32_16x16x32_bf16 v[2:5], v[184:187], v[216:219], v[2:5]
	s_barrier
; #define PG8_STAGE(bufoff, gbase, voff) do { _Pragma("unroll") for (int _i = 0; _i < 2; ++_i) \
;         __builtin_amdgcn_global_load_lds((const unsigned*)((const char*)(gbase) + (voff)[_i]), (LAS unsigned*)(lds + (bufoff) + ldsw + _i * 8192), 16, 0, 0); } while (0)
; #define PG8_LDA(dst, b, h) do { _Pragma("unroll") for (int m = 0; m < 4; ++m) _Pragma("unroll") for (int k = 0; k < 2; ++k) dst[m][k] = *(const LAS bf16x8*)(lds + PG8_SA(b, h) + aoff + m * 2048 + k * 1024); } while (0)
; #define PG8_LDB(dst, b, h) do { _Pragma("unroll") for (int n = 0; n < 2; ++n) _Pragma("unroll") for (int k = 0; k < 2; ++k) dst[n][k] = *(const LAS bf16x8*)(lds + PG8_SB(b, h) + boff + n * 2048 + k * 1024); } while (0)
; #define PG8_MMA(ai, bj, At, Bt) do { __builtin_amdgcn_s_setprio(1); _Pragma("unroll") for (int m = 0; m < 4; ++m) _Pragma("unroll") for (int n = 0; n < 2; ++n) _Pragma("unroll") for (int k = 0; k < 2; ++k) \
;         acc[ai][bj][m][n] = __builtin_amdgcn_mfma_f32_16x16x32_bf16(Bt[n][k], At[m][k], acc[ai][bj][m][n], 0, 0, 0); __builtin_amdgcn_s_setprio(0); } while (0)
; #define PG8_WAIT_V(n) asm volatile("s_waitcnt vmcnt(" #n ")" ::: "memory")
; #define PG8_WAIT_L(n) asm volatile("s_waitcnt lgkmcnt(" #n ")" ::: "memory")
; #define PG8_BAR __builtin_amdgcn_s_barrier()
; #define PG8_SCHED __builtin_amdgcn_sched_barrier(0)
; template <class Epi>
; DI void gemm_phase(LAS unsigned char* lds, const Gemm g, const StaticOrder& S, const Epi& E) {
;     ...
;             PG8_LDB(B0, 1, 0); PG8_LDB(B1, 1, 1); PG8_SCHED; PG8_LDA(At, 1, 0); PG8_STAGE(PG8_SA(0, 1), a2 + hstepA, voffA);
;             PG8_WAIT_V(8); PG8_WAIT_L(0); PG8_BAR; PG8_MMA(0, 0, At, B0); PG8_MMA(0, 1, At, B1); PG8_BAR; PG8_SCHED;
	s_add_i32 s2, 0, 0x18000
	s_add_i32 s15, 0, 0x1c000
	v_add_u32_e32 v158, s2, v148
	v_add_u32_e32 v184, s15, v148
	ds_read_b128 v[142:145], v158
	ds_read_b128 v[150:153], v158 offset:1024
	ds_read_b128 v[154:157], v158 offset:2048
	ds_read_b128 v[158:161], v158 offset:3072
	ds_read_b128 v[162:165], v184
	ds_read_b128 v[166:169], v184 offset:1024
	ds_read_b128 v[180:183], v184 offset:2048
	ds_read_b128 v[184:187], v184 offset:3072
	s_add_u32 s22, s22, 0x40000
	s_addc_u32 s23, s23, 0
	s_mov_b32 m0, s70
	v_lshl_add_u64 v[244:245], s[22:23], 0, v[136:137]
	ds_read_b128 v[188:191], v149 offset:32768
	ds_read_b128 v[192:195], v149 offset:33792
	ds_read_b128 v[196:199], v149 offset:34816
	ds_read_b128 v[200:203], v149 offset:35840
	ds_read_b128 v[204:207], v149 offset:36864
	ds_read_b128 v[208:211], v149 offset:37888
	ds_read_b128 v[212:215], v149 offset:38912
	ds_read_b128 v[216:219], v149 offset:39936
	global_load_lds_dwordx4 v[244:245], off
	v_lshl_add_u64 v[244:245], s[22:23], 0, v[132:133]
	s_mov_b32 m0, s71
	s_nop 0
	global_load_lds_dwordx4 v[244:245], off
	s_waitcnt vmcnt(8)
	s_waitcnt lgkmcnt(0)
	s_barrier
	s_waitcnt lgkmcnt(0)
	v_mfma_f32_16x16x32_bf16 v[126:129], v[142:145], v[188:191], v[126:129]
	v_mfma_f32_16x16x32_bf16 v[122:125], v[154:157], v[188:191], v[122:125]
	v_mfma_f32_16x16x32_bf16 v[110:113], v[142:145], v[196:199], v[110:113]
	v_mfma_f32_16x16x32_bf16 v[106:109], v[154:157], v[196:199], v[106:109]
	v_mfma_f32_16x16x32_bf16 v[94:97], v[142:145], v[204:207], v[94:97]
	v_mfma_f32_16x16x32_bf16 v[90:93], v[154:157], v[204:207], v[90:93]
	v_mfma_f32_16x16x32_bf16 v[78:81], v[142:145], v[212:215], v[78:81]
	v_mfma_f32_16x16x32_bf16 v[74:77], v[154:157], v[212:215], v[74:77]
	v_mfma_f32_16x16x32_bf16 v[126:129], v[150:153], v[192:195], v[126:129]
	v_mfma_f32_16x16x32_bf16 v[122:125], v[158:161], v[192:195], v[122:125]
	v_mfma_f32_16x16x32_bf16 v[110:113], v[150:153], v[200:203], v[110:113]
	v_mfma_f32_16x16x32_bf16 v[106:109], v[158:161], v[200:203], v[106:109]
	v_mfma_f32_16x16x32_bf16 v[94:97], v[150:153], v[208:211], v[94:97]
	v_mfma_f32_16x16x32_bf16 v[90:93], v[158:161], v[208:211], v[90:93]
	v_mfma_f32_16x16x32_bf16 v[78:81], v[150:153], v[216:219], v[78:81]
	v_mfma_f32_16x16x32_bf16 v[74:77], v[158:161], v[216:219], v[74:77]
	v_mfma_f32_16x16x32_bf16 v[118:121], v[162:165], v[188:191], v[118:121]
	v_mfma_f32_16x16x32_bf16 v[114:117], v[180:183], v[188:191], v[114:117]
	v_mfma_f32_16x16x32_bf16 v[102:105], v[162:165], v[196:199], v[102:105]
	v_mfma_f32_16x16x32_bf16 v[98:101], v[180:183], v[196:199], v[98:101]
	v_mfma_f32_16x16x32_bf16 v[86:89], v[162:165], v[204:207], v[86:89]
	v_mfma_f32_16x16x32_bf16 v[82:85], v[180:183], v[204:207], v[82:85]
	v_mfma_f32_16x16x32_bf16 v[70:73], v[162:165], v[212:215], v[70:73]
	v_mfma_f32_16x16x32_bf16 v[66:69], v[180:183], v[212:215], v[66:69]
	v_mfma_f32_16x16x32_bf16 v[118:121], v[166:169], v[192:195], v[118:121]
	v_mfma_f32_16x16x32_bf16 v[114:117], v[184:187], v[192:195], v[114:117]
	v_mfma_f32_16x16x32_bf16 v[102:105], v[166:169], v[200:203], v[102:105]
	v_mfma_f32_16x16x32_bf16 v[98:101], v[184:187], v[200:203], v[98:101]
	v_mfma_f32_16x16x32_bf16 v[86:89], v[166:169], v[208:211], v[86:89]
	v_mfma_f32_16x16x32_bf16 v[82:85], v[184:187], v[208:211], v[82:85]
	v_mfma_f32_16x16x32_bf16 v[70:73], v[166:169], v[216:219], v[70:73]
	v_mfma_f32_16x16x32_bf16 v[66:69], v[184:187], v[216:219], v[66:69]
	s_barrier
; #define PG8_STAGE(bufoff, gbase, voff) do { _Pragma("unroll") for (int _i = 0; _i < 2; ++_i) \
;         __builtin_amdgcn_global_load_lds((const unsigned*)((const char*)(gbase) + (voff)[_i]), (LAS unsigned*)(lds + (bufoff) + ldsw + _i * 8192), 16, 0, 0); } while (0)
; #define PG8_LDA(dst, b, h) do { _Pragma("unroll") for (int m = 0; m < 4; ++m) _Pragma("unroll") for (int k = 0; k < 2; ++k) dst[m][k] = *(const LAS bf16x8*)(lds + PG8_SA(b, h) + aoff + m * 2048 + k * 1024); } while (0)
; #define PG8_MMA(ai, bj, At, Bt) do { __builtin_amdgcn_s_setprio(1); _Pragma("unroll") for (int m = 0; m < 4; ++m) _Pragma("unroll") for (int n = 0; n < 2; ++n) _Pragma("unroll") for (int k = 0; k < 2; ++k) \
;         acc[ai][bj][m][n] = __builtin_amdgcn_mfma_f32_16x16x32_bf16(Bt[n][k], At[m][k], acc[ai][bj][m][n], 0, 0, 0); __builtin_amdgcn_s_setprio(0); } while (0)
; #define PG8_WAIT_V(n) asm volatile("s_waitcnt vmcnt(" #n ")" ::: "memory")
; #define PG8_WAIT_L(n) asm volatile("s_waitcnt lgkmcnt(" #n ")" ::: "memory")
; #define PG8_BAR __builtin_amdgcn_s_barrier()
; #define PG8_SCHED __builtin_amdgcn_sched_barrier(0)
; template <class Epi>
; DI void gemm_phase(LAS unsigned char* lds, const Gemm g, const StaticOrder& S, const Epi& E) {
;     ...
;             PG8_LDA(At, 1, 1); PG8_STAGE(PG8_SB(1, 0), b3, voffB); PG8_STAGE(PG8_SB(1, 1), b3 + hstepB, voffB); PG8_STAGE(PG8_SA(1, 0), a3, voffA);
;             PG8_WAIT_V(8); PG8_WAIT_L(0); PG8_BAR; PG8_MMA(1, 0, At, B0); PG8_MMA(1, 1, At, B1); PG8_BAR; PG8_SCHED;
;         }
;         if (wr == 0) PG8_BAR;
	s_add_i32 s2, s2, s51
	v_lshl_add_u64 v[170:171], v[170:171], 0, s[6:7]
	s_mov_b32 m0, s2
	ds_read_b128 v[188:191], v149 offset:49152
	ds_read_b128 v[192:195], v149 offset:50176
	ds_read_b128 v[196:199], v149 offset:51200
	ds_read_b128 v[200:203], v149 offset:52224
	ds_read_b128 v[204:207], v149 offset:53248
	ds_read_b128 v[208:211], v149 offset:54272
	ds_read_b128 v[212:215], v149 offset:55296
	ds_read_b128 v[216:219], v149 offset:56320
	global_load_lds_dwordx4 v[170:171], off
	s_add_i32 m0, s2, 0x2000
	s_add_u32 s18, s18, 0x40080
	v_lshl_add_u64 v[170:171], v[238:239], 0, s[6:7]
	s_addc_u32 s19, s19, 0
	s_add_i32 s2, s15, s51
	global_load_lds_dwordx4 v[170:171], off
	v_lshl_add_u64 v[170:171], s[18:19], 0, v[134:135]
	s_mov_b32 m0, s2
	s_nop 0
	global_load_lds_dwordx4 v[170:171], off
	v_lshl_add_u64 v[170:171], s[18:19], 0, v[130:131]
	s_add_i32 m0, s2, 0x2000
	s_nop 0
	global_load_lds_dwordx4 v[170:171], off
	v_lshl_add_u64 v[170:171], v[240:241], 0, s[6:7]
	s_mov_b32 m0, s73
	s_nop 0
	global_load_lds_dwordx4 v[170:171], off
	v_lshl_add_u64 v[170:171], v[242:243], 0, s[6:7]
	s_mov_b32 m0, s74
	s_nop 0
	global_load_lds_dwordx4 v[170:171], off
	s_waitcnt vmcnt(8)
	s_waitcnt lgkmcnt(0)
	s_barrier
	s_waitcnt lgkmcnt(0)
	v_mfma_f32_16x16x32_bf16 v[62:65], v[142:145], v[188:191], v[62:65]
	v_mfma_f32_16x16x32_bf16 v[58:61], v[154:157], v[188:191], v[58:61]
	v_mfma_f32_16x16x32_bf16 v[46:49], v[142:145], v[196:199], v[46:49]
	v_mfma_f32_16x16x32_bf16 v[42:45], v[154:157], v[196:199], v[42:45]
	v_mfma_f32_16x16x32_bf16 v[30:33], v[142:145], v[204:207], v[30:33]
	v_mfma_f32_16x16x32_bf16 v[26:29], v[154:157], v[204:207], v[26:29]
	v_mfma_f32_16x16x32_bf16 v[14:17], v[142:145], v[212:215], v[14:17]
	v_mfma_f32_16x16x32_bf16 v[10:13], v[154:157], v[212:215], v[10:13]
	v_mfma_f32_16x16x32_bf16 v[62:65], v[150:153], v[192:195], v[62:65]
	v_mfma_f32_16x16x32_bf16 v[58:61], v[158:161], v[192:195], v[58:61]
	v_mfma_f32_16x16x32_bf16 v[46:49], v[150:153], v[200:203], v[46:49]
	v_mfma_f32_16x16x32_bf16 v[42:45], v[158:161], v[200:203], v[42:45]
	v_mfma_f32_16x16x32_bf16 v[30:33], v[150:153], v[208:211], v[30:33]
	v_mfma_f32_16x16x32_bf16 v[26:29], v[158:161], v[208:211], v[26:29]
	v_mfma_f32_16x16x32_bf16 v[14:17], v[150:153], v[216:219], v[14:17]
	v_mfma_f32_16x16x32_bf16 v[10:13], v[158:161], v[216:219], v[10:13]
	v_mfma_f32_16x16x32_bf16 v[54:57], v[162:165], v[188:191], v[54:57]
	v_mfma_f32_16x16x32_bf16 v[50:53], v[180:183], v[188:191], v[50:53]
	v_mfma_f32_16x16x32_bf16 v[38:41], v[162:165], v[196:199], v[38:41]
	v_mfma_f32_16x16x32_bf16 v[34:37], v[180:183], v[196:199], v[34:37]
	v_mfma_f32_16x16x32_bf16 v[22:25], v[162:165], v[204:207], v[22:25]
	v_mfma_f32_16x16x32_bf16 v[18:21], v[180:183], v[204:207], v[18:21]
	v_mfma_f32_16x16x32_bf16 v[6:9], v[162:165], v[212:215], v[6:9]
	v_mfma_f32_16x16x32_bf16 v[2:5], v[180:183], v[212:215], v[2:5]
	v_mfma_f32_16x16x32_bf16 v[54:57], v[166:169], v[192:195], v[54:57]
	v_mfma_f32_16x16x32_bf16 v[50:53], v[184:187], v[192:195], v[50:53]
	v_mfma_f32_16x16x32_bf16 v[38:41], v[166:169], v[200:203], v[38:41]
	v_mfma_f32_16x16x32_bf16 v[34:37], v[184:187], v[200:203], v[34:37]
	v_mfma_f32_16x16x32_bf16 v[22:25], v[166:169], v[208:211], v[22:25]
	v_mfma_f32_16x16x32_bf16 v[18:21], v[184:187], v[208:211], v[18:21]
	v_mfma_f32_16x16x32_bf16 v[6:9], v[166:169], v[216:219], v[6:9]
	v_mfma_f32_16x16x32_bf16 v[2:5], v[184:187], v[216:219], v[2:5]
	s_barrier
	s_add_i32 s90, s90, 2
	s_add_u32 s88, s88, 0x100
	s_addc_u32 s89, s89, 0
	s_add_u32 s38, s38, 0x100
	s_addc_u32 s39, s39, 0
	s_cmp_gt_u32 s90, 13
	s_cbranch_scc0 .LBB0_2162
	s_setprio 0
	s_and_b64 vcc, exec, s[26:27]
	s_movk_i32 s84, 0x5000
	v_readlane_b32 s89, v255, 19
	s_cbranch_vccz .LBB0_2165
	s_barrier

; #define PG8_STAGE(bufoff, gbase, voff) do { _Pragma("unroll") for (int _i = 0; _i < 2; ++_i) \
;         __builtin_amdgcn_global_load_lds((const unsigned*)((const char*)(gbase) + (voff)[_i]), (LAS unsigned*)(lds + (bufoff) + ldsw + _i * 8192), 16, 0, 0); } while (0)
; #define PG8_LDA(dst, b, h) do { _Pragma("unroll") for (int m = 0; m < 4; ++m) _Pragma("unroll") for (int k = 0; k < 2; ++k) dst[m][k] = *(const LAS bf16x8*)(lds + PG8_SA(b, h) + aoff + m * 2048 + k * 1024); } while (0)
; #define PG8_LDB(dst, b, h) do { _Pragma("unroll") for (int n = 0; n < 2; ++n) _Pragma("unroll") for (int k = 0; k < 2; ++k) dst[n][k] = *(const LAS bf16x8*)(lds + PG8_SB(b, h) + boff + n * 2048 + k * 1024); } while (0)
; #define PG8_MMA(ai, bj, At, Bt) do { __builtin_amdgcn_s_setprio(1); _Pragma("unroll") for (int m = 0; m < 4; ++m) _Pragma("unroll") for (int n = 0; n < 2; ++n) _Pragma("unroll") for (int k = 0; k < 2; ++k) \
;         acc[ai][bj][m][n] = __builtin_amdgcn_mfma_f32_16x16x32_bf16(Bt[n][k], At[m][k], acc[ai][bj][m][n], 0, 0, 0); __builtin_amdgcn_s_setprio(0); } while (0)
; template <class Epi>
; DI void gemm_phase(LAS unsigned char* lds, const Gemm g, const StaticOrder& S, const Epi& E) {
;     ...
;         const bool has_next = S.next(ui + 1, nxt);
;         const char* nA = has_next ? (const char*)g.A + (size_t)nxt.pm * tstepA + (size_t)nxt.pn * g.a_pn_off * 2 : cA; const char* nB = has_next ? (const char*)g.Bt + (size_t)nxt.pn * tstepB : cB;
;         for (int t = 0; t < nt; t += 2) {
;             const bool last = (t == nt - 2);
;             const char* a1 = cA + (size_t)(t + 1) * kstepA;
;             const char* a2 = last ? nA : cA + (size_t)(t + 2) * kstepA; const char* b2 = last ? nB : cB + (size_t)(t + 2) * kstepB;
;             const char* a3 = a2 + kstepA; const char* b3 = b2 + kstepB;
;             PG8_LDB(B0, 0, 0); PG8_LDB(B1, 0, 1); PG8_SCHED; PG8_LDA(At, 0, 0); PG8_STAGE(PG8_SA(1, 1), a1 + hstepA, voffA);
;             PG8_WAIT_V(8); PG8_WAIT_L(0); PG8_BAR; PG8_MMA(0, 0, At, B0); PG8_MMA(0, 1, At, B1); PG8_BAR; PG8_SCHED;
;     ...
; #pragma unroll
;         for (int a = 0; a < 2; ++a)
; #pragma unroll
;             for (int b = 0; b < 2; ++b)
; #pragma unroll
;                 for (int m = 0; m < 4; ++m)
; #pragma unroll
;                     for (int n = 0; n < 2; ++n) acc[a][b][m][n] = (f32x4){0.f, 0.f, 0.f, 0.f};
;         cur = nxt; cA = nA; cB = nB; ++ui;
.LBB0_2288:
	s_ashr_i32 s41, s40, 31
	s_lshl_b64 s[22:23], s[40:41], 15
	s_add_u32 s44, s42, s22
	s_addc_u32 s45, s43, s23
	s_and_b64 s[22:23], s[38:39], exec
	s_cselect_b32 s41, s45, s49
	s_cselect_b32 s84, s44, s48
	s_ashr_i32 s37, s36, 31
	s_lshl_b64 s[22:23], s[36:37], 15
	s_add_u32 s46, s20, s22
	s_addc_u32 s47, s21, s23
	s_and_b64 s[22:23], s[38:39], exec
	s_cselect_b32 s37, s47, s19
	s_cselect_b32 s85, s46, s18
	s_add_u32 s89, s18, 0x40000
	s_addc_u32 s90, s19, 0
	s_add_u32 s48, s48, 0x20c000
	v_mov_b32_e32 v2, 0
	s_addc_u32 s49, s49, 0
	s_mov_b32 s91, -2
	v_mov_b32_e32 v3, v2
	v_mov_b32_e32 v4, v2
	v_mov_b32_e32 v5, v2
	v_mov_b32_e32 v6, v2
	v_mov_b32_e32 v7, v2
	v_mov_b32_e32 v8, v2
	v_mov_b32_e32 v9, v2
	v_mov_b32_e32 v18, v2
	v_mov_b32_e32 v19, v2
	v_mov_b32_e32 v20, v2
	v_mov_b32_e32 v21, v2
	v_mov_b32_e32 v22, v2
	v_mov_b32_e32 v23, v2
	v_mov_b32_e32 v24, v2
	v_mov_b32_e32 v25, v2
	v_mov_b32_e32 v34, v2
	v_mov_b32_e32 v35, v2
	v_mov_b32_e32 v36, v2
	v_mov_b32_e32 v37, v2
	v_mov_b32_e32 v38, v2
	v_mov_b32_e32 v39, v2
	v_mov_b32_e32 v40, v2
	v_mov_b32_e32 v41, v2
	v_mov_b32_e32 v50, v2
	v_mov_b32_e32 v51, v2
	v_mov_b32_e32 v52, v2
	v_mov_b32_e32 v53, v2
	v_mov_b32_e32 v54, v2
	v_mov_b32_e32 v55, v2
	v_mov_b32_e32 v56, v2
	v_mov_b32_e32 v57, v2
	v_mov_b32_e32 v10, v2
	v_mov_b32_e32 v11, v2
	v_mov_b32_e32 v12, v2
	v_mov_b32_e32 v13, v2
	v_mov_b32_e32 v14, v2
	v_mov_b32_e32 v15, v2
	v_mov_b32_e32 v16, v2
	v_mov_b32_e32 v17, v2
	v_mov_b32_e32 v26, v2
	v_mov_b32_e32 v27, v2
	v_mov_b32_e32 v28, v2
	v_mov_b32_e32 v29, v2
	v_mov_b32_e32 v30, v2
	v_mov_b32_e32 v31, v2
	v_mov_b32_e32 v32, v2
	v_mov_b32_e32 v33, v2
	v_mov_b32_e32 v42, v2
	v_mov_b32_e32 v43, v2
	v_mov_b32_e32 v44, v2
	v_mov_b32_e32 v45, v2
	v_mov_b32_e32 v46, v2
	v_mov_b32_e32 v47, v2
	v_mov_b32_e32 v48, v2
	v_mov_b32_e32 v49, v2
	v_mov_b32_e32 v58, v2
	v_mov_b32_e32 v59, v2
	v_mov_b32_e32 v60, v2
	v_mov_b32_e32 v61, v2
	v_mov_b32_e32 v62, v2
	v_mov_b32_e32 v63, v2
	v_mov_b32_e32 v64, v2
	v_mov_b32_e32 v65, v2
	v_mov_b32_e32 v66, v2
	v_mov_b32_e32 v67, v2
	v_mov_b32_e32 v68, v2
	v_mov_b32_e32 v69, v2
	v_mov_b32_e32 v70, v2
	v_mov_b32_e32 v71, v2
	v_mov_b32_e32 v72, v2
	v_mov_b32_e32 v73, v2
	v_mov_b32_e32 v82, v2
	v_mov_b32_e32 v83, v2
	v_mov_b32_e32 v84, v2
	v_mov_b32_e32 v85, v2
	v_mov_b32_e32 v86, v2
	v_mov_b32_e32 v87, v2
	v_mov_b32_e32 v88, v2
	v_mov_b32_e32 v89, v2
	v_mov_b32_e32 v98, v2
	v_mov_b32_e32 v99, v2
	v_mov_b32_e32 v100, v2
	v_mov_b32_e32 v101, v2
	v_mov_b32_e32 v102, v2
	v_mov_b32_e32 v103, v2
	v_mov_b32_e32 v104, v2
	v_mov_b32_e32 v105, v2
	v_mov_b32_e32 v114, v2
	v_mov_b32_e32 v115, v2
	v_mov_b32_e32 v116, v2
	v_mov_b32_e32 v117, v2
	v_mov_b32_e32 v118, v2
	v_mov_b32_e32 v119, v2
	v_mov_b32_e32 v120, v2
	v_mov_b32_e32 v121, v2
	v_mov_b32_e32 v74, v2
	v_mov_b32_e32 v75, v2
	v_mov_b32_e32 v76, v2
	v_mov_b32_e32 v77, v2
	v_mov_b32_e32 v78, v2
	v_mov_b32_e32 v79, v2
	v_mov_b32_e32 v80, v2
	v_mov_b32_e32 v81, v2
	v_mov_b32_e32 v90, v2
	v_mov_b32_e32 v91, v2
	v_mov_b32_e32 v92, v2
	v_mov_b32_e32 v93, v2
	v_mov_b32_e32 v94, v2
	v_mov_b32_e32 v95, v2
	v_mov_b32_e32 v96, v2
	v_mov_b32_e32 v97, v2
	v_mov_b32_e32 v106, v2
	v_mov_b32_e32 v107, v2
	v_mov_b32_e32 v108, v2
	v_mov_b32_e32 v109, v2
	v_mov_b32_e32 v110, v2
	v_mov_b32_e32 v111, v2
	v_mov_b32_e32 v112, v2
	v_mov_b32_e32 v113, v2
	v_mov_b32_e32 v122, v2
	v_mov_b32_e32 v123, v2
	v_mov_b32_e32 v124, v2
	v_mov_b32_e32 v125, v2
	v_mov_b32_e32 v126, v2
	v_mov_b32_e32 v127, v2
	v_mov_b32_e32 v128, v2
	v_mov_b32_e32 v129, v2
	v_readfirstlane_b32 s2, v220
	s_lshr_b32 s2, s2, 8
	s_cmp_eq_u32 s2, 0
	s_cbranch_scc1 .Lsprio_7
	s_setprio 1
.Lsprio_7:
.LBB0_2289:
	s_add_u32 s2, s48, 0x204000
	s_addc_u32 s15, s49, 0
	s_cmp_eq_u32 s91, 40
	s_cselect_b32 s22, s84, s2
	s_cselect_b32 s23, s41, s15
	s_cselect_b32 s50, s85, s89
	s_cselect_b32 s51, s37, s90
	s_add_u32 s18, s22, 0x208000
	s_addc_u32 s19, s23, 0
	s_add_i32 s2, 0, 0x10000
	s_add_i32 s15, 0, 0x14000
	v_add_u32_e32 v158, s2, v152
	v_add_u32_e32 v170, s15, v152
	ds_read_b128 v[142:145], v158
	ds_read_b128 v[146:149], v158 offset:1024
	ds_read_b128 v[154:157], v158 offset:2048
	ds_read_b128 v[158:161], v158 offset:3072
	ds_read_b128 v[162:165], v170
	ds_read_b128 v[166:169], v170 offset:1024
	ds_read_b128 v[180:183], v170 offset:2048
	ds_read_b128 v[184:187], v170 offset:3072
	v_lshl_add_u64 v[170:171], s[48:49], 0, v[140:141]
	s_add_i32 m0, s62, 0xc000
	ds_read_b128 v[188:191], v153
	ds_read_b128 v[192:195], v153 offset:1024
	ds_read_b128 v[196:199], v153 offset:2048
	ds_read_b128 v[200:203], v153 offset:3072
	ds_read_b128 v[204:207], v153 offset:4096
	ds_read_b128 v[208:211], v153 offset:5120
	ds_read_b128 v[212:215], v153 offset:6144
	ds_read_b128 v[216:219], v153 offset:7168
	global_load_lds_dwordx4 v[170:171], off
	v_lshl_add_u64 v[170:171], s[48:49], 0, v[138:139]
	s_add_i32 m0, s62, 0xe000
	s_nop 0
	global_load_lds_dwordx4 v[170:171], off
	s_waitcnt vmcnt(8)
	s_waitcnt lgkmcnt(0)
	s_barrier
; #define PG8_STAGE(bufoff, gbase, voff) do { _Pragma("unroll") for (int _i = 0; _i < 2; ++_i) \
;         __builtin_amdgcn_global_load_lds((const unsigned*)((const char*)(gbase) + (voff)[_i]), (LAS unsigned*)(lds + (bufoff) + ldsw + _i * 8192), 16, 0, 0); } while (0)
; #define PG8_LDA(dst, b, h) do { _Pragma("unroll") for (int m = 0; m < 4; ++m) _Pragma("unroll") for (int k = 0; k < 2; ++k) dst[m][k] = *(const LAS bf16x8*)(lds + PG8_SA(b, h) + aoff + m * 2048 + k * 1024); } while (0)
; #define PG8_MMA(ai, bj, At, Bt) do { __builtin_amdgcn_s_setprio(1); _Pragma("unroll") for (int m = 0; m < 4; ++m) _Pragma("unroll") for (int n = 0; n < 2; ++n) _Pragma("unroll") for (int k = 0; k < 2; ++k) \
;         acc[ai][bj][m][n] = __builtin_amdgcn_mfma_f32_16x16x32_bf16(Bt[n][k], At[m][k], acc[ai][bj][m][n], 0, 0, 0); __builtin_amdgcn_s_setprio(0); } while (0)
; #define PG8_WAIT_V(n) asm volatile("s_waitcnt vmcnt(" #n ")" ::: "memory")
; #define PG8_WAIT_L(n) asm volatile("s_waitcnt lgkmcnt(" #n ")" ::: "memory")
; #define PG8_BAR __builtin_amdgcn_s_barrier()
; #define PG8_SCHED __builtin_amdgcn_sched_barrier(0)
; template <class Epi>
; DI void gemm_phase(LAS unsigned char* lds, const Gemm g, const StaticOrder& S, const Epi& E) {
;     ...
;             PG8_WAIT_V(8); PG8_WAIT_L(0); PG8_BAR; PG8_MMA(0, 0, At, B0); PG8_MMA(0, 1, At, B1); PG8_BAR; PG8_SCHED;
;             PG8_LDA(At, 0, 1); PG8_STAGE(PG8_SB(0, 0), b2, voffB); PG8_STAGE(PG8_SB(0, 1), b2 + hstepB, voffB); PG8_STAGE(PG8_SA(0, 0), a2, voffA);
;             PG8_WAIT_V(8); PG8_WAIT_L(0); PG8_BAR; PG8_MMA(1, 0, At, B0); PG8_MMA(1, 1, At, B1); PG8_BAR; PG8_SCHED;
	s_waitcnt lgkmcnt(0)
	v_mfma_f32_16x16x32_bf16 v[126:129], v[142:145], v[188:191], v[126:129]
	v_mfma_f32_16x16x32_bf16 v[122:125], v[154:157], v[188:191], v[122:125]
	v_mfma_f32_16x16x32_bf16 v[110:113], v[142:145], v[196:199], v[110:113]
	v_mfma_f32_16x16x32_bf16 v[106:109], v[154:157], v[196:199], v[106:109]
	v_mfma_f32_16x16x32_bf16 v[94:97], v[142:145], v[204:207], v[94:97]
	v_mfma_f32_16x16x32_bf16 v[90:93], v[154:157], v[204:207], v[90:93]
	v_mfma_f32_16x16x32_bf16 v[78:81], v[142:145], v[212:215], v[78:81]
	v_mfma_f32_16x16x32_bf16 v[74:77], v[154:157], v[212:215], v[74:77]
	v_mfma_f32_16x16x32_bf16 v[126:129], v[146:149], v[192:195], v[126:129]
	v_mfma_f32_16x16x32_bf16 v[122:125], v[158:161], v[192:195], v[122:125]
	v_mfma_f32_16x16x32_bf16 v[110:113], v[146:149], v[200:203], v[110:113]
	v_mfma_f32_16x16x32_bf16 v[106:109], v[158:161], v[200:203], v[106:109]
	v_mfma_f32_16x16x32_bf16 v[94:97], v[146:149], v[208:211], v[94:97]
	v_mfma_f32_16x16x32_bf16 v[90:93], v[158:161], v[208:211], v[90:93]
	v_mfma_f32_16x16x32_bf16 v[78:81], v[146:149], v[216:219], v[78:81]
	v_mfma_f32_16x16x32_bf16 v[74:77], v[158:161], v[216:219], v[74:77]
	v_mfma_f32_16x16x32_bf16 v[118:121], v[162:165], v[188:191], v[118:121]
	v_mfma_f32_16x16x32_bf16 v[114:117], v[180:183], v[188:191], v[114:117]
	v_mfma_f32_16x16x32_bf16 v[102:105], v[162:165], v[196:199], v[102:105]
	v_mfma_f32_16x16x32_bf16 v[98:101], v[180:183], v[196:199], v[98:101]
	v_mfma_f32_16x16x32_bf16 v[86:89], v[162:165], v[204:207], v[86:89]
	v_mfma_f32_16x16x32_bf16 v[82:85], v[180:183], v[204:207], v[82:85]
	v_mfma_f32_16x16x32_bf16 v[70:73], v[162:165], v[212:215], v[70:73]
	v_mfma_f32_16x16x32_bf16 v[66:69], v[180:183], v[212:215], v[66:69]
	v_mfma_f32_16x16x32_bf16 v[118:121], v[166:169], v[192:195], v[118:121]
	v_mfma_f32_16x16x32_bf16 v[114:117], v[184:187], v[192:195], v[114:117]
	v_mfma_f32_16x16x32_bf16 v[102:105], v[166:169], v[200:203], v[102:105]
	v_mfma_f32_16x16x32_bf16 v[98:101], v[184:187], v[200:203], v[98:101]
	v_mfma_f32_16x16x32_bf16 v[86:89], v[166:169], v[208:211], v[86:89]
	v_mfma_f32_16x16x32_bf16 v[82:85], v[184:187], v[208:211], v[82:85]
	v_mfma_f32_16x16x32_bf16 v[70:73], v[166:169], v[216:219], v[70:73]
	v_mfma_f32_16x16x32_bf16 v[66:69], v[184:187], v[216:219], v[66:69]
	s_barrier
	s_add_i32 s2, s2, s24
	v_lshl_add_u64 v[170:171], s[50:51], 0, v[134:135]
	s_mov_b32 m0, s2
	ds_read_b128 v[188:191], v153 offset:16384
	ds_read_b128 v[192:195], v153 offset:17408
	ds_read_b128 v[196:199], v153 offset:18432
	ds_read_b128 v[200:203], v153 offset:19456
	ds_read_b128 v[204:207], v153 offset:20480
	ds_read_b128 v[208:211], v153 offset:21504
	ds_read_b128 v[212:215], v153 offset:22528
	ds_read_b128 v[216:219], v153 offset:23552
	global_load_lds_dwordx4 v[170:171], off
	s_add_i32 m0, s2, 0x2000
	s_add_u32 s92, s50, 0x4000
	v_lshl_add_u64 v[170:171], s[50:51], 0, v[130:131]
	s_addc_u32 s93, s51, 0
	s_add_i32 s2, s15, s24
	global_load_lds_dwordx4 v[170:171], off
	v_lshl_add_u64 v[170:171], s[92:93], 0, v[134:135]
	s_mov_b32 m0, s2
	s_nop 0
	global_load_lds_dwordx4 v[170:171], off
	v_lshl_add_u64 v[170:171], s[92:93], 0, v[130:131]
	s_add_i32 m0, s2, 0x2000
	s_nop 0
	global_load_lds_dwordx4 v[170:171], off
	v_lshl_add_u64 v[170:171], s[22:23], 0, v[136:137]
	s_mov_b32 m0, s62
	s_nop 0
	global_load_lds_dwordx4 v[170:171], off
	v_lshl_add_u64 v[170:171], s[22:23], 0, v[132:133]
	s_mov_b32 m0, s69
	s_nop 0
	global_load_lds_dwordx4 v[170:171], off
	s_waitcnt vmcnt(8)
	s_waitcnt lgkmcnt(0)
	s_barrier
	s_waitcnt lgkmcnt(0)
	v_mfma_f32_16x16x32_bf16 v[62:65], v[142:145], v[188:191], v[62:65]
	v_mfma_f32_16x16x32_bf16 v[58:61], v[154:157], v[188:191], v[58:61]
	v_mfma_f32_16x16x32_bf16 v[46:49], v[142:145], v[196:199], v[46:49]
	v_mfma_f32_16x16x32_bf16 v[42:45], v[154:157], v[196:199], v[42:45]
	v_mfma_f32_16x16x32_bf16 v[30:33], v[142:145], v[204:207], v[30:33]
	v_mfma_f32_16x16x32_bf16 v[26:29], v[154:157], v[204:207], v[26:29]
	v_mfma_f32_16x16x32_bf16 v[14:17], v[142:145], v[212:215], v[14:17]
	v_mfma_f32_16x16x32_bf16 v[10:13], v[154:157], v[212:215], v[10:13]
	v_mfma_f32_16x16x32_bf16 v[62:65], v[146:149], v[192:195], v[62:65]
	v_mfma_f32_16x16x32_bf16 v[58:61], v[158:161], v[192:195], v[58:61]
	v_mfma_f32_16x16x32_bf16 v[46:49], v[146:149], v[200:203], v[46:49]
	v_mfma_f32_16x16x32_bf16 v[42:45], v[158:161], v[200:203], v[42:45]
	v_mfma_f32_16x16x32_bf16 v[30:33], v[146:149], v[208:211], v[30:33]
	v_mfma_f32_16x16x32_bf16 v[26:29], v[158:161], v[208:211], v[26:29]
	v_mfma_f32_16x16x32_bf16 v[14:17], v[146:149], v[216:219], v[14:17]
	v_mfma_f32_16x16x32_bf16 v[10:13], v[158:161], v[216:219], v[10:13]
	v_mfma_f32_16x16x32_bf16 v[54:57], v[162:165], v[188:191], v[54:57]
	v_mfma_f32_16x16x32_bf16 v[50:53], v[180:183], v[188:191], v[50:53]
	v_mfma_f32_16x16x32_bf16 v[38:41], v[162:165], v[196:199], v[38:41]
	v_mfma_f32_16x16x32_bf16 v[34:37], v[180:183], v[196:199], v[34:37]
	v_mfma_f32_16x16x32_bf16 v[22:25], v[162:165], v[204:207], v[22:25]
	v_mfma_f32_16x16x32_bf16 v[18:21], v[180:183], v[204:207], v[18:21]
	v_mfma_f32_16x16x32_bf16 v[6:9], v[162:165], v[212:215], v[6:9]
	v_mfma_f32_16x16x32_bf16 v[2:5], v[180:183], v[212:215], v[2:5]
	v_mfma_f32_16x16x32_bf16 v[54:57], v[166:169], v[192:195], v[54:57]
	v_mfma_f32_16x16x32_bf16 v[50:53], v[184:187], v[192:195], v[50:53]
	v_mfma_f32_16x16x32_bf16 v[38:41], v[166:169], v[200:203], v[38:41]
	v_mfma_f32_16x16x32_bf16 v[34:37], v[184:187], v[200:203], v[34:37]
	v_mfma_f32_16x16x32_bf16 v[22:25], v[166:169], v[208:211], v[22:25]
	v_mfma_f32_16x16x32_bf16 v[18:21], v[184:187], v[208:211], v[18:21]
	v_mfma_f32_16x16x32_bf16 v[6:9], v[166:169], v[216:219], v[6:9]
	v_mfma_f32_16x16x32_bf16 v[2:5], v[184:187], v[216:219], v[2:5]
	s_barrier
; #define PG8_STAGE(bufoff, gbase, voff) do { _Pragma("unroll") for (int _i = 0; _i < 2; ++_i) \
;         __builtin_amdgcn_global_load_lds((const unsigned*)((const char*)(gbase) + (voff)[_i]), (LAS unsigned*)(lds + (bufoff) + ldsw + _i * 8192), 16, 0, 0); } while (0)
; #define PG8_LDA(dst, b, h) do { _Pragma("unroll") for (int m = 0; m < 4; ++m) _Pragma("unroll") for (int k = 0; k < 2; ++k) dst[m][k] = *(const LAS bf16x8*)(lds + PG8_SA(b, h) + aoff + m * 2048 + k * 1024); } while (0)
; #define PG8_LDB(dst, b, h) do { _Pragma("unroll") for (int n = 0; n < 2; ++n) _Pragma("unroll") for (int k = 0; k < 2; ++k) dst[n][k] = *(const LAS bf16x8*)(lds + PG8_SB(b, h) + boff + n * 2048 + k * 1024); } while (0)
; #define PG8_MMA(ai, bj, At, Bt) do { __builtin_amdgcn_s_setprio(1); _Pragma("unroll") for (int m = 0; m < 4; ++m) _Pragma("unroll") for (int n = 0; n < 2; ++n) _Pragma("unroll") for (int k = 0; k < 2; ++k) \
;         acc[ai][bj][m][n] = __builtin_amdgcn_mfma_f32_16x16x32_bf16(Bt[n][k], At[m][k], acc[ai][bj][m][n], 0, 0, 0); __builtin_amdgcn_s_setprio(0); } while (0)
; #define PG8_WAIT_V(n) asm volatile("s_waitcnt vmcnt(" #n ")" ::: "memory")
; #define PG8_WAIT_L(n) asm volatile("s_waitcnt lgkmcnt(" #n ")" ::: "memory")
; #define PG8_BAR __builtin_amdgcn_s_barrier()
; #define PG8_SCHED __builtin_amdgcn_sched_barrier(0)
; template <class Epi>
; DI void gemm_phase(LAS unsigned char* lds, const Gemm g, const StaticOrder& S, const Epi& E) {
;     ...
;             PG8_LDB(B0, 1, 0); PG8_LDB(B1, 1, 1); PG8_SCHED; PG8_LDA(At, 1, 0); PG8_STAGE(PG8_SA(0, 1), a2 + hstepA, voffA);
;             PG8_WAIT_V(8); PG8_WAIT_L(0); PG8_BAR; PG8_MMA(0, 0, At, B0); PG8_MMA(0, 1, At, B1); PG8_BAR; PG8_SCHED;
	s_add_i32 s2, 0, 0x18000
	s_add_i32 s15, 0, 0x1c000
	v_add_u32_e32 v158, s2, v152
	v_add_u32_e32 v170, s15, v152
	ds_read_b128 v[142:145], v158
	ds_read_b128 v[146:149], v158 offset:1024
	ds_read_b128 v[154:157], v158 offset:2048
	ds_read_b128 v[158:161], v158 offset:3072
	ds_read_b128 v[162:165], v170
	ds_read_b128 v[166:169], v170 offset:1024
	ds_read_b128 v[180:183], v170 offset:2048
	ds_read_b128 v[184:187], v170 offset:3072
	s_add_u32 s22, s22, 0x4000
	s_addc_u32 s23, s23, 0
	s_mov_b32 m0, s70
	v_lshl_add_u64 v[170:171], s[22:23], 0, v[136:137]
	ds_read_b128 v[188:191], v153 offset:32768
	ds_read_b128 v[192:195], v153 offset:33792
	ds_read_b128 v[196:199], v153 offset:34816
	ds_read_b128 v[200:203], v153 offset:35840
	ds_read_b128 v[204:207], v153 offset:36864
	ds_read_b128 v[208:211], v153 offset:37888
	ds_read_b128 v[212:215], v153 offset:38912
	ds_read_b128 v[216:219], v153 offset:39936
	global_load_lds_dwordx4 v[170:171], off
	v_lshl_add_u64 v[170:171], s[22:23], 0, v[132:133]
	s_mov_b32 m0, s71
	s_nop 0
	global_load_lds_dwordx4 v[170:171], off
	s_waitcnt vmcnt(8)
	s_waitcnt lgkmcnt(0)
	s_barrier
	s_waitcnt lgkmcnt(0)
	v_mfma_f32_16x16x32_bf16 v[126:129], v[142:145], v[188:191], v[126:129]
	v_mfma_f32_16x16x32_bf16 v[122:125], v[154:157], v[188:191], v[122:125]
	v_mfma_f32_16x16x32_bf16 v[110:113], v[142:145], v[196:199], v[110:113]
	v_mfma_f32_16x16x32_bf16 v[106:109], v[154:157], v[196:199], v[106:109]
	v_mfma_f32_16x16x32_bf16 v[94:97], v[142:145], v[204:207], v[94:97]
	v_mfma_f32_16x16x32_bf16 v[90:93], v[154:157], v[204:207], v[90:93]
	v_mfma_f32_16x16x32_bf16 v[78:81], v[142:145], v[212:215], v[78:81]
	v_mfma_f32_16x16x32_bf16 v[74:77], v[154:157], v[212:215], v[74:77]
	v_mfma_f32_16x16x32_bf16 v[126:129], v[146:149], v[192:195], v[126:129]
	v_mfma_f32_16x16x32_bf16 v[122:125], v[158:161], v[192:195], v[122:125]
	v_mfma_f32_16x16x32_bf16 v[110:113], v[146:149], v[200:203], v[110:113]
	v_mfma_f32_16x16x32_bf16 v[106:109], v[158:161], v[200:203], v[106:109]
	v_mfma_f32_16x16x32_bf16 v[94:97], v[146:149], v[208:211], v[94:97]
	v_mfma_f32_16x16x32_bf16 v[90:93], v[158:161], v[208:211], v[90:93]
	v_mfma_f32_16x16x32_bf16 v[78:81], v[146:149], v[216:219], v[78:81]
	v_mfma_f32_16x16x32_bf16 v[74:77], v[158:161], v[216:219], v[74:77]
	v_mfma_f32_16x16x32_bf16 v[118:121], v[162:165], v[188:191], v[118:121]
	v_mfma_f32_16x16x32_bf16 v[114:117], v[180:183], v[188:191], v[114:117]
	v_mfma_f32_16x16x32_bf16 v[102:105], v[162:165], v[196:199], v[102:105]
	v_mfma_f32_16x16x32_bf16 v[98:101], v[180:183], v[196:199], v[98:101]
	v_mfma_f32_16x16x32_bf16 v[86:89], v[162:165], v[204:207], v[86:89]
	v_mfma_f32_16x16x32_bf16 v[82:85], v[180:183], v[204:207], v[82:85]
	v_mfma_f32_16x16x32_bf16 v[70:73], v[162:165], v[212:215], v[70:73]
	v_mfma_f32_16x16x32_bf16 v[66:69], v[180:183], v[212:215], v[66:69]
	v_mfma_f32_16x16x32_bf16 v[118:121], v[166:169], v[192:195], v[118:121]
	v_mfma_f32_16x16x32_bf16 v[114:117], v[184:187], v[192:195], v[114:117]
	v_mfma_f32_16x16x32_bf16 v[102:105], v[166:169], v[200:203], v[102:105]
	v_mfma_f32_16x16x32_bf16 v[98:101], v[184:187], v[200:203], v[98:101]
	v_mfma_f32_16x16x32_bf16 v[86:89], v[166:169], v[208:211], v[86:89]
	v_mfma_f32_16x16x32_bf16 v[82:85], v[184:187], v[208:211], v[82:85]
	v_mfma_f32_16x16x32_bf16 v[70:73], v[166:169], v[216:219], v[70:73]
	v_mfma_f32_16x16x32_bf16 v[66:69], v[184:187], v[216:219], v[66:69]
	s_barrier
; #define PG8_STAGE(bufoff, gbase, voff) do { _Pragma("unroll") for (int _i = 0; _i < 2; ++_i) \
;         __builtin_amdgcn_global_load_lds((const unsigned*)((const char*)(gbase) + (voff)[_i]), (LAS unsigned*)(lds + (bufoff) + ldsw + _i * 8192), 16, 0, 0); } while (0)
; #define PG8_LDA(dst, b, h) do { _Pragma("unroll") for (int m = 0; m < 4; ++m) _Pragma("unroll") for (int k = 0; k < 2; ++k) dst[m][k] = *(const LAS bf16x8*)(lds + PG8_SA(b, h) + aoff + m * 2048 + k * 1024); } while (0)
; #define PG8_MMA(ai, bj, At, Bt) do { __builtin_amdgcn_s_setprio(1); _Pragma("unroll") for (int m = 0; m < 4; ++m) _Pragma("unroll") for (int n = 0; n < 2; ++n) _Pragma("unroll") for (int k = 0; k < 2; ++k) \
;         acc[ai][bj][m][n] = __builtin_amdgcn_mfma_f32_16x16x32_bf16(Bt[n][k], At[m][k], acc[ai][bj][m][n], 0, 0, 0); __builtin_amdgcn_s_setprio(0); } while (0)
; #define PG8_WAIT_V(n) asm volatile("s_waitcnt vmcnt(" #n ")" ::: "memory")
; #define PG8_WAIT_L(n) asm volatile("s_waitcnt lgkmcnt(" #n ")" ::: "memory")
; #define PG8_BAR __builtin_amdgcn_s_barrier()
; #define PG8_SCHED __builtin_amdgcn_sched_barrier(0)
; template <class Epi>
; DI void gemm_phase(LAS unsigned char* lds, const Gemm g, const StaticOrder& S, const Epi& E) {
;     ...
;             PG8_LDA(At, 1, 1); PG8_STAGE(PG8_SB(1, 0), b3, voffB); PG8_STAGE(PG8_SB(1, 1), b3 + hstepB, voffB); PG8_STAGE(PG8_SA(1, 0), a3, voffA);
;             PG8_WAIT_V(8); PG8_WAIT_L(0); PG8_BAR; PG8_MMA(1, 0, At, B0); PG8_MMA(1, 1, At, B1); PG8_BAR; PG8_SCHED;
;         }
;         if (wr == 0) PG8_BAR;
	s_add_u32 s22, s50, 0x20000
	s_addc_u32 s23, s51, 0
	s_add_i32 s2, s2, s24
	v_lshl_add_u64 v[170:171], s[22:23], 0, v[134:135]
	s_mov_b32 m0, s2
	ds_read_b128 v[188:191], v153 offset:49152
	ds_read_b128 v[192:195], v153 offset:50176
	ds_read_b128 v[196:199], v153 offset:51200
	ds_read_b128 v[200:203], v153 offset:52224
	ds_read_b128 v[204:207], v153 offset:53248
	ds_read_b128 v[208:211], v153 offset:54272
	ds_read_b128 v[212:215], v153 offset:55296
	ds_read_b128 v[216:219], v153 offset:56320
	global_load_lds_dwordx4 v[170:171], off
	s_add_i32 m0, s2, 0x2000
	v_lshl_add_u64 v[170:171], s[22:23], 0, v[130:131]
	s_add_u32 s22, s50, 0x24000
	s_addc_u32 s23, s51, 0
	s_add_i32 s2, s15, s24
	global_load_lds_dwordx4 v[170:171], off
	v_lshl_add_u64 v[170:171], s[22:23], 0, v[134:135]
	s_mov_b32 m0, s2
	s_nop 0
	global_load_lds_dwordx4 v[170:171], off
	v_lshl_add_u64 v[170:171], s[22:23], 0, v[130:131]
	s_add_i32 m0, s2, 0x2000
	s_nop 0
	global_load_lds_dwordx4 v[170:171], off
	v_lshl_add_u64 v[170:171], s[18:19], 0, v[136:137]
	s_mov_b32 m0, s74
	s_nop 0
	global_load_lds_dwordx4 v[170:171], off
	v_lshl_add_u64 v[170:171], s[18:19], 0, v[132:133]
	s_mov_b32 m0, s75
	s_nop 0
	global_load_lds_dwordx4 v[170:171], off
	s_waitcnt vmcnt(8)
	s_waitcnt lgkmcnt(0)
	s_barrier
	s_waitcnt lgkmcnt(0)
	v_mfma_f32_16x16x32_bf16 v[62:65], v[142:145], v[188:191], v[62:65]
	v_mfma_f32_16x16x32_bf16 v[58:61], v[154:157], v[188:191], v[58:61]
	v_mfma_f32_16x16x32_bf16 v[46:49], v[142:145], v[196:199], v[46:49]
	v_mfma_f32_16x16x32_bf16 v[42:45], v[154:157], v[196:199], v[42:45]
	v_mfma_f32_16x16x32_bf16 v[30:33], v[142:145], v[204:207], v[30:33]
	v_mfma_f32_16x16x32_bf16 v[26:29], v[154:157], v[204:207], v[26:29]
	v_mfma_f32_16x16x32_bf16 v[14:17], v[142:145], v[212:215], v[14:17]
	v_mfma_f32_16x16x32_bf16 v[10:13], v[154:157], v[212:215], v[10:13]
	v_mfma_f32_16x16x32_bf16 v[62:65], v[146:149], v[192:195], v[62:65]
	v_mfma_f32_16x16x32_bf16 v[58:61], v[158:161], v[192:195], v[58:61]
	v_mfma_f32_16x16x32_bf16 v[46:49], v[146:149], v[200:203], v[46:49]
	v_mfma_f32_16x16x32_bf16 v[42:45], v[158:161], v[200:203], v[42:45]
	v_mfma_f32_16x16x32_bf16 v[30:33], v[146:149], v[208:211], v[30:33]
	v_mfma_f32_16x16x32_bf16 v[26:29], v[158:161], v[208:211], v[26:29]
	v_mfma_f32_16x16x32_bf16 v[14:17], v[146:149], v[216:219], v[14:17]
	v_mfma_f32_16x16x32_bf16 v[10:13], v[158:161], v[216:219], v[10:13]
	v_mfma_f32_16x16x32_bf16 v[54:57], v[162:165], v[188:191], v[54:57]
	v_mfma_f32_16x16x32_bf16 v[50:53], v[180:183], v[188:191], v[50:53]
	v_mfma_f32_16x16x32_bf16 v[38:41], v[162:165], v[196:199], v[38:41]
	v_mfma_f32_16x16x32_bf16 v[34:37], v[180:183], v[196:199], v[34:37]
	v_mfma_f32_16x16x32_bf16 v[22:25], v[162:165], v[204:207], v[22:25]
	v_mfma_f32_16x16x32_bf16 v[18:21], v[180:183], v[204:207], v[18:21]
	v_mfma_f32_16x16x32_bf16 v[6:9], v[162:165], v[212:215], v[6:9]
	v_mfma_f32_16x16x32_bf16 v[2:5], v[180:183], v[212:215], v[2:5]
	v_mfma_f32_16x16x32_bf16 v[54:57], v[166:169], v[192:195], v[54:57]
	v_mfma_f32_16x16x32_bf16 v[50:53], v[184:187], v[192:195], v[50:53]
	v_mfma_f32_16x16x32_bf16 v[38:41], v[166:169], v[200:203], v[38:41]
	v_mfma_f32_16x16x32_bf16 v[34:37], v[184:187], v[200:203], v[34:37]
	v_mfma_f32_16x16x32_bf16 v[22:25], v[166:169], v[208:211], v[22:25]
	v_mfma_f32_16x16x32_bf16 v[18:21], v[184:187], v[208:211], v[18:21]
	v_mfma_f32_16x16x32_bf16 v[6:9], v[166:169], v[216:219], v[6:9]
	v_mfma_f32_16x16x32_bf16 v[2:5], v[184:187], v[216:219], v[2:5]
	s_barrier
	s_add_i32 s91, s91, 2
	s_add_u32 s89, s89, 0x40000
	s_addc_u32 s90, s90, 0
	s_add_u32 s48, s48, 0x410000
	s_addc_u32 s49, s49, 0
	s_cmp_gt_u32 s91, 41
	s_cbranch_scc0 .LBB0_2289
	s_setprio 0
	s_and_b64 vcc, exec, s[34:35]
	s_movk_i32 s91, 0xfe00
	v_readlane_b32 s89, v255, 19
	s_cbranch_vccz .LBB0_2292
	s_barrier
